# K-loops: the s_waitcnt lgkmcnt(0) that directly followed each MFMA-segment barrier removed (an identical wait already precedes the barrier and no LDS op is issued in between); 40 sites
# speedup vs baseline: 1.0126x; 1.0126x over previous
; #define PG8_STAGE(bufoff, gbase, voff) do { _Pragma("unroll") for (int _i = 0; _i < 2; ++_i) \
;         __builtin_amdgcn_global_load_lds((const unsigned*)((const char*)(gbase) + (voff)[_i]), (PG8_LAS unsigned*)(lds + (bufoff) + ldsw + _i * 8192), 16, 0, 0); } while (0)
; #define PG8_LDA(dst, b, h) do { _Pragma("unroll") for (int m = 0; m < 4; ++m) _Pragma("unroll") for (int k = 0; k < 2; ++k) dst[m][k] = *(const PG8_LAS bf16x8*)(lds + PG8_SA(b, h) + aoff + m * 2048 + k * 1024); } while (0)
; #define PG8_LDB(dst, b, h) do { _Pragma("unroll") for (int n = 0; n < 2; ++n) _Pragma("unroll") for (int k = 0; k < 2; ++k) dst[n][k] = *(const PG8_LAS bf16x8*)(lds + PG8_SB(b, h) + boff + n * 2048 + k * 1024); } while (0)
; #define PG8_WAIT_V(n) asm volatile("s_waitcnt vmcnt(" #n ")" ::: "memory")
; #define PG8_WAIT_L(n) asm volatile("s_waitcnt lgkmcnt(" #n ")" ::: "memory")
; #define PG8_BAR __builtin_amdgcn_s_barrier()
; template <class Epi, class Sched, bool ALIGN_EPI = false, bool SP2 = false>
; __device__ __forceinline__ void gemm_phase(PG8_LAS unsigned char* lds, const Gemm g, const Sched& S, const Epi& E, int wave_s) {
;     ...
;         const bool has_next = S.next(ui + 1, nxt);
;         const char* nA = has_next ? (const char*)g.A + (size_t)nxt.pm * tstepA + (size_t)(nxt.pn / g.npg) * (size_t)(K * 2) : cA; const char* nB = has_next ? (const char*)g.Bt + (size_t)nxt.pn * tstepB : cB;
;         for (int t = 0; t < nt; t += 2) {
;             const bool last = (t == nt - 2);
;             const char* a1 = cA + (size_t)(t + 1) * kstep;
;             const char* a2 = last ? nA : cA + (size_t)(t + 2) * kstep; const char* b2 = last ? nB : cB + (size_t)(t + 2) * kstep;
;             const char* a3 = a2 + kstep; const char* b3 = b2 + kstep;
;             if (last && has_next) S.a_ready(nxt);
;             if constexpr (SP2) {
;             PG8_LDB(B0, 0, 0); PG8_LDB(B1, 0, 1); PG8_SCHED; PG8_LDA(At, 0, 0); PG8_STAGE(PG8_SA(1, 1), a1 + hstepA, voffA);
;             PG8_WAIT_V(8); PG8_WAIT_L(0); PG8_BAR; PG8_MMA(0, 0, At, B0); PG8_MMA(0, 1, At, B1); PG8_BAR; PG8_SCHED;
;             PG8_LDA(At, 0, 1); PG8_STAGE(PG8_SB(0, 0), b2, voffB); PG8_STAGE(PG8_SB(0, 1), b2 + hstepB, voffB); PG8_STAGE(PG8_SA(0, 0), a2, voffA);
;             PG8_WAIT_V(8); PG8_WAIT_L(0); PG8_BAR; PG8_MMA(1, 0, At, B0); PG8_MMA(1, 1, At, B1); PG8_BAR; PG8_SCHED;
.LBB0_313:
	s_ashr_i32 s29, s28, 31
	s_lshl_b64 s[2:3], s[28:29], 18
	s_add_u32 s96, s22, s2
	s_addc_u32 s97, s23, s3
	s_and_b64 s[2:3], s[4:5], exec
	s_cselect_b32 s2, s97, s31
	s_cselect_b32 s3, s96, s30
	s_add_u32 s4, s40, 0x80080
	s_addc_u32 s5, s41, 0
	s_add_u32 s29, s30, 0x100
	s_addc_u32 s81, s31, 0
	s_mov_b32 s84, -2
	s_add_u32 s30, s4, 0xfff80080
	s_addc_u32 s31, s5, -1
	s_add_i32 s85, 0, 0x10000
	s_cmp_eq_u32 s84, 4
	s_cselect_b32 s41, s91, s31
	s_cselect_b32 s40, s90, s30
	s_cselect_b32 s31, s2, s81
	s_cselect_b32 s30, s3, s29
	s_add_i32 s89, 0, 0x14000
	v_add_u32_e32 v118, s85, v229
	v_add_u32_e32 v150, s89, v229
	ds_read_b128 v[106:109], v118
	ds_read_b128 v[110:113], v118 offset:1024
	ds_read_b128 v[114:117], v118 offset:2048
	ds_read_b128 v[118:121], v118 offset:3072
	ds_read_b128 v[122:125], v150
	ds_read_b128 v[126:129], v150 offset:1024
	ds_read_b128 v[142:145], v150 offset:2048
	ds_read_b128 v[150:153], v150 offset:3072
	v_lshl_add_u64 v[194:195], s[4:5], 0, v[218:219]
	s_add_i32 m0, s35, 0xc000
	ds_read_b128 v[162:165], v230
	ds_read_b128 v[166:169], v230 offset:1024
	ds_read_b128 v[170:173], v230 offset:2048
	ds_read_b128 v[174:177], v230 offset:3072
	ds_read_b128 v[178:181], v230 offset:4096
	ds_read_b128 v[182:185], v230 offset:5120
	ds_read_b128 v[186:189], v230 offset:6144
	ds_read_b128 v[190:193], v230 offset:7168
	global_load_lds_dwordx4 v[194:195], off
	v_lshl_add_u64 v[194:195], s[4:5], 0, v[220:221]
	s_add_i32 m0, s35, 0xe000
	s_nop 0
	global_load_lds_dwordx4 v[194:195], off
	s_waitcnt vmcnt(8)
	s_waitcnt lgkmcnt(0)
	s_barrier
	v_mfma_f32_16x16x32_bf16 v[158:161], v[106:109], v[162:165], 0
	v_mfma_f32_16x16x32_bf16 v[154:157], v[114:117], v[162:165], 0
	v_mfma_f32_16x16x32_bf16 v[134:137], v[106:109], v[170:173], 0
	v_mfma_f32_16x16x32_bf16 v[130:133], v[114:117], v[170:173], 0
	v_mfma_f32_16x16x32_bf16 v[94:97], v[106:109], v[178:181], 0
	v_mfma_f32_16x16x32_bf16 v[90:93], v[114:117], v[178:181], 0
	v_mfma_f32_16x16x32_bf16 v[78:81], v[106:109], v[186:189], 0
	v_mfma_f32_16x16x32_bf16 v[74:77], v[114:117], v[186:189], 0
	v_mfma_f32_16x16x32_bf16 v[158:161], v[110:113], v[166:169], v[158:161]
	v_mfma_f32_16x16x32_bf16 v[154:157], v[118:121], v[166:169], v[154:157]
	v_mfma_f32_16x16x32_bf16 v[134:137], v[110:113], v[174:177], v[134:137]
	v_mfma_f32_16x16x32_bf16 v[130:133], v[118:121], v[174:177], v[130:133]
	v_mfma_f32_16x16x32_bf16 v[94:97], v[110:113], v[182:185], v[94:97]
	v_mfma_f32_16x16x32_bf16 v[90:93], v[118:121], v[182:185], v[90:93]
	v_mfma_f32_16x16x32_bf16 v[78:81], v[110:113], v[190:193], v[78:81]
	v_mfma_f32_16x16x32_bf16 v[74:77], v[118:121], v[190:193], v[74:77]
	v_mfma_f32_16x16x32_bf16 v[146:149], v[122:125], v[162:165], 0
	v_mfma_f32_16x16x32_bf16 v[138:141], v[142:145], v[162:165], 0
	v_mfma_f32_16x16x32_bf16 v[102:105], v[122:125], v[170:173], 0
	v_mfma_f32_16x16x32_bf16 v[98:101], v[142:145], v[170:173], 0
	v_mfma_f32_16x16x32_bf16 v[86:89], v[122:125], v[178:181], 0
	v_mfma_f32_16x16x32_bf16 v[82:85], v[142:145], v[178:181], 0
	v_mfma_f32_16x16x32_bf16 v[70:73], v[122:125], v[186:189], 0
	v_mfma_f32_16x16x32_bf16 v[66:69], v[142:145], v[186:189], 0
	v_mfma_f32_16x16x32_bf16 v[146:149], v[126:129], v[166:169], v[146:149]
	v_mfma_f32_16x16x32_bf16 v[138:141], v[150:153], v[166:169], v[138:141]
	v_mfma_f32_16x16x32_bf16 v[102:105], v[126:129], v[174:177], v[102:105]
	v_mfma_f32_16x16x32_bf16 v[98:101], v[150:153], v[174:177], v[98:101]
	v_mfma_f32_16x16x32_bf16 v[86:89], v[126:129], v[182:185], v[86:89]
	v_mfma_f32_16x16x32_bf16 v[82:85], v[150:153], v[182:185], v[82:85]
	v_mfma_f32_16x16x32_bf16 v[70:73], v[126:129], v[190:193], v[70:73]
	v_mfma_f32_16x16x32_bf16 v[66:69], v[150:153], v[190:193], v[66:69]
	s_barrier
	s_add_i32 s85, s85, s34
	v_lshl_add_u64 v[194:195], s[30:31], 0, v[214:215]
	s_mov_b32 m0, s85
	ds_read_b128 v[162:165], v230 offset:16384
	ds_read_b128 v[166:169], v230 offset:17408
	ds_read_b128 v[170:173], v230 offset:18432
	ds_read_b128 v[174:177], v230 offset:19456
	ds_read_b128 v[178:181], v230 offset:20480
	ds_read_b128 v[182:185], v230 offset:21504
	ds_read_b128 v[186:189], v230 offset:22528
	ds_read_b128 v[190:193], v230 offset:23552
	global_load_lds_dwordx4 v[194:195], off
	s_add_i32 m0, s85, 0x2000
	s_add_u32 s94, s30, 0x20000
	v_lshl_add_u64 v[196:197], s[30:31], 0, v[210:211]
	s_addc_u32 s95, s31, 0
	s_add_i32 s85, s89, s34
	global_load_lds_dwordx4 v[196:197], off
	v_lshl_add_u64 v[198:199], s[94:95], 0, v[214:215]
	s_mov_b32 m0, s85
	v_lshl_add_u64 v[200:201], s[40:41], 0, v[212:213]
	global_load_lds_dwordx4 v[198:199], off
	v_lshl_add_u64 v[198:199], s[94:95], 0, v[210:211]
	s_add_i32 m0, s85, 0x2000
	s_nop 0
	global_load_lds_dwordx4 v[198:199], off
	v_lshl_add_u64 v[198:199], s[40:41], 0, v[216:217]
	s_mov_b32 m0, s35
	s_nop 0
	global_load_lds_dwordx4 v[198:199], off
	s_mov_b32 m0, s36
	s_nop 0
	global_load_lds_dwordx4 v[200:201], off
	s_waitcnt vmcnt(8)
	s_waitcnt lgkmcnt(0)
	s_barrier
; #define PG8_STAGE(bufoff, gbase, voff) do { _Pragma("unroll") for (int _i = 0; _i < 2; ++_i) \
;         __builtin_amdgcn_global_load_lds((const unsigned*)((const char*)(gbase) + (voff)[_i]), (PG8_LAS unsigned*)(lds + (bufoff) + ldsw + _i * 8192), 16, 0, 0); } while (0)
; #define PG8_LDA(dst, b, h) do { _Pragma("unroll") for (int m = 0; m < 4; ++m) _Pragma("unroll") for (int k = 0; k < 2; ++k) dst[m][k] = *(const PG8_LAS bf16x8*)(lds + PG8_SA(b, h) + aoff + m * 2048 + k * 1024); } while (0)
; #define PG8_LDB(dst, b, h) do { _Pragma("unroll") for (int n = 0; n < 2; ++n) _Pragma("unroll") for (int k = 0; k < 2; ++k) dst[n][k] = *(const PG8_LAS bf16x8*)(lds + PG8_SB(b, h) + boff + n * 2048 + k * 1024); } while (0)
; #define PG8_MMA(ai, bj, At, Bt) do { __builtin_amdgcn_s_setprio(1); _Pragma("unroll") for (int m = 0; m < 4; ++m) _Pragma("unroll") for (int n = 0; n < 2; ++n) _Pragma("unroll") for (int k = 0; k < 2; ++k) \
;         acc[ai][bj][m][n] = __builtin_amdgcn_mfma_f32_16x16x32_bf16(Bt[n][k], At[m][k], acc[ai][bj][m][n], 0, 0, 0); __builtin_amdgcn_s_setprio(0); } while (0)
; #define PG8_WAIT_V(n) asm volatile("s_waitcnt vmcnt(" #n ")" ::: "memory")
; #define PG8_WAIT_L(n) asm volatile("s_waitcnt lgkmcnt(" #n ")" ::: "memory")
; #define PG8_BAR __builtin_amdgcn_s_barrier()
; #define PG8_SCHED __builtin_amdgcn_sched_barrier(0)
; template <class Epi, class Sched, bool ALIGN_EPI = false, bool SP2 = false>
; __device__ __forceinline__ void gemm_phase(PG8_LAS unsigned char* lds, const Gemm g, const Sched& S, const Epi& E, int wave_s) {
;     ...
;             PG8_WAIT_V(8); PG8_WAIT_L(0); PG8_BAR; PG8_MMA(1, 0, At, B0); PG8_MMA(1, 1, At, B1); PG8_BAR; PG8_SCHED;
;             PG8_LDB(B0, 1, 0); PG8_LDB(B1, 1, 1); PG8_SCHED; PG8_LDA(At, 1, 0); PG8_STAGE(PG8_SA(0, 1), a2 + hstepA, voffA);
;             PG8_WAIT_V(8); PG8_WAIT_L(0); PG8_BAR; PG8_MMA(0, 0, At, B0); PG8_MMA(0, 1, At, B1); PG8_BAR; PG8_SCHED;
	v_mfma_f32_16x16x32_bf16 v[62:65], v[106:109], v[162:165], 0
	v_mfma_f32_16x16x32_bf16 v[58:61], v[114:117], v[162:165], 0
	v_mfma_f32_16x16x32_bf16 v[46:49], v[106:109], v[170:173], 0
	v_mfma_f32_16x16x32_bf16 v[42:45], v[114:117], v[170:173], 0
	v_mfma_f32_16x16x32_bf16 v[30:33], v[106:109], v[178:181], 0
	v_mfma_f32_16x16x32_bf16 v[26:29], v[114:117], v[178:181], 0
	v_mfma_f32_16x16x32_bf16 v[14:17], v[106:109], v[186:189], 0
	v_mfma_f32_16x16x32_bf16 v[10:13], v[114:117], v[186:189], 0
	v_mfma_f32_16x16x32_bf16 v[62:65], v[110:113], v[166:169], v[62:65]
	v_mfma_f32_16x16x32_bf16 v[58:61], v[118:121], v[166:169], v[58:61]
	v_mfma_f32_16x16x32_bf16 v[46:49], v[110:113], v[174:177], v[46:49]
	v_mfma_f32_16x16x32_bf16 v[42:45], v[118:121], v[174:177], v[42:45]
	v_mfma_f32_16x16x32_bf16 v[30:33], v[110:113], v[182:185], v[30:33]
	v_mfma_f32_16x16x32_bf16 v[26:29], v[118:121], v[182:185], v[26:29]
	v_mfma_f32_16x16x32_bf16 v[14:17], v[110:113], v[190:193], v[14:17]
	v_mfma_f32_16x16x32_bf16 v[10:13], v[118:121], v[190:193], v[10:13]
	v_mfma_f32_16x16x32_bf16 v[54:57], v[122:125], v[162:165], 0
	v_mfma_f32_16x16x32_bf16 v[50:53], v[142:145], v[162:165], 0
	v_mfma_f32_16x16x32_bf16 v[38:41], v[122:125], v[170:173], 0
	v_mfma_f32_16x16x32_bf16 v[34:37], v[142:145], v[170:173], 0
	v_mfma_f32_16x16x32_bf16 v[22:25], v[122:125], v[178:181], 0
	v_mfma_f32_16x16x32_bf16 v[18:21], v[142:145], v[178:181], 0
	v_mfma_f32_16x16x32_bf16 v[6:9], v[122:125], v[186:189], 0
	v_mfma_f32_16x16x32_bf16 v[2:5], v[142:145], v[186:189], 0
	v_mfma_f32_16x16x32_bf16 v[54:57], v[126:129], v[166:169], v[54:57]
	v_mfma_f32_16x16x32_bf16 v[50:53], v[150:153], v[166:169], v[50:53]
	v_mfma_f32_16x16x32_bf16 v[38:41], v[126:129], v[174:177], v[38:41]
	v_mfma_f32_16x16x32_bf16 v[34:37], v[150:153], v[174:177], v[34:37]
	v_mfma_f32_16x16x32_bf16 v[22:25], v[126:129], v[182:185], v[22:25]
	v_mfma_f32_16x16x32_bf16 v[18:21], v[150:153], v[182:185], v[18:21]
	v_mfma_f32_16x16x32_bf16 v[6:9], v[126:129], v[190:193], v[6:9]
	v_mfma_f32_16x16x32_bf16 v[2:5], v[150:153], v[190:193], v[2:5]
	s_barrier
	s_add_i32 s85, 0, 0x18000
	s_add_i32 s89, 0, 0x1c000
	v_add_u32_e32 v118, s85, v229
	v_add_u32_e32 v150, s89, v229
	ds_read_b128 v[106:109], v118
	ds_read_b128 v[110:113], v118 offset:1024
	ds_read_b128 v[114:117], v118 offset:2048
	ds_read_b128 v[118:121], v118 offset:3072
	ds_read_b128 v[122:125], v150
	ds_read_b128 v[126:129], v150 offset:1024
	ds_read_b128 v[142:145], v150 offset:2048
	ds_read_b128 v[150:153], v150 offset:3072
	s_add_u32 s40, s40, 0x80000
	s_addc_u32 s41, s41, 0
	s_mov_b32 m0, s37
	v_lshl_add_u64 v[202:203], s[40:41], 0, v[216:217]
	ds_read_b128 v[162:165], v230 offset:32768
	ds_read_b128 v[166:169], v230 offset:33792
	ds_read_b128 v[170:173], v230 offset:34816
	ds_read_b128 v[174:177], v230 offset:35840
	ds_read_b128 v[178:181], v230 offset:36864
	ds_read_b128 v[182:185], v230 offset:37888
	ds_read_b128 v[186:189], v230 offset:38912
	ds_read_b128 v[190:193], v230 offset:39936
	global_load_lds_dwordx4 v[202:203], off
	v_lshl_add_u64 v[202:203], s[40:41], 0, v[212:213]
	s_mov_b32 m0, s42
	s_nop 0
	global_load_lds_dwordx4 v[202:203], off
	s_waitcnt vmcnt(8)
	s_waitcnt lgkmcnt(0)
	s_barrier
	v_mfma_f32_16x16x32_bf16 v[158:161], v[106:109], v[162:165], v[158:161]
	v_mfma_f32_16x16x32_bf16 v[154:157], v[114:117], v[162:165], v[154:157]
	v_mfma_f32_16x16x32_bf16 v[134:137], v[106:109], v[170:173], v[134:137]
	v_mfma_f32_16x16x32_bf16 v[130:133], v[114:117], v[170:173], v[130:133]
	v_mfma_f32_16x16x32_bf16 v[94:97], v[106:109], v[178:181], v[94:97]
	v_mfma_f32_16x16x32_bf16 v[90:93], v[114:117], v[178:181], v[90:93]
	v_mfma_f32_16x16x32_bf16 v[78:81], v[106:109], v[186:189], v[78:81]
	v_mfma_f32_16x16x32_bf16 v[74:77], v[114:117], v[186:189], v[74:77]
	v_mfma_f32_16x16x32_bf16 v[158:161], v[110:113], v[166:169], v[158:161]
	v_mfma_f32_16x16x32_bf16 v[154:157], v[118:121], v[166:169], v[154:157]
	v_mfma_f32_16x16x32_bf16 v[134:137], v[110:113], v[174:177], v[134:137]
	v_mfma_f32_16x16x32_bf16 v[130:133], v[118:121], v[174:177], v[130:133]
	v_mfma_f32_16x16x32_bf16 v[94:97], v[110:113], v[182:185], v[94:97]
	v_mfma_f32_16x16x32_bf16 v[90:93], v[118:121], v[182:185], v[90:93]
	v_mfma_f32_16x16x32_bf16 v[78:81], v[110:113], v[190:193], v[78:81]
	v_mfma_f32_16x16x32_bf16 v[74:77], v[118:121], v[190:193], v[74:77]
	v_mfma_f32_16x16x32_bf16 v[146:149], v[122:125], v[162:165], v[146:149]
	v_mfma_f32_16x16x32_bf16 v[138:141], v[142:145], v[162:165], v[138:141]
	v_mfma_f32_16x16x32_bf16 v[102:105], v[122:125], v[170:173], v[102:105]
	v_mfma_f32_16x16x32_bf16 v[98:101], v[142:145], v[170:173], v[98:101]
	v_mfma_f32_16x16x32_bf16 v[86:89], v[122:125], v[178:181], v[86:89]
	v_mfma_f32_16x16x32_bf16 v[82:85], v[142:145], v[178:181], v[82:85]
	v_mfma_f32_16x16x32_bf16 v[70:73], v[122:125], v[186:189], v[70:73]
	v_mfma_f32_16x16x32_bf16 v[66:69], v[142:145], v[186:189], v[66:69]
	v_mfma_f32_16x16x32_bf16 v[146:149], v[126:129], v[166:169], v[146:149]
	v_mfma_f32_16x16x32_bf16 v[138:141], v[150:153], v[166:169], v[138:141]
	v_mfma_f32_16x16x32_bf16 v[102:105], v[126:129], v[174:177], v[102:105]
	v_mfma_f32_16x16x32_bf16 v[98:101], v[150:153], v[174:177], v[98:101]
	v_mfma_f32_16x16x32_bf16 v[86:89], v[126:129], v[182:185], v[86:89]
	v_mfma_f32_16x16x32_bf16 v[82:85], v[150:153], v[182:185], v[82:85]
	v_mfma_f32_16x16x32_bf16 v[70:73], v[126:129], v[190:193], v[70:73]
	v_mfma_f32_16x16x32_bf16 v[66:69], v[150:153], v[190:193], v[66:69]
	s_barrier
; #define PG8_STAGE(bufoff, gbase, voff) do { _Pragma("unroll") for (int _i = 0; _i < 2; ++_i) \
;         __builtin_amdgcn_global_load_lds((const unsigned*)((const char*)(gbase) + (voff)[_i]), (PG8_LAS unsigned*)(lds + (bufoff) + ldsw + _i * 8192), 16, 0, 0); } while (0)
; #define PG8_LDA(dst, b, h) do { _Pragma("unroll") for (int m = 0; m < 4; ++m) _Pragma("unroll") for (int k = 0; k < 2; ++k) dst[m][k] = *(const PG8_LAS bf16x8*)(lds + PG8_SA(b, h) + aoff + m * 2048 + k * 1024); } while (0)
; #define PG8_LDB(dst, b, h) do { _Pragma("unroll") for (int n = 0; n < 2; ++n) _Pragma("unroll") for (int k = 0; k < 2; ++k) dst[n][k] = *(const PG8_LAS bf16x8*)(lds + PG8_SB(b, h) + boff + n * 2048 + k * 1024); } while (0)
; #define PG8_MMA(ai, bj, At, Bt) do { __builtin_amdgcn_s_setprio(1); _Pragma("unroll") for (int m = 0; m < 4; ++m) _Pragma("unroll") for (int n = 0; n < 2; ++n) _Pragma("unroll") for (int k = 0; k < 2; ++k) \
;         acc[ai][bj][m][n] = __builtin_amdgcn_mfma_f32_16x16x32_bf16(Bt[n][k], At[m][k], acc[ai][bj][m][n], 0, 0, 0); __builtin_amdgcn_s_setprio(0); } while (0)
; #define PG8_WAIT_V(n) asm volatile("s_waitcnt vmcnt(" #n ")" ::: "memory")
; #define PG8_WAIT_L(n) asm volatile("s_waitcnt lgkmcnt(" #n ")" ::: "memory")
; #define PG8_BAR __builtin_amdgcn_s_barrier()
; #define PG8_SCHED __builtin_amdgcn_sched_barrier(0)
; template <class Epi, class Sched, bool ALIGN_EPI = false, bool SP2 = false>
; __device__ __forceinline__ void gemm_phase(PG8_LAS unsigned char* lds, const Gemm g, const Sched& S, const Epi& E, int wave_s) {
;     ...
;             PG8_LDB(B0, 0, 0); PG8_LDB(B1, 0, 1); PG8_SCHED; PG8_LDA(At, 0, 0); PG8_STAGE(PG8_SA(1, 1), a1 + hstepA, voffA);
;     ...
;             PG8_LDA(At, 1, 1); PG8_STAGE(PG8_SB(1, 0), b3, voffB); PG8_STAGE(PG8_SB(1, 1), b3 + hstepB, voffB); PG8_STAGE(PG8_SA(1, 0), a3, voffA);
;             PG8_WAIT_V(8); PG8_WAIT_L(0); PG8_BAR; PG8_MMA(1, 0, At, B0); PG8_MMA(1, 1, At, B1); PG8_BAR; PG8_SCHED;
	s_add_i32 s40, s85, s34
	v_lshl_add_u64 v[194:195], v[194:195], 0, s[60:61]
	s_mov_b32 m0, s40
	ds_read_b128 v[162:165], v230 offset:49152
	ds_read_b128 v[166:169], v230 offset:50176
	ds_read_b128 v[170:173], v230 offset:51200
	ds_read_b128 v[174:177], v230 offset:52224
	ds_read_b128 v[178:181], v230 offset:53248
	ds_read_b128 v[182:185], v230 offset:54272
	ds_read_b128 v[186:189], v230 offset:55296
	ds_read_b128 v[190:193], v230 offset:56320
	global_load_lds_dwordx4 v[194:195], off
	s_add_i32 m0, s40, 0x2000
	s_add_u32 s30, s30, 0x20080
	v_lshl_add_u64 v[194:195], v[196:197], 0, s[60:61]
	s_addc_u32 s31, s31, 0
	s_add_i32 s40, s89, s34
	global_load_lds_dwordx4 v[194:195], off
	v_lshl_add_u64 v[194:195], s[30:31], 0, v[214:215]
	s_mov_b32 m0, s40
	s_nop 0
	global_load_lds_dwordx4 v[194:195], off
	v_lshl_add_u64 v[194:195], s[30:31], 0, v[210:211]
	s_add_i32 m0, s40, 0x2000
	s_nop 0
	global_load_lds_dwordx4 v[194:195], off
	v_lshl_add_u64 v[194:195], v[198:199], 0, s[60:61]
	s_mov_b32 m0, s46
	s_nop 0
	global_load_lds_dwordx4 v[194:195], off
	v_lshl_add_u64 v[194:195], v[200:201], 0, s[60:61]
	s_mov_b32 m0, s47
	s_nop 0
	global_load_lds_dwordx4 v[194:195], off
	s_waitcnt vmcnt(8)
	s_waitcnt lgkmcnt(0)
	s_barrier
	v_mfma_f32_16x16x32_bf16 v[62:65], v[106:109], v[162:165], v[62:65]
	v_mfma_f32_16x16x32_bf16 v[58:61], v[114:117], v[162:165], v[58:61]
	v_mfma_f32_16x16x32_bf16 v[46:49], v[106:109], v[170:173], v[46:49]
	v_mfma_f32_16x16x32_bf16 v[42:45], v[114:117], v[170:173], v[42:45]
	v_mfma_f32_16x16x32_bf16 v[30:33], v[106:109], v[178:181], v[30:33]
	v_mfma_f32_16x16x32_bf16 v[26:29], v[114:117], v[178:181], v[26:29]
	v_mfma_f32_16x16x32_bf16 v[14:17], v[106:109], v[186:189], v[14:17]
	v_mfma_f32_16x16x32_bf16 v[10:13], v[114:117], v[186:189], v[10:13]
	v_mfma_f32_16x16x32_bf16 v[62:65], v[110:113], v[166:169], v[62:65]
	v_mfma_f32_16x16x32_bf16 v[58:61], v[118:121], v[166:169], v[58:61]
	v_mfma_f32_16x16x32_bf16 v[46:49], v[110:113], v[174:177], v[46:49]
	v_mfma_f32_16x16x32_bf16 v[42:45], v[118:121], v[174:177], v[42:45]
	v_mfma_f32_16x16x32_bf16 v[30:33], v[110:113], v[182:185], v[30:33]
	v_mfma_f32_16x16x32_bf16 v[26:29], v[118:121], v[182:185], v[26:29]
	v_mfma_f32_16x16x32_bf16 v[14:17], v[110:113], v[190:193], v[14:17]
	v_mfma_f32_16x16x32_bf16 v[10:13], v[118:121], v[190:193], v[10:13]
	v_mfma_f32_16x16x32_bf16 v[54:57], v[122:125], v[162:165], v[54:57]
	v_mfma_f32_16x16x32_bf16 v[50:53], v[142:145], v[162:165], v[50:53]
	v_mfma_f32_16x16x32_bf16 v[38:41], v[122:125], v[170:173], v[38:41]
	v_mfma_f32_16x16x32_bf16 v[34:37], v[142:145], v[170:173], v[34:37]
	v_mfma_f32_16x16x32_bf16 v[22:25], v[122:125], v[178:181], v[22:25]
	v_mfma_f32_16x16x32_bf16 v[18:21], v[142:145], v[178:181], v[18:21]
	v_mfma_f32_16x16x32_bf16 v[6:9], v[122:125], v[186:189], v[6:9]
	v_mfma_f32_16x16x32_bf16 v[2:5], v[142:145], v[186:189], v[2:5]
	v_mfma_f32_16x16x32_bf16 v[54:57], v[126:129], v[166:169], v[54:57]
	v_mfma_f32_16x16x32_bf16 v[50:53], v[150:153], v[166:169], v[50:53]
	v_mfma_f32_16x16x32_bf16 v[38:41], v[126:129], v[174:177], v[38:41]
	v_mfma_f32_16x16x32_bf16 v[34:37], v[150:153], v[174:177], v[34:37]
	v_mfma_f32_16x16x32_bf16 v[22:25], v[126:129], v[182:185], v[22:25]
	v_mfma_f32_16x16x32_bf16 v[18:21], v[150:153], v[182:185], v[18:21]
	v_mfma_f32_16x16x32_bf16 v[6:9], v[126:129], v[190:193], v[6:9]
	v_mfma_f32_16x16x32_bf16 v[2:5], v[150:153], v[190:193], v[2:5]
	s_barrier
	s_add_i32 s84, s84, 2
	s_add_u32 s4, s4, 0x100
	s_addc_u32 s5, s5, 0
	s_add_u32 s29, s29, 0x100
	s_addc_u32 s81, s81, 0
	s_cmp_gt_u32 s84, 5
.LBB0_314:
	s_add_u32 s30, s4, 0xfff80080
	s_addc_u32 s31, s5, -1
	s_add_i32 s85, 0, 0x10000
	s_cmp_eq_u32 s84, 4
	s_cselect_b32 s41, s91, s31
	s_cselect_b32 s40, s90, s30
	s_cselect_b32 s31, s2, s81
	s_cselect_b32 s30, s3, s29
	s_add_i32 s89, 0, 0x14000
	v_add_u32_e32 v118, s85, v229
	v_add_u32_e32 v150, s89, v229
	ds_read_b128 v[106:109], v118
	ds_read_b128 v[110:113], v118 offset:1024
	ds_read_b128 v[114:117], v118 offset:2048
	ds_read_b128 v[118:121], v118 offset:3072
	ds_read_b128 v[122:125], v150
	ds_read_b128 v[126:129], v150 offset:1024
	ds_read_b128 v[142:145], v150 offset:2048
	ds_read_b128 v[150:153], v150 offset:3072
	v_lshl_add_u64 v[194:195], s[4:5], 0, v[218:219]
	s_add_i32 m0, s35, 0xc000
	ds_read_b128 v[162:165], v230
	ds_read_b128 v[166:169], v230 offset:1024
	ds_read_b128 v[170:173], v230 offset:2048
	ds_read_b128 v[174:177], v230 offset:3072
	ds_read_b128 v[178:181], v230 offset:4096
	ds_read_b128 v[182:185], v230 offset:5120
	ds_read_b128 v[186:189], v230 offset:6144
	ds_read_b128 v[190:193], v230 offset:7168
	global_load_lds_dwordx4 v[194:195], off
	v_lshl_add_u64 v[194:195], s[4:5], 0, v[220:221]
	s_add_i32 m0, s35, 0xe000
	s_nop 0
	global_load_lds_dwordx4 v[194:195], off
	s_waitcnt vmcnt(8)
	s_waitcnt lgkmcnt(0)
	s_barrier
; #define PG8_STAGE(bufoff, gbase, voff) do { _Pragma("unroll") for (int _i = 0; _i < 2; ++_i) \
;         __builtin_amdgcn_global_load_lds((const unsigned*)((const char*)(gbase) + (voff)[_i]), (PG8_LAS unsigned*)(lds + (bufoff) + ldsw + _i * 8192), 16, 0, 0); } while (0)
; #define PG8_LDA(dst, b, h) do { _Pragma("unroll") for (int m = 0; m < 4; ++m) _Pragma("unroll") for (int k = 0; k < 2; ++k) dst[m][k] = *(const PG8_LAS bf16x8*)(lds + PG8_SA(b, h) + aoff + m * 2048 + k * 1024); } while (0)
; #define PG8_MMA(ai, bj, At, Bt) do { __builtin_amdgcn_s_setprio(1); _Pragma("unroll") for (int m = 0; m < 4; ++m) _Pragma("unroll") for (int n = 0; n < 2; ++n) _Pragma("unroll") for (int k = 0; k < 2; ++k) \
;         acc[ai][bj][m][n] = __builtin_amdgcn_mfma_f32_16x16x32_bf16(Bt[n][k], At[m][k], acc[ai][bj][m][n], 0, 0, 0); __builtin_amdgcn_s_setprio(0); } while (0)
; #define PG8_WAIT_V(n) asm volatile("s_waitcnt vmcnt(" #n ")" ::: "memory")
; #define PG8_WAIT_L(n) asm volatile("s_waitcnt lgkmcnt(" #n ")" ::: "memory")
; #define PG8_BAR __builtin_amdgcn_s_barrier()
; #define PG8_SCHED __builtin_amdgcn_sched_barrier(0)
; template <class Epi, class Sched, bool ALIGN_EPI = false, bool SP2 = false>
; __device__ __forceinline__ void gemm_phase(PG8_LAS unsigned char* lds, const Gemm g, const Sched& S, const Epi& E, int wave_s) {
;     ...
;             PG8_WAIT_V(8); PG8_WAIT_L(0); PG8_BAR; PG8_MMA(0, 0, At, B0); PG8_MMA(0, 1, At, B1); PG8_BAR; PG8_SCHED;
;             PG8_LDA(At, 0, 1); PG8_STAGE(PG8_SB(0, 0), b2, voffB); PG8_STAGE(PG8_SB(0, 1), b2 + hstepB, voffB); PG8_STAGE(PG8_SA(0, 0), a2, voffA);
;             PG8_WAIT_V(8); PG8_WAIT_L(0); PG8_BAR; PG8_MMA(1, 0, At, B0); PG8_MMA(1, 1, At, B1); PG8_BAR; PG8_SCHED;
	v_mfma_f32_16x16x32_bf16 v[158:161], v[106:109], v[162:165], v[158:161]
	v_mfma_f32_16x16x32_bf16 v[154:157], v[114:117], v[162:165], v[154:157]
	v_mfma_f32_16x16x32_bf16 v[134:137], v[106:109], v[170:173], v[134:137]
	v_mfma_f32_16x16x32_bf16 v[130:133], v[114:117], v[170:173], v[130:133]
	v_mfma_f32_16x16x32_bf16 v[94:97], v[106:109], v[178:181], v[94:97]
	v_mfma_f32_16x16x32_bf16 v[90:93], v[114:117], v[178:181], v[90:93]
	v_mfma_f32_16x16x32_bf16 v[78:81], v[106:109], v[186:189], v[78:81]
	v_mfma_f32_16x16x32_bf16 v[74:77], v[114:117], v[186:189], v[74:77]
	v_mfma_f32_16x16x32_bf16 v[158:161], v[110:113], v[166:169], v[158:161]
	v_mfma_f32_16x16x32_bf16 v[154:157], v[118:121], v[166:169], v[154:157]
	v_mfma_f32_16x16x32_bf16 v[134:137], v[110:113], v[174:177], v[134:137]
	v_mfma_f32_16x16x32_bf16 v[130:133], v[118:121], v[174:177], v[130:133]
	v_mfma_f32_16x16x32_bf16 v[94:97], v[110:113], v[182:185], v[94:97]
	v_mfma_f32_16x16x32_bf16 v[90:93], v[118:121], v[182:185], v[90:93]
	v_mfma_f32_16x16x32_bf16 v[78:81], v[110:113], v[190:193], v[78:81]
	v_mfma_f32_16x16x32_bf16 v[74:77], v[118:121], v[190:193], v[74:77]
	v_mfma_f32_16x16x32_bf16 v[146:149], v[122:125], v[162:165], v[146:149]
	v_mfma_f32_16x16x32_bf16 v[138:141], v[142:145], v[162:165], v[138:141]
	v_mfma_f32_16x16x32_bf16 v[102:105], v[122:125], v[170:173], v[102:105]
	v_mfma_f32_16x16x32_bf16 v[98:101], v[142:145], v[170:173], v[98:101]
	v_mfma_f32_16x16x32_bf16 v[86:89], v[122:125], v[178:181], v[86:89]
	v_mfma_f32_16x16x32_bf16 v[82:85], v[142:145], v[178:181], v[82:85]
	v_mfma_f32_16x16x32_bf16 v[70:73], v[122:125], v[186:189], v[70:73]
	v_mfma_f32_16x16x32_bf16 v[66:69], v[142:145], v[186:189], v[66:69]
	v_mfma_f32_16x16x32_bf16 v[146:149], v[126:129], v[166:169], v[146:149]
	v_mfma_f32_16x16x32_bf16 v[138:141], v[150:153], v[166:169], v[138:141]
	v_mfma_f32_16x16x32_bf16 v[102:105], v[126:129], v[174:177], v[102:105]
	v_mfma_f32_16x16x32_bf16 v[98:101], v[150:153], v[174:177], v[98:101]
	v_mfma_f32_16x16x32_bf16 v[86:89], v[126:129], v[182:185], v[86:89]
	v_mfma_f32_16x16x32_bf16 v[82:85], v[150:153], v[182:185], v[82:85]
	v_mfma_f32_16x16x32_bf16 v[70:73], v[126:129], v[190:193], v[70:73]
	v_mfma_f32_16x16x32_bf16 v[66:69], v[150:153], v[190:193], v[66:69]
	s_barrier
	s_add_i32 s85, s85, s34
	v_lshl_add_u64 v[194:195], s[30:31], 0, v[214:215]
	s_mov_b32 m0, s85
	ds_read_b128 v[162:165], v230 offset:16384
	ds_read_b128 v[166:169], v230 offset:17408
	ds_read_b128 v[170:173], v230 offset:18432
	ds_read_b128 v[174:177], v230 offset:19456
	ds_read_b128 v[178:181], v230 offset:20480
	ds_read_b128 v[182:185], v230 offset:21504
	ds_read_b128 v[186:189], v230 offset:22528
	ds_read_b128 v[190:193], v230 offset:23552
	global_load_lds_dwordx4 v[194:195], off
	s_add_i32 m0, s85, 0x2000
	s_add_u32 s94, s30, 0x20000
	v_lshl_add_u64 v[196:197], s[30:31], 0, v[210:211]
	s_addc_u32 s95, s31, 0
	s_add_i32 s85, s89, s34
	global_load_lds_dwordx4 v[196:197], off
	v_lshl_add_u64 v[198:199], s[94:95], 0, v[214:215]
	s_mov_b32 m0, s85
	v_lshl_add_u64 v[200:201], s[40:41], 0, v[212:213]
	global_load_lds_dwordx4 v[198:199], off
	v_lshl_add_u64 v[198:199], s[94:95], 0, v[210:211]
	s_add_i32 m0, s85, 0x2000
	s_nop 0
	global_load_lds_dwordx4 v[198:199], off
	v_lshl_add_u64 v[198:199], s[40:41], 0, v[216:217]
	s_mov_b32 m0, s35
	s_nop 0
	global_load_lds_dwordx4 v[198:199], off
	s_mov_b32 m0, s36
	s_nop 0
	global_load_lds_dwordx4 v[200:201], off
	s_waitcnt vmcnt(8)
	s_waitcnt lgkmcnt(0)
	s_barrier
	v_mfma_f32_16x16x32_bf16 v[62:65], v[106:109], v[162:165], v[62:65]
	v_mfma_f32_16x16x32_bf16 v[58:61], v[114:117], v[162:165], v[58:61]
	v_mfma_f32_16x16x32_bf16 v[46:49], v[106:109], v[170:173], v[46:49]
	v_mfma_f32_16x16x32_bf16 v[42:45], v[114:117], v[170:173], v[42:45]
	v_mfma_f32_16x16x32_bf16 v[30:33], v[106:109], v[178:181], v[30:33]
	v_mfma_f32_16x16x32_bf16 v[26:29], v[114:117], v[178:181], v[26:29]
	v_mfma_f32_16x16x32_bf16 v[14:17], v[106:109], v[186:189], v[14:17]
	v_mfma_f32_16x16x32_bf16 v[10:13], v[114:117], v[186:189], v[10:13]
	v_mfma_f32_16x16x32_bf16 v[62:65], v[110:113], v[166:169], v[62:65]
	v_mfma_f32_16x16x32_bf16 v[58:61], v[118:121], v[166:169], v[58:61]
	v_mfma_f32_16x16x32_bf16 v[46:49], v[110:113], v[174:177], v[46:49]
	v_mfma_f32_16x16x32_bf16 v[42:45], v[118:121], v[174:177], v[42:45]
	v_mfma_f32_16x16x32_bf16 v[30:33], v[110:113], v[182:185], v[30:33]
	v_mfma_f32_16x16x32_bf16 v[26:29], v[118:121], v[182:185], v[26:29]
	v_mfma_f32_16x16x32_bf16 v[14:17], v[110:113], v[190:193], v[14:17]
	v_mfma_f32_16x16x32_bf16 v[10:13], v[118:121], v[190:193], v[10:13]
	v_mfma_f32_16x16x32_bf16 v[54:57], v[122:125], v[162:165], v[54:57]
	v_mfma_f32_16x16x32_bf16 v[50:53], v[142:145], v[162:165], v[50:53]
	v_mfma_f32_16x16x32_bf16 v[38:41], v[122:125], v[170:173], v[38:41]
	v_mfma_f32_16x16x32_bf16 v[34:37], v[142:145], v[170:173], v[34:37]
	v_mfma_f32_16x16x32_bf16 v[22:25], v[122:125], v[178:181], v[22:25]
	v_mfma_f32_16x16x32_bf16 v[18:21], v[142:145], v[178:181], v[18:21]
	v_mfma_f32_16x16x32_bf16 v[6:9], v[122:125], v[186:189], v[6:9]
	v_mfma_f32_16x16x32_bf16 v[2:5], v[142:145], v[186:189], v[2:5]
	v_mfma_f32_16x16x32_bf16 v[54:57], v[126:129], v[166:169], v[54:57]
	v_mfma_f32_16x16x32_bf16 v[50:53], v[150:153], v[166:169], v[50:53]
	v_mfma_f32_16x16x32_bf16 v[38:41], v[126:129], v[174:177], v[38:41]
	v_mfma_f32_16x16x32_bf16 v[34:37], v[150:153], v[174:177], v[34:37]
	v_mfma_f32_16x16x32_bf16 v[22:25], v[126:129], v[182:185], v[22:25]
	v_mfma_f32_16x16x32_bf16 v[18:21], v[150:153], v[182:185], v[18:21]
	v_mfma_f32_16x16x32_bf16 v[6:9], v[126:129], v[190:193], v[6:9]
	v_mfma_f32_16x16x32_bf16 v[2:5], v[150:153], v[190:193], v[2:5]
	s_barrier
; #define PG8_STAGE(bufoff, gbase, voff) do { _Pragma("unroll") for (int _i = 0; _i < 2; ++_i) \
;         __builtin_amdgcn_global_load_lds((const unsigned*)((const char*)(gbase) + (voff)[_i]), (PG8_LAS unsigned*)(lds + (bufoff) + ldsw + _i * 8192), 16, 0, 0); } while (0)
; #define PG8_LDA(dst, b, h) do { _Pragma("unroll") for (int m = 0; m < 4; ++m) _Pragma("unroll") for (int k = 0; k < 2; ++k) dst[m][k] = *(const PG8_LAS bf16x8*)(lds + PG8_SA(b, h) + aoff + m * 2048 + k * 1024); } while (0)
; #define PG8_LDB(dst, b, h) do { _Pragma("unroll") for (int n = 0; n < 2; ++n) _Pragma("unroll") for (int k = 0; k < 2; ++k) dst[n][k] = *(const PG8_LAS bf16x8*)(lds + PG8_SB(b, h) + boff + n * 2048 + k * 1024); } while (0)
; #define PG8_MMA(ai, bj, At, Bt) do { __builtin_amdgcn_s_setprio(1); _Pragma("unroll") for (int m = 0; m < 4; ++m) _Pragma("unroll") for (int n = 0; n < 2; ++n) _Pragma("unroll") for (int k = 0; k < 2; ++k) \
;         acc[ai][bj][m][n] = __builtin_amdgcn_mfma_f32_16x16x32_bf16(Bt[n][k], At[m][k], acc[ai][bj][m][n], 0, 0, 0); __builtin_amdgcn_s_setprio(0); } while (0)
; #define PG8_WAIT_V(n) asm volatile("s_waitcnt vmcnt(" #n ")" ::: "memory")
; #define PG8_WAIT_L(n) asm volatile("s_waitcnt lgkmcnt(" #n ")" ::: "memory")
; #define PG8_BAR __builtin_amdgcn_s_barrier()
; #define PG8_SCHED __builtin_amdgcn_sched_barrier(0)
; template <class Epi, class Sched, bool ALIGN_EPI = false, bool SP2 = false>
; __device__ __forceinline__ void gemm_phase(PG8_LAS unsigned char* lds, const Gemm g, const Sched& S, const Epi& E, int wave_s) {
;     ...
;             PG8_LDB(B0, 1, 0); PG8_LDB(B1, 1, 1); PG8_SCHED; PG8_LDA(At, 1, 0); PG8_STAGE(PG8_SA(0, 1), a2 + hstepA, voffA);
;             PG8_WAIT_V(8); PG8_WAIT_L(0); PG8_BAR; PG8_MMA(0, 0, At, B0); PG8_MMA(0, 1, At, B1); PG8_BAR; PG8_SCHED;
	s_add_i32 s85, 0, 0x18000
	s_add_i32 s89, 0, 0x1c000
	v_add_u32_e32 v118, s85, v229
	v_add_u32_e32 v150, s89, v229
	ds_read_b128 v[106:109], v118
	ds_read_b128 v[110:113], v118 offset:1024
	ds_read_b128 v[114:117], v118 offset:2048
	ds_read_b128 v[118:121], v118 offset:3072
	ds_read_b128 v[122:125], v150
	ds_read_b128 v[126:129], v150 offset:1024
	ds_read_b128 v[142:145], v150 offset:2048
	ds_read_b128 v[150:153], v150 offset:3072
	s_add_u32 s40, s40, 0x80000
	s_addc_u32 s41, s41, 0
	s_mov_b32 m0, s37
	v_lshl_add_u64 v[202:203], s[40:41], 0, v[216:217]
	ds_read_b128 v[162:165], v230 offset:32768
	ds_read_b128 v[166:169], v230 offset:33792
	ds_read_b128 v[170:173], v230 offset:34816
	ds_read_b128 v[174:177], v230 offset:35840
	ds_read_b128 v[178:181], v230 offset:36864
	ds_read_b128 v[182:185], v230 offset:37888
	ds_read_b128 v[186:189], v230 offset:38912
	ds_read_b128 v[190:193], v230 offset:39936
	global_load_lds_dwordx4 v[202:203], off
	v_lshl_add_u64 v[202:203], s[40:41], 0, v[212:213]
	s_mov_b32 m0, s42
	s_nop 0
	global_load_lds_dwordx4 v[202:203], off
	s_waitcnt vmcnt(8)
	s_waitcnt lgkmcnt(0)
	s_barrier
	v_mfma_f32_16x16x32_bf16 v[158:161], v[106:109], v[162:165], v[158:161]
	v_mfma_f32_16x16x32_bf16 v[154:157], v[114:117], v[162:165], v[154:157]
	v_mfma_f32_16x16x32_bf16 v[134:137], v[106:109], v[170:173], v[134:137]
	v_mfma_f32_16x16x32_bf16 v[130:133], v[114:117], v[170:173], v[130:133]
	v_mfma_f32_16x16x32_bf16 v[94:97], v[106:109], v[178:181], v[94:97]
	v_mfma_f32_16x16x32_bf16 v[90:93], v[114:117], v[178:181], v[90:93]
	v_mfma_f32_16x16x32_bf16 v[78:81], v[106:109], v[186:189], v[78:81]
	v_mfma_f32_16x16x32_bf16 v[74:77], v[114:117], v[186:189], v[74:77]
	v_mfma_f32_16x16x32_bf16 v[158:161], v[110:113], v[166:169], v[158:161]
	v_mfma_f32_16x16x32_bf16 v[154:157], v[118:121], v[166:169], v[154:157]
	v_mfma_f32_16x16x32_bf16 v[134:137], v[110:113], v[174:177], v[134:137]
	v_mfma_f32_16x16x32_bf16 v[130:133], v[118:121], v[174:177], v[130:133]
	v_mfma_f32_16x16x32_bf16 v[94:97], v[110:113], v[182:185], v[94:97]
	v_mfma_f32_16x16x32_bf16 v[90:93], v[118:121], v[182:185], v[90:93]
	v_mfma_f32_16x16x32_bf16 v[78:81], v[110:113], v[190:193], v[78:81]
	v_mfma_f32_16x16x32_bf16 v[74:77], v[118:121], v[190:193], v[74:77]
	v_mfma_f32_16x16x32_bf16 v[146:149], v[122:125], v[162:165], v[146:149]
	v_mfma_f32_16x16x32_bf16 v[138:141], v[142:145], v[162:165], v[138:141]
	v_mfma_f32_16x16x32_bf16 v[102:105], v[122:125], v[170:173], v[102:105]
	v_mfma_f32_16x16x32_bf16 v[98:101], v[142:145], v[170:173], v[98:101]
	v_mfma_f32_16x16x32_bf16 v[86:89], v[122:125], v[178:181], v[86:89]
	v_mfma_f32_16x16x32_bf16 v[82:85], v[142:145], v[178:181], v[82:85]
	v_mfma_f32_16x16x32_bf16 v[70:73], v[122:125], v[186:189], v[70:73]
	v_mfma_f32_16x16x32_bf16 v[66:69], v[142:145], v[186:189], v[66:69]
	v_mfma_f32_16x16x32_bf16 v[146:149], v[126:129], v[166:169], v[146:149]
	v_mfma_f32_16x16x32_bf16 v[138:141], v[150:153], v[166:169], v[138:141]
	v_mfma_f32_16x16x32_bf16 v[102:105], v[126:129], v[174:177], v[102:105]
	v_mfma_f32_16x16x32_bf16 v[98:101], v[150:153], v[174:177], v[98:101]
	v_mfma_f32_16x16x32_bf16 v[86:89], v[126:129], v[182:185], v[86:89]
	v_mfma_f32_16x16x32_bf16 v[82:85], v[150:153], v[182:185], v[82:85]
	v_mfma_f32_16x16x32_bf16 v[70:73], v[126:129], v[190:193], v[70:73]
	v_mfma_f32_16x16x32_bf16 v[66:69], v[150:153], v[190:193], v[66:69]
	s_barrier
; #define PG8_STAGE(bufoff, gbase, voff) do { _Pragma("unroll") for (int _i = 0; _i < 2; ++_i) \
;         __builtin_amdgcn_global_load_lds((const unsigned*)((const char*)(gbase) + (voff)[_i]), (PG8_LAS unsigned*)(lds + (bufoff) + ldsw + _i * 8192), 16, 0, 0); } while (0)
; #define PG8_LDA(dst, b, h) do { _Pragma("unroll") for (int m = 0; m < 4; ++m) _Pragma("unroll") for (int k = 0; k < 2; ++k) dst[m][k] = *(const PG8_LAS bf16x8*)(lds + PG8_SA(b, h) + aoff + m * 2048 + k * 1024); } while (0)
; #define PG8_MMA(ai, bj, At, Bt) do { __builtin_amdgcn_s_setprio(1); _Pragma("unroll") for (int m = 0; m < 4; ++m) _Pragma("unroll") for (int n = 0; n < 2; ++n) _Pragma("unroll") for (int k = 0; k < 2; ++k) \
;         acc[ai][bj][m][n] = __builtin_amdgcn_mfma_f32_16x16x32_bf16(Bt[n][k], At[m][k], acc[ai][bj][m][n], 0, 0, 0); __builtin_amdgcn_s_setprio(0); } while (0)
; #define PG8_WAIT_V(n) asm volatile("s_waitcnt vmcnt(" #n ")" ::: "memory")
; #define PG8_WAIT_L(n) asm volatile("s_waitcnt lgkmcnt(" #n ")" ::: "memory")
; #define PG8_BAR __builtin_amdgcn_s_barrier()
; #define PG8_SCHED __builtin_amdgcn_sched_barrier(0)
; template <class Epi, class Sched, bool ALIGN_EPI = false, bool SP2 = false>
; __device__ __forceinline__ void gemm_phase(PG8_LAS unsigned char* lds, const Gemm g, const Sched& S, const Epi& E, int wave_s) {
;     ...
;             PG8_LDA(At, 1, 1); PG8_STAGE(PG8_SB(1, 0), b3, voffB); PG8_STAGE(PG8_SB(1, 1), b3 + hstepB, voffB); PG8_STAGE(PG8_SA(1, 0), a3, voffA);
;             PG8_WAIT_V(8); PG8_WAIT_L(0); PG8_BAR; PG8_MMA(1, 0, At, B0); PG8_MMA(1, 1, At, B1); PG8_BAR; PG8_SCHED;
;     ...
;         if constexpr (ALIGN_EPI) { if (wr == 0) PG8_BAR; }
	s_add_i32 s40, s85, s34
	v_lshl_add_u64 v[194:195], v[194:195], 0, s[60:61]
	s_mov_b32 m0, s40
	ds_read_b128 v[162:165], v230 offset:49152
	ds_read_b128 v[166:169], v230 offset:50176
	ds_read_b128 v[170:173], v230 offset:51200
	ds_read_b128 v[174:177], v230 offset:52224
	ds_read_b128 v[178:181], v230 offset:53248
	ds_read_b128 v[182:185], v230 offset:54272
	ds_read_b128 v[186:189], v230 offset:55296
	ds_read_b128 v[190:193], v230 offset:56320
	global_load_lds_dwordx4 v[194:195], off
	s_add_i32 m0, s40, 0x2000
	s_add_u32 s30, s30, 0x20080
	v_lshl_add_u64 v[194:195], v[196:197], 0, s[60:61]
	s_addc_u32 s31, s31, 0
	s_add_i32 s40, s89, s34
	global_load_lds_dwordx4 v[194:195], off
	v_lshl_add_u64 v[194:195], s[30:31], 0, v[214:215]
	s_mov_b32 m0, s40
	s_nop 0
	global_load_lds_dwordx4 v[194:195], off
	v_lshl_add_u64 v[194:195], s[30:31], 0, v[210:211]
	s_add_i32 m0, s40, 0x2000
	s_nop 0
	global_load_lds_dwordx4 v[194:195], off
	v_lshl_add_u64 v[194:195], v[198:199], 0, s[60:61]
	s_mov_b32 m0, s46
	s_nop 0
	global_load_lds_dwordx4 v[194:195], off
	v_lshl_add_u64 v[194:195], v[200:201], 0, s[60:61]
	s_mov_b32 m0, s47
	s_nop 0
	global_load_lds_dwordx4 v[194:195], off
	s_waitcnt vmcnt(8)
	s_waitcnt lgkmcnt(0)
	s_barrier
	v_mfma_f32_16x16x32_bf16 v[62:65], v[106:109], v[162:165], v[62:65]
	v_mfma_f32_16x16x32_bf16 v[58:61], v[114:117], v[162:165], v[58:61]
	v_mfma_f32_16x16x32_bf16 v[46:49], v[106:109], v[170:173], v[46:49]
	v_mfma_f32_16x16x32_bf16 v[42:45], v[114:117], v[170:173], v[42:45]
	v_mfma_f32_16x16x32_bf16 v[30:33], v[106:109], v[178:181], v[30:33]
	v_mfma_f32_16x16x32_bf16 v[26:29], v[114:117], v[178:181], v[26:29]
	v_mfma_f32_16x16x32_bf16 v[14:17], v[106:109], v[186:189], v[14:17]
	v_mfma_f32_16x16x32_bf16 v[10:13], v[114:117], v[186:189], v[10:13]
	v_mfma_f32_16x16x32_bf16 v[62:65], v[110:113], v[166:169], v[62:65]
	v_mfma_f32_16x16x32_bf16 v[58:61], v[118:121], v[166:169], v[58:61]
	v_mfma_f32_16x16x32_bf16 v[46:49], v[110:113], v[174:177], v[46:49]
	v_mfma_f32_16x16x32_bf16 v[42:45], v[118:121], v[174:177], v[42:45]
	v_mfma_f32_16x16x32_bf16 v[30:33], v[110:113], v[182:185], v[30:33]
	v_mfma_f32_16x16x32_bf16 v[26:29], v[118:121], v[182:185], v[26:29]
	v_mfma_f32_16x16x32_bf16 v[14:17], v[110:113], v[190:193], v[14:17]
	v_mfma_f32_16x16x32_bf16 v[10:13], v[118:121], v[190:193], v[10:13]
	v_mfma_f32_16x16x32_bf16 v[54:57], v[122:125], v[162:165], v[54:57]
	v_mfma_f32_16x16x32_bf16 v[50:53], v[142:145], v[162:165], v[50:53]
	v_mfma_f32_16x16x32_bf16 v[38:41], v[122:125], v[170:173], v[38:41]
	v_mfma_f32_16x16x32_bf16 v[34:37], v[142:145], v[170:173], v[34:37]
	v_mfma_f32_16x16x32_bf16 v[22:25], v[122:125], v[178:181], v[22:25]
	v_mfma_f32_16x16x32_bf16 v[18:21], v[142:145], v[178:181], v[18:21]
	v_mfma_f32_16x16x32_bf16 v[6:9], v[122:125], v[186:189], v[6:9]
	v_mfma_f32_16x16x32_bf16 v[2:5], v[142:145], v[186:189], v[2:5]
	v_mfma_f32_16x16x32_bf16 v[54:57], v[126:129], v[166:169], v[54:57]
	v_mfma_f32_16x16x32_bf16 v[50:53], v[150:153], v[166:169], v[50:53]
	v_mfma_f32_16x16x32_bf16 v[38:41], v[126:129], v[174:177], v[38:41]
	v_mfma_f32_16x16x32_bf16 v[34:37], v[150:153], v[174:177], v[34:37]
	v_mfma_f32_16x16x32_bf16 v[22:25], v[126:129], v[182:185], v[22:25]
	v_mfma_f32_16x16x32_bf16 v[18:21], v[150:153], v[182:185], v[18:21]
	v_mfma_f32_16x16x32_bf16 v[6:9], v[126:129], v[190:193], v[6:9]
	v_mfma_f32_16x16x32_bf16 v[2:5], v[150:153], v[190:193], v[2:5]
	s_barrier
	s_add_i32 s84, s84, 2
	s_add_u32 s4, s4, 0x100
	s_addc_u32 s5, s5, 0
	s_add_u32 s29, s29, 0x100
	s_addc_u32 s81, s81, 0
	s_cmp_gt_u32 s84, 5
	s_cbranch_scc0 .LBB0_314
	s_and_b64 vcc, exec, s[20:21]
	s_cbranch_vccz .LBB0_317
	s_barrier

; #define PG8_STAGE(bufoff, gbase, voff) do { _Pragma("unroll") for (int _i = 0; _i < 2; ++_i) \
;         __builtin_amdgcn_global_load_lds((const unsigned*)((const char*)(gbase) + (voff)[_i]), (PG8_LAS unsigned*)(lds + (bufoff) + ldsw + _i * 8192), 16, 0, 0); } while (0)
; #define PG8_LDA(dst, b, h) do { _Pragma("unroll") for (int m = 0; m < 4; ++m) _Pragma("unroll") for (int k = 0; k < 2; ++k) dst[m][k] = *(const PG8_LAS bf16x8*)(lds + PG8_SA(b, h) + aoff + m * 2048 + k * 1024); } while (0)
; #define PG8_LDB(dst, b, h) do { _Pragma("unroll") for (int n = 0; n < 2; ++n) _Pragma("unroll") for (int k = 0; k < 2; ++k) dst[n][k] = *(const PG8_LAS bf16x8*)(lds + PG8_SB(b, h) + boff + n * 2048 + k * 1024); } while (0)
; #define PG8_WAIT_V(n) asm volatile("s_waitcnt vmcnt(" #n ")" ::: "memory")
; #define PG8_WAIT_L(n) asm volatile("s_waitcnt lgkmcnt(" #n ")" ::: "memory")
; #define PG8_BAR __builtin_amdgcn_s_barrier()
; template <class Epi, class Sched, bool ALIGN_EPI = false, bool SP2 = false>
; __device__ __forceinline__ void gemm_phase(PG8_LAS unsigned char* lds, const Gemm g, const Sched& S, const Epi& E, int wave_s) {
;     ...
;         const bool has_next = S.next(ui + 1, nxt);
;         const char* nA = has_next ? (const char*)g.A + (size_t)nxt.pm * tstepA + (size_t)(nxt.pn / g.npg) * (size_t)(K * 2) : cA; const char* nB = has_next ? (const char*)g.Bt + (size_t)nxt.pn * tstepB : cB;
;         for (int t = 0; t < nt; t += 2) {
;             const bool last = (t == nt - 2);
;             const char* a1 = cA + (size_t)(t + 1) * kstep;
;             const char* a2 = last ? nA : cA + (size_t)(t + 2) * kstep; const char* b2 = last ? nB : cB + (size_t)(t + 2) * kstep;
;             const char* a3 = a2 + kstep; const char* b3 = b2 + kstep;
;             if (last && has_next) S.a_ready(nxt);
;             if constexpr (SP2) {
;             PG8_LDB(B0, 0, 0); PG8_LDB(B1, 0, 1); PG8_SCHED; PG8_LDA(At, 0, 0); PG8_STAGE(PG8_SA(1, 1), a1 + hstepA, voffA);
;             PG8_WAIT_V(8); PG8_WAIT_L(0); PG8_BAR; PG8_MMA(0, 0, At, B0); PG8_MMA(0, 1, At, B1); PG8_BAR; PG8_SCHED;
;             PG8_LDA(At, 0, 1); PG8_STAGE(PG8_SB(0, 0), b2, voffB); PG8_STAGE(PG8_SB(0, 1), b2 + hstepB, voffB); PG8_STAGE(PG8_SA(0, 0), a2, voffA);
;             PG8_WAIT_V(8); PG8_WAIT_L(0); PG8_BAR; PG8_MMA(1, 0, At, B0); PG8_MMA(1, 1, At, B1); PG8_BAR; PG8_SCHED;
.LBB0_411:
	s_ashr_i32 s15, s14, 31
	s_lshl_b64 s[2:3], s[14:15], 20
	s_add_u32 s28, s22, s2
	s_addc_u32 s29, s23, s3
	s_and_b64 s[2:3], s[4:5], exec
	s_cselect_b32 s2, s29, s31
	s_cselect_b32 s3, s28, s30
	s_add_u32 s4, s40, 0x80080
	s_addc_u32 s5, s41, 0
	s_add_u32 s15, s30, 0x100
	s_addc_u32 s21, s31, 0
	s_mov_b32 s94, -2
	s_add_u32 s30, s4, 0xfff80080
	s_addc_u32 s31, s5, -1
	s_add_i32 s95, 0, 0x10000
	s_cmp_eq_u32 s94, 28
	s_cselect_b32 s41, s27, s31
	s_cselect_b32 s40, s26, s30
	v_add_u32_e32 v149, s95, v147
	s_cselect_b32 s31, s2, s21
	s_cselect_b32 s30, s3, s15
	s_add_i32 vcc_lo, 0, 0x14000
	ds_read_b128 v[142:145], v149
	ds_read_b128 v[150:153], v149 offset:1024
	ds_read_b128 v[154:157], v149 offset:2048
	ds_read_b128 v[158:161], v149 offset:3072
	v_add_u32_e32 v149, vcc_lo, v147
	ds_read_b128 v[162:165], v149
	ds_read_b128 v[166:169], v149 offset:1024
	ds_read_b128 v[170:173], v149 offset:2048
	ds_read_b128 v[174:177], v149 offset:3072
	v_lshl_add_u64 v[210:211], s[4:5], 0, v[138:139]
	s_add_i32 m0, s35, 0xc000
	ds_read_b128 v[178:181], v148
	ds_read_b128 v[182:185], v148 offset:1024
	ds_read_b128 v[186:189], v148 offset:2048
	ds_read_b128 v[190:193], v148 offset:3072
	ds_read_b128 v[194:197], v148 offset:4096
	ds_read_b128 v[198:201], v148 offset:5120
	ds_read_b128 v[202:205], v148 offset:6144
	ds_read_b128 v[206:209], v148 offset:7168
	global_load_lds_dwordx4 v[210:211], off
	v_lshl_add_u64 v[210:211], s[4:5], 0, v[140:141]
	s_add_i32 m0, s35, 0xe000
	s_nop 0
	global_load_lds_dwordx4 v[210:211], off
	s_waitcnt vmcnt(8)
	s_waitcnt lgkmcnt(0)
	s_barrier
	v_mfma_f32_16x16x32_bf16 v[126:129], v[142:145], v[178:181], 0
	v_mfma_f32_16x16x32_bf16 v[122:125], v[154:157], v[178:181], 0
	v_mfma_f32_16x16x32_bf16 v[110:113], v[142:145], v[186:189], 0
	v_mfma_f32_16x16x32_bf16 v[106:109], v[154:157], v[186:189], 0
	v_mfma_f32_16x16x32_bf16 v[94:97], v[142:145], v[194:197], 0
	v_mfma_f32_16x16x32_bf16 v[90:93], v[154:157], v[194:197], 0
	v_mfma_f32_16x16x32_bf16 v[78:81], v[142:145], v[202:205], 0
	v_mfma_f32_16x16x32_bf16 v[74:77], v[154:157], v[202:205], 0
	v_mfma_f32_16x16x32_bf16 v[126:129], v[150:153], v[182:185], v[126:129]
	v_mfma_f32_16x16x32_bf16 v[122:125], v[158:161], v[182:185], v[122:125]
	v_mfma_f32_16x16x32_bf16 v[110:113], v[150:153], v[190:193], v[110:113]
	v_mfma_f32_16x16x32_bf16 v[106:109], v[158:161], v[190:193], v[106:109]
	v_mfma_f32_16x16x32_bf16 v[94:97], v[150:153], v[198:201], v[94:97]
	v_mfma_f32_16x16x32_bf16 v[90:93], v[158:161], v[198:201], v[90:93]
	v_mfma_f32_16x16x32_bf16 v[78:81], v[150:153], v[206:209], v[78:81]
	v_mfma_f32_16x16x32_bf16 v[74:77], v[158:161], v[206:209], v[74:77]
	v_mfma_f32_16x16x32_bf16 v[118:121], v[162:165], v[178:181], 0
	v_mfma_f32_16x16x32_bf16 v[114:117], v[170:173], v[178:181], 0
	v_mfma_f32_16x16x32_bf16 v[102:105], v[162:165], v[186:189], 0
	v_mfma_f32_16x16x32_bf16 v[98:101], v[170:173], v[186:189], 0
	v_mfma_f32_16x16x32_bf16 v[86:89], v[162:165], v[194:197], 0
	v_mfma_f32_16x16x32_bf16 v[82:85], v[170:173], v[194:197], 0
	v_mfma_f32_16x16x32_bf16 v[70:73], v[162:165], v[202:205], 0
	v_mfma_f32_16x16x32_bf16 v[66:69], v[170:173], v[202:205], 0
	v_mfma_f32_16x16x32_bf16 v[118:121], v[166:169], v[182:185], v[118:121]
	v_mfma_f32_16x16x32_bf16 v[114:117], v[174:177], v[182:185], v[114:117]
	v_mfma_f32_16x16x32_bf16 v[102:105], v[166:169], v[190:193], v[102:105]
	v_mfma_f32_16x16x32_bf16 v[98:101], v[174:177], v[190:193], v[98:101]
	v_mfma_f32_16x16x32_bf16 v[86:89], v[166:169], v[198:201], v[86:89]
	v_mfma_f32_16x16x32_bf16 v[82:85], v[174:177], v[198:201], v[82:85]
	v_mfma_f32_16x16x32_bf16 v[70:73], v[166:169], v[206:209], v[70:73]
	v_mfma_f32_16x16x32_bf16 v[66:69], v[174:177], v[206:209], v[66:69]
	s_barrier
	s_add_i32 s95, s95, s34
	v_lshl_add_u64 v[210:211], s[30:31], 0, v[132:133]
	s_mov_b32 m0, s95
	ds_read_b128 v[178:181], v148 offset:16384
	ds_read_b128 v[182:185], v148 offset:17408
	ds_read_b128 v[186:189], v148 offset:18432
	ds_read_b128 v[190:193], v148 offset:19456
	ds_read_b128 v[194:197], v148 offset:20480
	ds_read_b128 v[198:201], v148 offset:21504
	ds_read_b128 v[202:205], v148 offset:22528
	ds_read_b128 v[206:209], v148 offset:23552
	global_load_lds_dwordx4 v[210:211], off
	s_add_i32 m0, s95, 0x2000
	s_add_u32 s96, s30, 0x80000
	v_lshl_add_u64 v[212:213], s[30:31], 0, v[136:137]
	s_addc_u32 s97, s31, 0
	s_add_i32 s95, vcc_lo, s34
	global_load_lds_dwordx4 v[212:213], off
	v_lshl_add_u64 v[214:215], s[96:97], 0, v[132:133]
	s_mov_b32 m0, s95
	v_lshl_add_u64 v[216:217], s[40:41], 0, v[134:135]
	global_load_lds_dwordx4 v[214:215], off
	v_lshl_add_u64 v[214:215], s[96:97], 0, v[136:137]
	s_add_i32 m0, s95, 0x2000
	s_nop 0
	global_load_lds_dwordx4 v[214:215], off
	v_lshl_add_u64 v[214:215], s[40:41], 0, v[130:131]
	s_mov_b32 m0, s35
	s_nop 0
	global_load_lds_dwordx4 v[214:215], off
	s_mov_b32 m0, s36
	s_nop 0
	global_load_lds_dwordx4 v[216:217], off
	s_waitcnt vmcnt(8)
	s_waitcnt lgkmcnt(0)
	s_barrier
; #define PG8_STAGE(bufoff, gbase, voff) do { _Pragma("unroll") for (int _i = 0; _i < 2; ++_i) \
;         __builtin_amdgcn_global_load_lds((const unsigned*)((const char*)(gbase) + (voff)[_i]), (PG8_LAS unsigned*)(lds + (bufoff) + ldsw + _i * 8192), 16, 0, 0); } while (0)
; #define PG8_LDA(dst, b, h) do { _Pragma("unroll") for (int m = 0; m < 4; ++m) _Pragma("unroll") for (int k = 0; k < 2; ++k) dst[m][k] = *(const PG8_LAS bf16x8*)(lds + PG8_SA(b, h) + aoff + m * 2048 + k * 1024); } while (0)
; #define PG8_LDB(dst, b, h) do { _Pragma("unroll") for (int n = 0; n < 2; ++n) _Pragma("unroll") for (int k = 0; k < 2; ++k) dst[n][k] = *(const PG8_LAS bf16x8*)(lds + PG8_SB(b, h) + boff + n * 2048 + k * 1024); } while (0)
; #define PG8_MMA(ai, bj, At, Bt) do { __builtin_amdgcn_s_setprio(1); _Pragma("unroll") for (int m = 0; m < 4; ++m) _Pragma("unroll") for (int n = 0; n < 2; ++n) _Pragma("unroll") for (int k = 0; k < 2; ++k) \
;         acc[ai][bj][m][n] = __builtin_amdgcn_mfma_f32_16x16x32_bf16(Bt[n][k], At[m][k], acc[ai][bj][m][n], 0, 0, 0); __builtin_amdgcn_s_setprio(0); } while (0)
; #define PG8_WAIT_V(n) asm volatile("s_waitcnt vmcnt(" #n ")" ::: "memory")
; #define PG8_WAIT_L(n) asm volatile("s_waitcnt lgkmcnt(" #n ")" ::: "memory")
; #define PG8_BAR __builtin_amdgcn_s_barrier()
; #define PG8_SCHED __builtin_amdgcn_sched_barrier(0)
; template <class Epi, class Sched, bool ALIGN_EPI = false, bool SP2 = false>
; __device__ __forceinline__ void gemm_phase(PG8_LAS unsigned char* lds, const Gemm g, const Sched& S, const Epi& E, int wave_s) {
;     ...
;             PG8_WAIT_V(8); PG8_WAIT_L(0); PG8_BAR; PG8_MMA(1, 0, At, B0); PG8_MMA(1, 1, At, B1); PG8_BAR; PG8_SCHED;
;             PG8_LDB(B0, 1, 0); PG8_LDB(B1, 1, 1); PG8_SCHED; PG8_LDA(At, 1, 0); PG8_STAGE(PG8_SA(0, 1), a2 + hstepA, voffA);
;             PG8_WAIT_V(8); PG8_WAIT_L(0); PG8_BAR; PG8_MMA(0, 0, At, B0); PG8_MMA(0, 1, At, B1); PG8_BAR; PG8_SCHED;
	v_mfma_f32_16x16x32_bf16 v[62:65], v[142:145], v[178:181], 0
	v_mfma_f32_16x16x32_bf16 v[58:61], v[154:157], v[178:181], 0
	v_mfma_f32_16x16x32_bf16 v[46:49], v[142:145], v[186:189], 0
	v_mfma_f32_16x16x32_bf16 v[42:45], v[154:157], v[186:189], 0
	v_mfma_f32_16x16x32_bf16 v[30:33], v[142:145], v[194:197], 0
	v_mfma_f32_16x16x32_bf16 v[26:29], v[154:157], v[194:197], 0
	v_mfma_f32_16x16x32_bf16 v[14:17], v[142:145], v[202:205], 0
	v_mfma_f32_16x16x32_bf16 v[10:13], v[154:157], v[202:205], 0
	v_mfma_f32_16x16x32_bf16 v[62:65], v[150:153], v[182:185], v[62:65]
	v_mfma_f32_16x16x32_bf16 v[58:61], v[158:161], v[182:185], v[58:61]
	v_mfma_f32_16x16x32_bf16 v[46:49], v[150:153], v[190:193], v[46:49]
	v_mfma_f32_16x16x32_bf16 v[42:45], v[158:161], v[190:193], v[42:45]
	v_mfma_f32_16x16x32_bf16 v[30:33], v[150:153], v[198:201], v[30:33]
	v_mfma_f32_16x16x32_bf16 v[26:29], v[158:161], v[198:201], v[26:29]
	v_mfma_f32_16x16x32_bf16 v[14:17], v[150:153], v[206:209], v[14:17]
	v_mfma_f32_16x16x32_bf16 v[10:13], v[158:161], v[206:209], v[10:13]
	v_mfma_f32_16x16x32_bf16 v[54:57], v[162:165], v[178:181], 0
	v_mfma_f32_16x16x32_bf16 v[50:53], v[170:173], v[178:181], 0
	v_mfma_f32_16x16x32_bf16 v[38:41], v[162:165], v[186:189], 0
	v_mfma_f32_16x16x32_bf16 v[34:37], v[170:173], v[186:189], 0
	v_mfma_f32_16x16x32_bf16 v[22:25], v[162:165], v[194:197], 0
	v_mfma_f32_16x16x32_bf16 v[18:21], v[170:173], v[194:197], 0
	v_mfma_f32_16x16x32_bf16 v[6:9], v[162:165], v[202:205], 0
	v_mfma_f32_16x16x32_bf16 v[2:5], v[170:173], v[202:205], 0
	v_mfma_f32_16x16x32_bf16 v[54:57], v[166:169], v[182:185], v[54:57]
	v_mfma_f32_16x16x32_bf16 v[50:53], v[174:177], v[182:185], v[50:53]
	v_mfma_f32_16x16x32_bf16 v[38:41], v[166:169], v[190:193], v[38:41]
	v_mfma_f32_16x16x32_bf16 v[34:37], v[174:177], v[190:193], v[34:37]
	v_mfma_f32_16x16x32_bf16 v[22:25], v[166:169], v[198:201], v[22:25]
	v_mfma_f32_16x16x32_bf16 v[18:21], v[174:177], v[198:201], v[18:21]
	v_mfma_f32_16x16x32_bf16 v[6:9], v[166:169], v[206:209], v[6:9]
	v_mfma_f32_16x16x32_bf16 v[2:5], v[174:177], v[206:209], v[2:5]
	s_barrier
	s_add_i32 s95, 0, 0x18000
	v_add_u32_e32 v149, s95, v147
	s_add_i32 s96, 0, 0x1c000
	ds_read_b128 v[142:145], v149
	ds_read_b128 v[150:153], v149 offset:1024
	ds_read_b128 v[154:157], v149 offset:2048
	ds_read_b128 v[158:161], v149 offset:3072
	v_add_u32_e32 v149, s96, v147
	ds_read_b128 v[162:165], v149
	ds_read_b128 v[166:169], v149 offset:1024
	ds_read_b128 v[170:173], v149 offset:2048
	ds_read_b128 v[174:177], v149 offset:3072
	s_add_u32 s40, s40, 0x80000
	s_addc_u32 s41, s41, 0
	s_mov_b32 m0, s37
	v_lshl_add_u64 v[218:219], s[40:41], 0, v[130:131]
	ds_read_b128 v[178:181], v148 offset:32768
	ds_read_b128 v[182:185], v148 offset:33792
	ds_read_b128 v[186:189], v148 offset:34816
	ds_read_b128 v[190:193], v148 offset:35840
	ds_read_b128 v[194:197], v148 offset:36864
	ds_read_b128 v[198:201], v148 offset:37888
	ds_read_b128 v[202:205], v148 offset:38912
	ds_read_b128 v[206:209], v148 offset:39936
	global_load_lds_dwordx4 v[218:219], off
	v_lshl_add_u64 v[218:219], s[40:41], 0, v[134:135]
	s_mov_b32 m0, s42
	s_nop 0
	global_load_lds_dwordx4 v[218:219], off
	s_waitcnt vmcnt(8)
	s_waitcnt lgkmcnt(0)
	s_barrier
	v_mfma_f32_16x16x32_bf16 v[126:129], v[142:145], v[178:181], v[126:129]
	v_mfma_f32_16x16x32_bf16 v[122:125], v[154:157], v[178:181], v[122:125]
	v_mfma_f32_16x16x32_bf16 v[110:113], v[142:145], v[186:189], v[110:113]
	v_mfma_f32_16x16x32_bf16 v[106:109], v[154:157], v[186:189], v[106:109]
	v_mfma_f32_16x16x32_bf16 v[94:97], v[142:145], v[194:197], v[94:97]
	v_mfma_f32_16x16x32_bf16 v[90:93], v[154:157], v[194:197], v[90:93]
	v_mfma_f32_16x16x32_bf16 v[78:81], v[142:145], v[202:205], v[78:81]
	v_mfma_f32_16x16x32_bf16 v[74:77], v[154:157], v[202:205], v[74:77]
	v_mfma_f32_16x16x32_bf16 v[126:129], v[150:153], v[182:185], v[126:129]
	v_mfma_f32_16x16x32_bf16 v[122:125], v[158:161], v[182:185], v[122:125]
	v_mfma_f32_16x16x32_bf16 v[110:113], v[150:153], v[190:193], v[110:113]
	v_mfma_f32_16x16x32_bf16 v[106:109], v[158:161], v[190:193], v[106:109]
	v_mfma_f32_16x16x32_bf16 v[94:97], v[150:153], v[198:201], v[94:97]
	v_mfma_f32_16x16x32_bf16 v[90:93], v[158:161], v[198:201], v[90:93]
	v_mfma_f32_16x16x32_bf16 v[78:81], v[150:153], v[206:209], v[78:81]
	v_mfma_f32_16x16x32_bf16 v[74:77], v[158:161], v[206:209], v[74:77]
	v_mfma_f32_16x16x32_bf16 v[118:121], v[162:165], v[178:181], v[118:121]
	v_mfma_f32_16x16x32_bf16 v[114:117], v[170:173], v[178:181], v[114:117]
	v_mfma_f32_16x16x32_bf16 v[102:105], v[162:165], v[186:189], v[102:105]
	v_mfma_f32_16x16x32_bf16 v[98:101], v[170:173], v[186:189], v[98:101]
	v_mfma_f32_16x16x32_bf16 v[86:89], v[162:165], v[194:197], v[86:89]
	v_mfma_f32_16x16x32_bf16 v[82:85], v[170:173], v[194:197], v[82:85]
	v_mfma_f32_16x16x32_bf16 v[70:73], v[162:165], v[202:205], v[70:73]
	v_mfma_f32_16x16x32_bf16 v[66:69], v[170:173], v[202:205], v[66:69]
	v_mfma_f32_16x16x32_bf16 v[118:121], v[166:169], v[182:185], v[118:121]
	v_mfma_f32_16x16x32_bf16 v[114:117], v[174:177], v[182:185], v[114:117]
	v_mfma_f32_16x16x32_bf16 v[102:105], v[166:169], v[190:193], v[102:105]
	v_mfma_f32_16x16x32_bf16 v[98:101], v[174:177], v[190:193], v[98:101]
	v_mfma_f32_16x16x32_bf16 v[86:89], v[166:169], v[198:201], v[86:89]
	v_mfma_f32_16x16x32_bf16 v[82:85], v[174:177], v[198:201], v[82:85]
	v_mfma_f32_16x16x32_bf16 v[70:73], v[166:169], v[206:209], v[70:73]
	v_mfma_f32_16x16x32_bf16 v[66:69], v[174:177], v[206:209], v[66:69]
	s_barrier
; #define PG8_STAGE(bufoff, gbase, voff) do { _Pragma("unroll") for (int _i = 0; _i < 2; ++_i) \
;         __builtin_amdgcn_global_load_lds((const unsigned*)((const char*)(gbase) + (voff)[_i]), (PG8_LAS unsigned*)(lds + (bufoff) + ldsw + _i * 8192), 16, 0, 0); } while (0)
; #define PG8_LDA(dst, b, h) do { _Pragma("unroll") for (int m = 0; m < 4; ++m) _Pragma("unroll") for (int k = 0; k < 2; ++k) dst[m][k] = *(const PG8_LAS bf16x8*)(lds + PG8_SA(b, h) + aoff + m * 2048 + k * 1024); } while (0)
; #define PG8_LDB(dst, b, h) do { _Pragma("unroll") for (int n = 0; n < 2; ++n) _Pragma("unroll") for (int k = 0; k < 2; ++k) dst[n][k] = *(const PG8_LAS bf16x8*)(lds + PG8_SB(b, h) + boff + n * 2048 + k * 1024); } while (0)
; #define PG8_MMA(ai, bj, At, Bt) do { __builtin_amdgcn_s_setprio(1); _Pragma("unroll") for (int m = 0; m < 4; ++m) _Pragma("unroll") for (int n = 0; n < 2; ++n) _Pragma("unroll") for (int k = 0; k < 2; ++k) \
;         acc[ai][bj][m][n] = __builtin_amdgcn_mfma_f32_16x16x32_bf16(Bt[n][k], At[m][k], acc[ai][bj][m][n], 0, 0, 0); __builtin_amdgcn_s_setprio(0); } while (0)
; #define PG8_WAIT_V(n) asm volatile("s_waitcnt vmcnt(" #n ")" ::: "memory")
; #define PG8_WAIT_L(n) asm volatile("s_waitcnt lgkmcnt(" #n ")" ::: "memory")
; #define PG8_BAR __builtin_amdgcn_s_barrier()
; #define PG8_SCHED __builtin_amdgcn_sched_barrier(0)
; template <class Epi, class Sched, bool ALIGN_EPI = false, bool SP2 = false>
; __device__ __forceinline__ void gemm_phase(PG8_LAS unsigned char* lds, const Gemm g, const Sched& S, const Epi& E, int wave_s) {
;     ...
;             PG8_LDB(B0, 0, 0); PG8_LDB(B1, 0, 1); PG8_SCHED; PG8_LDA(At, 0, 0); PG8_STAGE(PG8_SA(1, 1), a1 + hstepA, voffA);
;     ...
;             PG8_LDA(At, 1, 1); PG8_STAGE(PG8_SB(1, 0), b3, voffB); PG8_STAGE(PG8_SB(1, 1), b3 + hstepB, voffB); PG8_STAGE(PG8_SA(1, 0), a3, voffA);
;             PG8_WAIT_V(8); PG8_WAIT_L(0); PG8_BAR; PG8_MMA(1, 0, At, B0); PG8_MMA(1, 1, At, B1); PG8_BAR; PG8_SCHED;
	s_add_i32 s40, s95, s34
	v_lshl_add_u64 v[210:211], v[210:211], 0, s[60:61]
	s_mov_b32 m0, s40
	ds_read_b128 v[178:181], v148 offset:49152
	ds_read_b128 v[182:185], v148 offset:50176
	ds_read_b128 v[186:189], v148 offset:51200
	ds_read_b128 v[190:193], v148 offset:52224
	ds_read_b128 v[194:197], v148 offset:53248
	ds_read_b128 v[198:201], v148 offset:54272
	ds_read_b128 v[202:205], v148 offset:55296
	ds_read_b128 v[206:209], v148 offset:56320
	global_load_lds_dwordx4 v[210:211], off
	s_add_i32 m0, s40, 0x2000
	s_add_u32 s30, s30, 0x80080
	v_lshl_add_u64 v[210:211], v[212:213], 0, s[60:61]
	s_addc_u32 s31, s31, 0
	s_add_i32 s40, s96, s34
	global_load_lds_dwordx4 v[210:211], off
	v_lshl_add_u64 v[210:211], s[30:31], 0, v[132:133]
	s_mov_b32 m0, s40
	s_nop 0
	global_load_lds_dwordx4 v[210:211], off
	v_lshl_add_u64 v[210:211], s[30:31], 0, v[136:137]
	s_add_i32 m0, s40, 0x2000
	s_nop 0
	global_load_lds_dwordx4 v[210:211], off
	v_lshl_add_u64 v[210:211], v[214:215], 0, s[60:61]
	s_mov_b32 m0, s45
	s_nop 0
	global_load_lds_dwordx4 v[210:211], off
	v_lshl_add_u64 v[210:211], v[216:217], 0, s[60:61]
	s_mov_b32 m0, s46
	s_nop 0
	global_load_lds_dwordx4 v[210:211], off
	s_waitcnt vmcnt(8)
	s_waitcnt lgkmcnt(0)
	s_barrier
	v_mfma_f32_16x16x32_bf16 v[62:65], v[142:145], v[178:181], v[62:65]
	v_mfma_f32_16x16x32_bf16 v[58:61], v[154:157], v[178:181], v[58:61]
	v_mfma_f32_16x16x32_bf16 v[46:49], v[142:145], v[186:189], v[46:49]
	v_mfma_f32_16x16x32_bf16 v[42:45], v[154:157], v[186:189], v[42:45]
	v_mfma_f32_16x16x32_bf16 v[30:33], v[142:145], v[194:197], v[30:33]
	v_mfma_f32_16x16x32_bf16 v[26:29], v[154:157], v[194:197], v[26:29]
	v_mfma_f32_16x16x32_bf16 v[14:17], v[142:145], v[202:205], v[14:17]
	v_mfma_f32_16x16x32_bf16 v[10:13], v[154:157], v[202:205], v[10:13]
	v_mfma_f32_16x16x32_bf16 v[62:65], v[150:153], v[182:185], v[62:65]
	v_mfma_f32_16x16x32_bf16 v[58:61], v[158:161], v[182:185], v[58:61]
	v_mfma_f32_16x16x32_bf16 v[46:49], v[150:153], v[190:193], v[46:49]
	v_mfma_f32_16x16x32_bf16 v[42:45], v[158:161], v[190:193], v[42:45]
	v_mfma_f32_16x16x32_bf16 v[30:33], v[150:153], v[198:201], v[30:33]
	v_mfma_f32_16x16x32_bf16 v[26:29], v[158:161], v[198:201], v[26:29]
	v_mfma_f32_16x16x32_bf16 v[14:17], v[150:153], v[206:209], v[14:17]
	v_mfma_f32_16x16x32_bf16 v[10:13], v[158:161], v[206:209], v[10:13]
	v_mfma_f32_16x16x32_bf16 v[54:57], v[162:165], v[178:181], v[54:57]
	v_mfma_f32_16x16x32_bf16 v[50:53], v[170:173], v[178:181], v[50:53]
	v_mfma_f32_16x16x32_bf16 v[38:41], v[162:165], v[186:189], v[38:41]
	v_mfma_f32_16x16x32_bf16 v[34:37], v[170:173], v[186:189], v[34:37]
	v_mfma_f32_16x16x32_bf16 v[22:25], v[162:165], v[194:197], v[22:25]
	v_mfma_f32_16x16x32_bf16 v[18:21], v[170:173], v[194:197], v[18:21]
	v_mfma_f32_16x16x32_bf16 v[6:9], v[162:165], v[202:205], v[6:9]
	v_mfma_f32_16x16x32_bf16 v[2:5], v[170:173], v[202:205], v[2:5]
	v_mfma_f32_16x16x32_bf16 v[54:57], v[166:169], v[182:185], v[54:57]
	v_mfma_f32_16x16x32_bf16 v[50:53], v[174:177], v[182:185], v[50:53]
	v_mfma_f32_16x16x32_bf16 v[38:41], v[166:169], v[190:193], v[38:41]
	v_mfma_f32_16x16x32_bf16 v[34:37], v[174:177], v[190:193], v[34:37]
	v_mfma_f32_16x16x32_bf16 v[22:25], v[166:169], v[198:201], v[22:25]
	v_mfma_f32_16x16x32_bf16 v[18:21], v[174:177], v[198:201], v[18:21]
	v_mfma_f32_16x16x32_bf16 v[6:9], v[166:169], v[206:209], v[6:9]
	v_mfma_f32_16x16x32_bf16 v[2:5], v[174:177], v[206:209], v[2:5]
	s_barrier
	s_add_i32 s94, s94, 2
	s_add_u32 s4, s4, 0x100
	s_addc_u32 s5, s5, 0
	s_add_u32 s15, s15, 0x100
	s_addc_u32 s21, s21, 0
	s_cmp_gt_u32 s94, 29
.LBB0_412:
	s_add_u32 s30, s4, 0xfff80080
	s_addc_u32 s31, s5, -1
	s_add_i32 s95, 0, 0x10000
	s_cmp_eq_u32 s94, 28
	s_cselect_b32 s41, s27, s31
	s_cselect_b32 s40, s26, s30
	v_add_u32_e32 v149, s95, v147
	s_cselect_b32 s31, s2, s21
	s_cselect_b32 s30, s3, s15
	s_add_i32 vcc_lo, 0, 0x14000
	ds_read_b128 v[142:145], v149
	ds_read_b128 v[150:153], v149 offset:1024
	ds_read_b128 v[154:157], v149 offset:2048
	ds_read_b128 v[158:161], v149 offset:3072
	v_add_u32_e32 v149, vcc_lo, v147
	ds_read_b128 v[162:165], v149
	ds_read_b128 v[166:169], v149 offset:1024
	ds_read_b128 v[170:173], v149 offset:2048
	ds_read_b128 v[174:177], v149 offset:3072
	v_lshl_add_u64 v[210:211], s[4:5], 0, v[138:139]
	s_add_i32 m0, s35, 0xc000
	ds_read_b128 v[178:181], v148
	ds_read_b128 v[182:185], v148 offset:1024
	ds_read_b128 v[186:189], v148 offset:2048
	ds_read_b128 v[190:193], v148 offset:3072
	ds_read_b128 v[194:197], v148 offset:4096
	ds_read_b128 v[198:201], v148 offset:5120
	ds_read_b128 v[202:205], v148 offset:6144
	ds_read_b128 v[206:209], v148 offset:7168
	global_load_lds_dwordx4 v[210:211], off
	v_lshl_add_u64 v[210:211], s[4:5], 0, v[140:141]
	s_add_i32 m0, s35, 0xe000
	s_nop 0
	global_load_lds_dwordx4 v[210:211], off
	s_waitcnt vmcnt(8)
	s_waitcnt lgkmcnt(0)
	s_barrier
; #define PG8_STAGE(bufoff, gbase, voff) do { _Pragma("unroll") for (int _i = 0; _i < 2; ++_i) \
;         __builtin_amdgcn_global_load_lds((const unsigned*)((const char*)(gbase) + (voff)[_i]), (PG8_LAS unsigned*)(lds + (bufoff) + ldsw + _i * 8192), 16, 0, 0); } while (0)
; #define PG8_LDA(dst, b, h) do { _Pragma("unroll") for (int m = 0; m < 4; ++m) _Pragma("unroll") for (int k = 0; k < 2; ++k) dst[m][k] = *(const PG8_LAS bf16x8*)(lds + PG8_SA(b, h) + aoff + m * 2048 + k * 1024); } while (0)
; #define PG8_MMA(ai, bj, At, Bt) do { __builtin_amdgcn_s_setprio(1); _Pragma("unroll") for (int m = 0; m < 4; ++m) _Pragma("unroll") for (int n = 0; n < 2; ++n) _Pragma("unroll") for (int k = 0; k < 2; ++k) \
;         acc[ai][bj][m][n] = __builtin_amdgcn_mfma_f32_16x16x32_bf16(Bt[n][k], At[m][k], acc[ai][bj][m][n], 0, 0, 0); __builtin_amdgcn_s_setprio(0); } while (0)
; #define PG8_WAIT_V(n) asm volatile("s_waitcnt vmcnt(" #n ")" ::: "memory")
; #define PG8_WAIT_L(n) asm volatile("s_waitcnt lgkmcnt(" #n ")" ::: "memory")
; #define PG8_BAR __builtin_amdgcn_s_barrier()
; #define PG8_SCHED __builtin_amdgcn_sched_barrier(0)
; template <class Epi, class Sched, bool ALIGN_EPI = false, bool SP2 = false>
; __device__ __forceinline__ void gemm_phase(PG8_LAS unsigned char* lds, const Gemm g, const Sched& S, const Epi& E, int wave_s) {
;     ...
;             PG8_WAIT_V(8); PG8_WAIT_L(0); PG8_BAR; PG8_MMA(0, 0, At, B0); PG8_MMA(0, 1, At, B1); PG8_BAR; PG8_SCHED;
;             PG8_LDA(At, 0, 1); PG8_STAGE(PG8_SB(0, 0), b2, voffB); PG8_STAGE(PG8_SB(0, 1), b2 + hstepB, voffB); PG8_STAGE(PG8_SA(0, 0), a2, voffA);
;             PG8_WAIT_V(8); PG8_WAIT_L(0); PG8_BAR; PG8_MMA(1, 0, At, B0); PG8_MMA(1, 1, At, B1); PG8_BAR; PG8_SCHED;
	v_mfma_f32_16x16x32_bf16 v[126:129], v[142:145], v[178:181], v[126:129]
	v_mfma_f32_16x16x32_bf16 v[122:125], v[154:157], v[178:181], v[122:125]
	v_mfma_f32_16x16x32_bf16 v[110:113], v[142:145], v[186:189], v[110:113]
	v_mfma_f32_16x16x32_bf16 v[106:109], v[154:157], v[186:189], v[106:109]
	v_mfma_f32_16x16x32_bf16 v[94:97], v[142:145], v[194:197], v[94:97]
	v_mfma_f32_16x16x32_bf16 v[90:93], v[154:157], v[194:197], v[90:93]
	v_mfma_f32_16x16x32_bf16 v[78:81], v[142:145], v[202:205], v[78:81]
	v_mfma_f32_16x16x32_bf16 v[74:77], v[154:157], v[202:205], v[74:77]
	v_mfma_f32_16x16x32_bf16 v[126:129], v[150:153], v[182:185], v[126:129]
	v_mfma_f32_16x16x32_bf16 v[122:125], v[158:161], v[182:185], v[122:125]
	v_mfma_f32_16x16x32_bf16 v[110:113], v[150:153], v[190:193], v[110:113]
	v_mfma_f32_16x16x32_bf16 v[106:109], v[158:161], v[190:193], v[106:109]
	v_mfma_f32_16x16x32_bf16 v[94:97], v[150:153], v[198:201], v[94:97]
	v_mfma_f32_16x16x32_bf16 v[90:93], v[158:161], v[198:201], v[90:93]
	v_mfma_f32_16x16x32_bf16 v[78:81], v[150:153], v[206:209], v[78:81]
	v_mfma_f32_16x16x32_bf16 v[74:77], v[158:161], v[206:209], v[74:77]
	v_mfma_f32_16x16x32_bf16 v[118:121], v[162:165], v[178:181], v[118:121]
	v_mfma_f32_16x16x32_bf16 v[114:117], v[170:173], v[178:181], v[114:117]
	v_mfma_f32_16x16x32_bf16 v[102:105], v[162:165], v[186:189], v[102:105]
	v_mfma_f32_16x16x32_bf16 v[98:101], v[170:173], v[186:189], v[98:101]
	v_mfma_f32_16x16x32_bf16 v[86:89], v[162:165], v[194:197], v[86:89]
	v_mfma_f32_16x16x32_bf16 v[82:85], v[170:173], v[194:197], v[82:85]
	v_mfma_f32_16x16x32_bf16 v[70:73], v[162:165], v[202:205], v[70:73]
	v_mfma_f32_16x16x32_bf16 v[66:69], v[170:173], v[202:205], v[66:69]
	v_mfma_f32_16x16x32_bf16 v[118:121], v[166:169], v[182:185], v[118:121]
	v_mfma_f32_16x16x32_bf16 v[114:117], v[174:177], v[182:185], v[114:117]
	v_mfma_f32_16x16x32_bf16 v[102:105], v[166:169], v[190:193], v[102:105]
	v_mfma_f32_16x16x32_bf16 v[98:101], v[174:177], v[190:193], v[98:101]
	v_mfma_f32_16x16x32_bf16 v[86:89], v[166:169], v[198:201], v[86:89]
	v_mfma_f32_16x16x32_bf16 v[82:85], v[174:177], v[198:201], v[82:85]
	v_mfma_f32_16x16x32_bf16 v[70:73], v[166:169], v[206:209], v[70:73]
	v_mfma_f32_16x16x32_bf16 v[66:69], v[174:177], v[206:209], v[66:69]
	s_barrier
	s_add_i32 s95, s95, s34
	v_lshl_add_u64 v[210:211], s[30:31], 0, v[132:133]
	s_mov_b32 m0, s95
	ds_read_b128 v[178:181], v148 offset:16384
	ds_read_b128 v[182:185], v148 offset:17408
	ds_read_b128 v[186:189], v148 offset:18432
	ds_read_b128 v[190:193], v148 offset:19456
	ds_read_b128 v[194:197], v148 offset:20480
	ds_read_b128 v[198:201], v148 offset:21504
	ds_read_b128 v[202:205], v148 offset:22528
	ds_read_b128 v[206:209], v148 offset:23552
	global_load_lds_dwordx4 v[210:211], off
	s_add_i32 m0, s95, 0x2000
	s_add_u32 s96, s30, 0x80000
	v_lshl_add_u64 v[212:213], s[30:31], 0, v[136:137]
	s_addc_u32 s97, s31, 0
	s_add_i32 s95, vcc_lo, s34
	global_load_lds_dwordx4 v[212:213], off
	v_lshl_add_u64 v[214:215], s[96:97], 0, v[132:133]
	s_mov_b32 m0, s95
	v_lshl_add_u64 v[216:217], s[40:41], 0, v[134:135]
	global_load_lds_dwordx4 v[214:215], off
	v_lshl_add_u64 v[214:215], s[96:97], 0, v[136:137]
	s_add_i32 m0, s95, 0x2000
	s_nop 0
	global_load_lds_dwordx4 v[214:215], off
	v_lshl_add_u64 v[214:215], s[40:41], 0, v[130:131]
	s_mov_b32 m0, s35
	s_nop 0
	global_load_lds_dwordx4 v[214:215], off
	s_mov_b32 m0, s36
	s_nop 0
	global_load_lds_dwordx4 v[216:217], off
	s_waitcnt vmcnt(8)
	s_waitcnt lgkmcnt(0)
	s_barrier
	v_mfma_f32_16x16x32_bf16 v[62:65], v[142:145], v[178:181], v[62:65]
	v_mfma_f32_16x16x32_bf16 v[58:61], v[154:157], v[178:181], v[58:61]
	v_mfma_f32_16x16x32_bf16 v[46:49], v[142:145], v[186:189], v[46:49]
	v_mfma_f32_16x16x32_bf16 v[42:45], v[154:157], v[186:189], v[42:45]
	v_mfma_f32_16x16x32_bf16 v[30:33], v[142:145], v[194:197], v[30:33]
	v_mfma_f32_16x16x32_bf16 v[26:29], v[154:157], v[194:197], v[26:29]
	v_mfma_f32_16x16x32_bf16 v[14:17], v[142:145], v[202:205], v[14:17]
	v_mfma_f32_16x16x32_bf16 v[10:13], v[154:157], v[202:205], v[10:13]
	v_mfma_f32_16x16x32_bf16 v[62:65], v[150:153], v[182:185], v[62:65]
	v_mfma_f32_16x16x32_bf16 v[58:61], v[158:161], v[182:185], v[58:61]
	v_mfma_f32_16x16x32_bf16 v[46:49], v[150:153], v[190:193], v[46:49]
	v_mfma_f32_16x16x32_bf16 v[42:45], v[158:161], v[190:193], v[42:45]
	v_mfma_f32_16x16x32_bf16 v[30:33], v[150:153], v[198:201], v[30:33]
	v_mfma_f32_16x16x32_bf16 v[26:29], v[158:161], v[198:201], v[26:29]
	v_mfma_f32_16x16x32_bf16 v[14:17], v[150:153], v[206:209], v[14:17]
	v_mfma_f32_16x16x32_bf16 v[10:13], v[158:161], v[206:209], v[10:13]
	v_mfma_f32_16x16x32_bf16 v[54:57], v[162:165], v[178:181], v[54:57]
	v_mfma_f32_16x16x32_bf16 v[50:53], v[170:173], v[178:181], v[50:53]
	v_mfma_f32_16x16x32_bf16 v[38:41], v[162:165], v[186:189], v[38:41]
	v_mfma_f32_16x16x32_bf16 v[34:37], v[170:173], v[186:189], v[34:37]
	v_mfma_f32_16x16x32_bf16 v[22:25], v[162:165], v[194:197], v[22:25]
	v_mfma_f32_16x16x32_bf16 v[18:21], v[170:173], v[194:197], v[18:21]
	v_mfma_f32_16x16x32_bf16 v[6:9], v[162:165], v[202:205], v[6:9]
	v_mfma_f32_16x16x32_bf16 v[2:5], v[170:173], v[202:205], v[2:5]
	v_mfma_f32_16x16x32_bf16 v[54:57], v[166:169], v[182:185], v[54:57]
	v_mfma_f32_16x16x32_bf16 v[50:53], v[174:177], v[182:185], v[50:53]
	v_mfma_f32_16x16x32_bf16 v[38:41], v[166:169], v[190:193], v[38:41]
	v_mfma_f32_16x16x32_bf16 v[34:37], v[174:177], v[190:193], v[34:37]
	v_mfma_f32_16x16x32_bf16 v[22:25], v[166:169], v[198:201], v[22:25]
	v_mfma_f32_16x16x32_bf16 v[18:21], v[174:177], v[198:201], v[18:21]
	v_mfma_f32_16x16x32_bf16 v[6:9], v[166:169], v[206:209], v[6:9]
	v_mfma_f32_16x16x32_bf16 v[2:5], v[174:177], v[206:209], v[2:5]
	s_barrier
; #define PG8_STAGE(bufoff, gbase, voff) do { _Pragma("unroll") for (int _i = 0; _i < 2; ++_i) \
;         __builtin_amdgcn_global_load_lds((const unsigned*)((const char*)(gbase) + (voff)[_i]), (PG8_LAS unsigned*)(lds + (bufoff) + ldsw + _i * 8192), 16, 0, 0); } while (0)
; #define PG8_LDA(dst, b, h) do { _Pragma("unroll") for (int m = 0; m < 4; ++m) _Pragma("unroll") for (int k = 0; k < 2; ++k) dst[m][k] = *(const PG8_LAS bf16x8*)(lds + PG8_SA(b, h) + aoff + m * 2048 + k * 1024); } while (0)
; #define PG8_LDB(dst, b, h) do { _Pragma("unroll") for (int n = 0; n < 2; ++n) _Pragma("unroll") for (int k = 0; k < 2; ++k) dst[n][k] = *(const PG8_LAS bf16x8*)(lds + PG8_SB(b, h) + boff + n * 2048 + k * 1024); } while (0)
; #define PG8_MMA(ai, bj, At, Bt) do { __builtin_amdgcn_s_setprio(1); _Pragma("unroll") for (int m = 0; m < 4; ++m) _Pragma("unroll") for (int n = 0; n < 2; ++n) _Pragma("unroll") for (int k = 0; k < 2; ++k) \
;         acc[ai][bj][m][n] = __builtin_amdgcn_mfma_f32_16x16x32_bf16(Bt[n][k], At[m][k], acc[ai][bj][m][n], 0, 0, 0); __builtin_amdgcn_s_setprio(0); } while (0)
; #define PG8_WAIT_V(n) asm volatile("s_waitcnt vmcnt(" #n ")" ::: "memory")
; #define PG8_WAIT_L(n) asm volatile("s_waitcnt lgkmcnt(" #n ")" ::: "memory")
; #define PG8_BAR __builtin_amdgcn_s_barrier()
; #define PG8_SCHED __builtin_amdgcn_sched_barrier(0)
; template <class Epi, class Sched, bool ALIGN_EPI = false, bool SP2 = false>
; __device__ __forceinline__ void gemm_phase(PG8_LAS unsigned char* lds, const Gemm g, const Sched& S, const Epi& E, int wave_s) {
;     ...
;             PG8_LDB(B0, 1, 0); PG8_LDB(B1, 1, 1); PG8_SCHED; PG8_LDA(At, 1, 0); PG8_STAGE(PG8_SA(0, 1), a2 + hstepA, voffA);
;             PG8_WAIT_V(8); PG8_WAIT_L(0); PG8_BAR; PG8_MMA(0, 0, At, B0); PG8_MMA(0, 1, At, B1); PG8_BAR; PG8_SCHED;
	s_add_i32 s95, 0, 0x18000
	v_add_u32_e32 v149, s95, v147
	s_add_i32 s96, 0, 0x1c000
	ds_read_b128 v[142:145], v149
	ds_read_b128 v[150:153], v149 offset:1024
	ds_read_b128 v[154:157], v149 offset:2048
	ds_read_b128 v[158:161], v149 offset:3072
	v_add_u32_e32 v149, s96, v147
	ds_read_b128 v[162:165], v149
	ds_read_b128 v[166:169], v149 offset:1024
	ds_read_b128 v[170:173], v149 offset:2048
	ds_read_b128 v[174:177], v149 offset:3072
	s_add_u32 s40, s40, 0x80000
	s_addc_u32 s41, s41, 0
	s_mov_b32 m0, s37
	v_lshl_add_u64 v[218:219], s[40:41], 0, v[130:131]
	ds_read_b128 v[178:181], v148 offset:32768
	ds_read_b128 v[182:185], v148 offset:33792
	ds_read_b128 v[186:189], v148 offset:34816
	ds_read_b128 v[190:193], v148 offset:35840
	ds_read_b128 v[194:197], v148 offset:36864
	ds_read_b128 v[198:201], v148 offset:37888
	ds_read_b128 v[202:205], v148 offset:38912
	ds_read_b128 v[206:209], v148 offset:39936
	global_load_lds_dwordx4 v[218:219], off
	v_lshl_add_u64 v[218:219], s[40:41], 0, v[134:135]
	s_mov_b32 m0, s42
	s_nop 0
	global_load_lds_dwordx4 v[218:219], off
	s_waitcnt vmcnt(8)
	s_waitcnt lgkmcnt(0)
	s_barrier
	v_mfma_f32_16x16x32_bf16 v[126:129], v[142:145], v[178:181], v[126:129]
	v_mfma_f32_16x16x32_bf16 v[122:125], v[154:157], v[178:181], v[122:125]
	v_mfma_f32_16x16x32_bf16 v[110:113], v[142:145], v[186:189], v[110:113]
	v_mfma_f32_16x16x32_bf16 v[106:109], v[154:157], v[186:189], v[106:109]
	v_mfma_f32_16x16x32_bf16 v[94:97], v[142:145], v[194:197], v[94:97]
	v_mfma_f32_16x16x32_bf16 v[90:93], v[154:157], v[194:197], v[90:93]
	v_mfma_f32_16x16x32_bf16 v[78:81], v[142:145], v[202:205], v[78:81]
	v_mfma_f32_16x16x32_bf16 v[74:77], v[154:157], v[202:205], v[74:77]
	v_mfma_f32_16x16x32_bf16 v[126:129], v[150:153], v[182:185], v[126:129]
	v_mfma_f32_16x16x32_bf16 v[122:125], v[158:161], v[182:185], v[122:125]
	v_mfma_f32_16x16x32_bf16 v[110:113], v[150:153], v[190:193], v[110:113]
	v_mfma_f32_16x16x32_bf16 v[106:109], v[158:161], v[190:193], v[106:109]
	v_mfma_f32_16x16x32_bf16 v[94:97], v[150:153], v[198:201], v[94:97]
	v_mfma_f32_16x16x32_bf16 v[90:93], v[158:161], v[198:201], v[90:93]
	v_mfma_f32_16x16x32_bf16 v[78:81], v[150:153], v[206:209], v[78:81]
	v_mfma_f32_16x16x32_bf16 v[74:77], v[158:161], v[206:209], v[74:77]
	v_mfma_f32_16x16x32_bf16 v[118:121], v[162:165], v[178:181], v[118:121]
	v_mfma_f32_16x16x32_bf16 v[114:117], v[170:173], v[178:181], v[114:117]
	v_mfma_f32_16x16x32_bf16 v[102:105], v[162:165], v[186:189], v[102:105]
	v_mfma_f32_16x16x32_bf16 v[98:101], v[170:173], v[186:189], v[98:101]
	v_mfma_f32_16x16x32_bf16 v[86:89], v[162:165], v[194:197], v[86:89]
	v_mfma_f32_16x16x32_bf16 v[82:85], v[170:173], v[194:197], v[82:85]
	v_mfma_f32_16x16x32_bf16 v[70:73], v[162:165], v[202:205], v[70:73]
	v_mfma_f32_16x16x32_bf16 v[66:69], v[170:173], v[202:205], v[66:69]
	v_mfma_f32_16x16x32_bf16 v[118:121], v[166:169], v[182:185], v[118:121]
	v_mfma_f32_16x16x32_bf16 v[114:117], v[174:177], v[182:185], v[114:117]
	v_mfma_f32_16x16x32_bf16 v[102:105], v[166:169], v[190:193], v[102:105]
	v_mfma_f32_16x16x32_bf16 v[98:101], v[174:177], v[190:193], v[98:101]
	v_mfma_f32_16x16x32_bf16 v[86:89], v[166:169], v[198:201], v[86:89]
	v_mfma_f32_16x16x32_bf16 v[82:85], v[174:177], v[198:201], v[82:85]
	v_mfma_f32_16x16x32_bf16 v[70:73], v[166:169], v[206:209], v[70:73]
	v_mfma_f32_16x16x32_bf16 v[66:69], v[174:177], v[206:209], v[66:69]
	s_barrier
; #define PG8_STAGE(bufoff, gbase, voff) do { _Pragma("unroll") for (int _i = 0; _i < 2; ++_i) \
;         __builtin_amdgcn_global_load_lds((const unsigned*)((const char*)(gbase) + (voff)[_i]), (PG8_LAS unsigned*)(lds + (bufoff) + ldsw + _i * 8192), 16, 0, 0); } while (0)
; #define PG8_LDA(dst, b, h) do { _Pragma("unroll") for (int m = 0; m < 4; ++m) _Pragma("unroll") for (int k = 0; k < 2; ++k) dst[m][k] = *(const PG8_LAS bf16x8*)(lds + PG8_SA(b, h) + aoff + m * 2048 + k * 1024); } while (0)
; #define PG8_MMA(ai, bj, At, Bt) do { __builtin_amdgcn_s_setprio(1); _Pragma("unroll") for (int m = 0; m < 4; ++m) _Pragma("unroll") for (int n = 0; n < 2; ++n) _Pragma("unroll") for (int k = 0; k < 2; ++k) \
;         acc[ai][bj][m][n] = __builtin_amdgcn_mfma_f32_16x16x32_bf16(Bt[n][k], At[m][k], acc[ai][bj][m][n], 0, 0, 0); __builtin_amdgcn_s_setprio(0); } while (0)
; #define PG8_WAIT_V(n) asm volatile("s_waitcnt vmcnt(" #n ")" ::: "memory")
; #define PG8_WAIT_L(n) asm volatile("s_waitcnt lgkmcnt(" #n ")" ::: "memory")
; #define PG8_BAR __builtin_amdgcn_s_barrier()
; #define PG8_SCHED __builtin_amdgcn_sched_barrier(0)
; template <class Epi, class Sched, bool ALIGN_EPI = false, bool SP2 = false>
; __device__ __forceinline__ void gemm_phase(PG8_LAS unsigned char* lds, const Gemm g, const Sched& S, const Epi& E, int wave_s) {
;     ...
;         for (int t = 0; t < nt; t += 2) {
;             const bool last = (t == nt - 2);
;             const char* a1 = cA + (size_t)(t + 1) * kstep;
;             const char* a2 = last ? nA : cA + (size_t)(t + 2) * kstep; const char* b2 = last ? nB : cB + (size_t)(t + 2) * kstep;
;     ...
;             PG8_LDA(At, 1, 1); PG8_STAGE(PG8_SB(1, 0), b3, voffB); PG8_STAGE(PG8_SB(1, 1), b3 + hstepB, voffB); PG8_STAGE(PG8_SA(1, 0), a3, voffA);
;             PG8_WAIT_V(8); PG8_WAIT_L(0); PG8_BAR; PG8_MMA(1, 0, At, B0); PG8_MMA(1, 1, At, B1); PG8_BAR; PG8_SCHED;
	s_add_i32 s40, s95, s34
	v_lshl_add_u64 v[210:211], v[210:211], 0, s[60:61]
	s_mov_b32 m0, s40
	ds_read_b128 v[178:181], v148 offset:49152
	ds_read_b128 v[182:185], v148 offset:50176
	ds_read_b128 v[186:189], v148 offset:51200
	ds_read_b128 v[190:193], v148 offset:52224
	ds_read_b128 v[194:197], v148 offset:53248
	ds_read_b128 v[198:201], v148 offset:54272
	ds_read_b128 v[202:205], v148 offset:55296
	ds_read_b128 v[206:209], v148 offset:56320
	global_load_lds_dwordx4 v[210:211], off
	s_add_i32 m0, s40, 0x2000
	s_add_u32 s30, s30, 0x80080
	v_lshl_add_u64 v[210:211], v[212:213], 0, s[60:61]
	s_addc_u32 s31, s31, 0
	s_add_i32 s40, s96, s34
	global_load_lds_dwordx4 v[210:211], off
	v_lshl_add_u64 v[210:211], s[30:31], 0, v[132:133]
	s_mov_b32 m0, s40
	s_nop 0
	global_load_lds_dwordx4 v[210:211], off
	v_lshl_add_u64 v[210:211], s[30:31], 0, v[136:137]
	s_add_i32 m0, s40, 0x2000
	s_nop 0
	global_load_lds_dwordx4 v[210:211], off
	v_lshl_add_u64 v[210:211], v[214:215], 0, s[60:61]
	s_mov_b32 m0, s45
	s_nop 0
	global_load_lds_dwordx4 v[210:211], off
	v_lshl_add_u64 v[210:211], v[216:217], 0, s[60:61]
	s_mov_b32 m0, s46
	s_nop 0
	global_load_lds_dwordx4 v[210:211], off
	s_waitcnt vmcnt(8)
	s_waitcnt lgkmcnt(0)
	s_barrier
	v_mfma_f32_16x16x32_bf16 v[62:65], v[142:145], v[178:181], v[62:65]
	v_mfma_f32_16x16x32_bf16 v[58:61], v[154:157], v[178:181], v[58:61]
	v_mfma_f32_16x16x32_bf16 v[46:49], v[142:145], v[186:189], v[46:49]
	v_mfma_f32_16x16x32_bf16 v[42:45], v[154:157], v[186:189], v[42:45]
	v_mfma_f32_16x16x32_bf16 v[30:33], v[142:145], v[194:197], v[30:33]
	v_mfma_f32_16x16x32_bf16 v[26:29], v[154:157], v[194:197], v[26:29]
	v_mfma_f32_16x16x32_bf16 v[14:17], v[142:145], v[202:205], v[14:17]
	v_mfma_f32_16x16x32_bf16 v[10:13], v[154:157], v[202:205], v[10:13]
	v_mfma_f32_16x16x32_bf16 v[62:65], v[150:153], v[182:185], v[62:65]
	v_mfma_f32_16x16x32_bf16 v[58:61], v[158:161], v[182:185], v[58:61]
	v_mfma_f32_16x16x32_bf16 v[46:49], v[150:153], v[190:193], v[46:49]
	v_mfma_f32_16x16x32_bf16 v[42:45], v[158:161], v[190:193], v[42:45]
	v_mfma_f32_16x16x32_bf16 v[30:33], v[150:153], v[198:201], v[30:33]
	v_mfma_f32_16x16x32_bf16 v[26:29], v[158:161], v[198:201], v[26:29]
	v_mfma_f32_16x16x32_bf16 v[14:17], v[150:153], v[206:209], v[14:17]
	v_mfma_f32_16x16x32_bf16 v[10:13], v[158:161], v[206:209], v[10:13]
	v_mfma_f32_16x16x32_bf16 v[54:57], v[162:165], v[178:181], v[54:57]
	v_mfma_f32_16x16x32_bf16 v[50:53], v[170:173], v[178:181], v[50:53]
	v_mfma_f32_16x16x32_bf16 v[38:41], v[162:165], v[186:189], v[38:41]
	v_mfma_f32_16x16x32_bf16 v[34:37], v[170:173], v[186:189], v[34:37]
	v_mfma_f32_16x16x32_bf16 v[22:25], v[162:165], v[194:197], v[22:25]
	v_mfma_f32_16x16x32_bf16 v[18:21], v[170:173], v[194:197], v[18:21]
	v_mfma_f32_16x16x32_bf16 v[6:9], v[162:165], v[202:205], v[6:9]
	v_mfma_f32_16x16x32_bf16 v[2:5], v[170:173], v[202:205], v[2:5]
	v_mfma_f32_16x16x32_bf16 v[54:57], v[166:169], v[182:185], v[54:57]
	v_mfma_f32_16x16x32_bf16 v[50:53], v[174:177], v[182:185], v[50:53]
	v_mfma_f32_16x16x32_bf16 v[38:41], v[166:169], v[190:193], v[38:41]
	v_mfma_f32_16x16x32_bf16 v[34:37], v[174:177], v[190:193], v[34:37]
	v_mfma_f32_16x16x32_bf16 v[22:25], v[166:169], v[198:201], v[22:25]
	v_mfma_f32_16x16x32_bf16 v[18:21], v[174:177], v[198:201], v[18:21]
	v_mfma_f32_16x16x32_bf16 v[6:9], v[166:169], v[206:209], v[6:9]
	v_mfma_f32_16x16x32_bf16 v[2:5], v[174:177], v[206:209], v[2:5]
	s_barrier
	s_add_i32 s94, s94, 2
	s_add_u32 s4, s4, 0x100
	s_addc_u32 s5, s5, 0
	s_add_u32 s15, s15, 0x100
	s_addc_u32 s21, s21, 0
	s_cmp_gt_u32 s94, 29
	s_cbranch_scc0 .LBB0_412
	s_and_b64 vcc, exec, s[12:13]
	s_cbranch_vccz .LBB0_415
	s_barrier

; #define PG8_STAGE(bufoff, gbase, voff) do { _Pragma("unroll") for (int _i = 0; _i < 2; ++_i) \
;         __builtin_amdgcn_global_load_lds((const unsigned*)((const char*)(gbase) + (voff)[_i]), (PG8_LAS unsigned*)(lds + (bufoff) + ldsw + _i * 8192), 16, 0, 0); } while (0)
; #define PG8_LDA(dst, b, h) do { _Pragma("unroll") for (int m = 0; m < 4; ++m) _Pragma("unroll") for (int k = 0; k < 2; ++k) dst[m][k] = *(const PG8_LAS bf16x8*)(lds + PG8_SA(b, h) + aoff + m * 2048 + k * 1024); } while (0)
; #define PG8_LDB(dst, b, h) do { _Pragma("unroll") for (int n = 0; n < 2; ++n) _Pragma("unroll") for (int k = 0; k < 2; ++k) dst[n][k] = *(const PG8_LAS bf16x8*)(lds + PG8_SB(b, h) + boff + n * 2048 + k * 1024); } while (0)
; #define PG8_WAIT_V(n) asm volatile("s_waitcnt vmcnt(" #n ")" ::: "memory")
; #define PG8_WAIT_L(n) asm volatile("s_waitcnt lgkmcnt(" #n ")" ::: "memory")
; #define PG8_BAR __builtin_amdgcn_s_barrier()
; template <class Epi, class Sched, bool ALIGN_EPI = false, bool SP2 = false>
; __device__ __forceinline__ void gemm_phase(PG8_LAS unsigned char* lds, const Gemm g, const Sched& S, const Epi& E, int wave_s) {
;     ...
;         const bool has_next = S.next(ui + 1, nxt);
;         const char* nA = has_next ? (const char*)g.A + (size_t)nxt.pm * tstepA + (size_t)(nxt.pn / g.npg) * (size_t)(K * 2) : cA; const char* nB = has_next ? (const char*)g.Bt + (size_t)nxt.pn * tstepB : cB;
;         for (int t = 0; t < nt; t += 2) {
;             const bool last = (t == nt - 2);
;             const char* a1 = cA + (size_t)(t + 1) * kstep;
;             const char* a2 = last ? nA : cA + (size_t)(t + 2) * kstep; const char* b2 = last ? nB : cB + (size_t)(t + 2) * kstep;
;             const char* a3 = a2 + kstep; const char* b3 = b2 + kstep;
;             if (last && has_next) S.a_ready(nxt);
;             if constexpr (SP2) {
;             PG8_LDB(B0, 0, 0); PG8_LDB(B1, 0, 1); PG8_SCHED; PG8_LDA(At, 0, 0); PG8_STAGE(PG8_SA(1, 1), a1 + hstepA, voffA);
;             PG8_WAIT_V(8); PG8_WAIT_L(0); PG8_BAR; PG8_MMA(0, 0, At, B0); PG8_MMA(0, 1, At, B1); PG8_BAR; PG8_SCHED;
;             PG8_LDA(At, 0, 1); PG8_STAGE(PG8_SB(0, 0), b2, voffB); PG8_STAGE(PG8_SB(0, 1), b2 + hstepB, voffB); PG8_STAGE(PG8_SA(0, 0), a2, voffA);
;             PG8_WAIT_V(8); PG8_WAIT_L(0); PG8_BAR; PG8_MMA(1, 0, At, B0); PG8_MMA(1, 1, At, B1); PG8_BAR; PG8_SCHED;
.LBB0_601:
	s_ashr_i32 s21, s20, 31
	s_lshl_b64 s[2:3], s[20:21], 20
	s_add_u32 s88, s22, s2
	s_addc_u32 s89, s23, s3
	s_and_b64 s[2:3], s[4:5], exec
	s_cselect_b32 s2, s89, s31
	s_cselect_b32 s3, s88, s30
	s_add_u32 s4, s40, 0x80080
	s_addc_u32 s5, s41, 0
	s_add_u32 s21, s30, 0x100
	s_addc_u32 s27, s31, 0
	s_mov_b32 s81, -2
	s_add_u32 s30, s4, 0xfff80080
	s_addc_u32 s31, s5, -1
	s_add_i32 s84, 0, 0x10000
	s_cmp_eq_u32 s81, 28
	s_cselect_b32 s41, s29, s31
	s_cselect_b32 s40, s28, s30
	s_cselect_b32 s31, s2, s27
	s_cselect_b32 s30, s3, s21
	s_add_i32 s90, 0, 0x14000
	v_add_u32_e32 v134, s84, v207
	v_add_u32_e32 v158, s90, v207
	ds_read_b128 v[118:121], v134
	ds_read_b128 v[126:129], v134 offset:1024
	ds_read_b128 v[130:133], v134 offset:2048
	ds_read_b128 v[134:137], v134 offset:3072
	ds_read_b128 v[138:141], v158
	ds_read_b128 v[142:145], v158 offset:1024
	ds_read_b128 v[154:157], v158 offset:2048
	ds_read_b128 v[158:161], v158 offset:3072
	v_lshl_add_u64 v[210:211], s[4:5], 0, v[198:199]
	s_add_i32 m0, s35, 0xc000
	ds_read_b128 v[162:165], v208
	ds_read_b128 v[166:169], v208 offset:1024
	ds_read_b128 v[170:173], v208 offset:2048
	ds_read_b128 v[174:177], v208 offset:3072
	ds_read_b128 v[178:181], v208 offset:4096
	ds_read_b128 v[182:185], v208 offset:5120
	ds_read_b128 v[186:189], v208 offset:6144
	ds_read_b128 v[202:205], v208 offset:7168
	global_load_lds_dwordx4 v[210:211], off
	v_lshl_add_u64 v[210:211], s[4:5], 0, v[200:201]
	s_add_i32 m0, s35, 0xe000
	s_nop 0
	global_load_lds_dwordx4 v[210:211], off
	s_waitcnt vmcnt(8)
	s_waitcnt lgkmcnt(0)
	s_barrier
	v_mfma_f32_16x16x32_bf16 v[150:153], v[118:121], v[162:165], 0
	v_mfma_f32_16x16x32_bf16 v[146:149], v[130:133], v[162:165], 0
	v_mfma_f32_16x16x32_bf16 v[110:113], v[118:121], v[170:173], 0
	v_mfma_f32_16x16x32_bf16 v[106:109], v[130:133], v[170:173], 0
	v_mfma_f32_16x16x32_bf16 v[94:97], v[118:121], v[178:181], 0
	v_mfma_f32_16x16x32_bf16 v[90:93], v[130:133], v[178:181], 0
	v_mfma_f32_16x16x32_bf16 v[78:81], v[118:121], v[186:189], 0
	v_mfma_f32_16x16x32_bf16 v[74:77], v[130:133], v[186:189], 0
	v_mfma_f32_16x16x32_bf16 v[150:153], v[126:129], v[166:169], v[150:153]
	v_mfma_f32_16x16x32_bf16 v[146:149], v[134:137], v[166:169], v[146:149]
	v_mfma_f32_16x16x32_bf16 v[110:113], v[126:129], v[174:177], v[110:113]
	v_mfma_f32_16x16x32_bf16 v[106:109], v[134:137], v[174:177], v[106:109]
	v_mfma_f32_16x16x32_bf16 v[94:97], v[126:129], v[182:185], v[94:97]
	v_mfma_f32_16x16x32_bf16 v[90:93], v[134:137], v[182:185], v[90:93]
	v_mfma_f32_16x16x32_bf16 v[78:81], v[126:129], v[202:205], v[78:81]
	v_mfma_f32_16x16x32_bf16 v[74:77], v[134:137], v[202:205], v[74:77]
	v_mfma_f32_16x16x32_bf16 v[122:125], v[138:141], v[162:165], 0
	v_mfma_f32_16x16x32_bf16 v[114:117], v[154:157], v[162:165], 0
	v_mfma_f32_16x16x32_bf16 v[102:105], v[138:141], v[170:173], 0
	v_mfma_f32_16x16x32_bf16 v[98:101], v[154:157], v[170:173], 0
	v_mfma_f32_16x16x32_bf16 v[86:89], v[138:141], v[178:181], 0
	v_mfma_f32_16x16x32_bf16 v[82:85], v[154:157], v[178:181], 0
	v_mfma_f32_16x16x32_bf16 v[70:73], v[138:141], v[186:189], 0
	v_mfma_f32_16x16x32_bf16 v[66:69], v[154:157], v[186:189], 0
	v_mfma_f32_16x16x32_bf16 v[122:125], v[142:145], v[166:169], v[122:125]
	v_mfma_f32_16x16x32_bf16 v[114:117], v[158:161], v[166:169], v[114:117]
	v_mfma_f32_16x16x32_bf16 v[102:105], v[142:145], v[174:177], v[102:105]
	v_mfma_f32_16x16x32_bf16 v[98:101], v[158:161], v[174:177], v[98:101]
	v_mfma_f32_16x16x32_bf16 v[86:89], v[142:145], v[182:185], v[86:89]
	v_mfma_f32_16x16x32_bf16 v[82:85], v[158:161], v[182:185], v[82:85]
	v_mfma_f32_16x16x32_bf16 v[70:73], v[142:145], v[202:205], v[70:73]
	v_mfma_f32_16x16x32_bf16 v[66:69], v[158:161], v[202:205], v[66:69]
	s_barrier
	s_add_i32 s84, s84, s34
	v_lshl_add_u64 v[210:211], s[30:31], 0, v[194:195]
	s_mov_b32 m0, s84
	ds_read_b128 v[162:165], v208 offset:16384
	ds_read_b128 v[166:169], v208 offset:17408
	ds_read_b128 v[170:173], v208 offset:18432
	ds_read_b128 v[174:177], v208 offset:19456
	ds_read_b128 v[178:181], v208 offset:20480
	ds_read_b128 v[182:185], v208 offset:21504
	ds_read_b128 v[186:189], v208 offset:22528
	ds_read_b128 v[202:205], v208 offset:23552
	global_load_lds_dwordx4 v[210:211], off
	s_add_i32 m0, s84, 0x2000
	s_add_u32 s84, s30, 0x80000
	v_lshl_add_u64 v[212:213], s[30:31], 0, v[190:191]
	s_addc_u32 s85, s31, 0
	s_add_i32 s90, s90, s34
	global_load_lds_dwordx4 v[212:213], off
	v_lshl_add_u64 v[214:215], s[84:85], 0, v[194:195]
	s_mov_b32 m0, s90
	v_lshl_add_u64 v[216:217], s[40:41], 0, v[192:193]
	global_load_lds_dwordx4 v[214:215], off
	v_lshl_add_u64 v[214:215], s[84:85], 0, v[190:191]
	s_add_i32 m0, s90, 0x2000
	s_nop 0
	global_load_lds_dwordx4 v[214:215], off
	v_lshl_add_u64 v[214:215], s[40:41], 0, v[196:197]
	s_mov_b32 m0, s35
	s_nop 0
	global_load_lds_dwordx4 v[214:215], off
	s_mov_b32 m0, s36
	s_nop 0
	global_load_lds_dwordx4 v[216:217], off
	s_waitcnt vmcnt(8)
	s_waitcnt lgkmcnt(0)
	s_barrier
; #define PG8_STAGE(bufoff, gbase, voff) do { _Pragma("unroll") for (int _i = 0; _i < 2; ++_i) \
;         __builtin_amdgcn_global_load_lds((const unsigned*)((const char*)(gbase) + (voff)[_i]), (PG8_LAS unsigned*)(lds + (bufoff) + ldsw + _i * 8192), 16, 0, 0); } while (0)
; #define PG8_LDA(dst, b, h) do { _Pragma("unroll") for (int m = 0; m < 4; ++m) _Pragma("unroll") for (int k = 0; k < 2; ++k) dst[m][k] = *(const PG8_LAS bf16x8*)(lds + PG8_SA(b, h) + aoff + m * 2048 + k * 1024); } while (0)
; #define PG8_LDB(dst, b, h) do { _Pragma("unroll") for (int n = 0; n < 2; ++n) _Pragma("unroll") for (int k = 0; k < 2; ++k) dst[n][k] = *(const PG8_LAS bf16x8*)(lds + PG8_SB(b, h) + boff + n * 2048 + k * 1024); } while (0)
; #define PG8_MMA(ai, bj, At, Bt) do { __builtin_amdgcn_s_setprio(1); _Pragma("unroll") for (int m = 0; m < 4; ++m) _Pragma("unroll") for (int n = 0; n < 2; ++n) _Pragma("unroll") for (int k = 0; k < 2; ++k) \
;         acc[ai][bj][m][n] = __builtin_amdgcn_mfma_f32_16x16x32_bf16(Bt[n][k], At[m][k], acc[ai][bj][m][n], 0, 0, 0); __builtin_amdgcn_s_setprio(0); } while (0)
; #define PG8_WAIT_V(n) asm volatile("s_waitcnt vmcnt(" #n ")" ::: "memory")
; #define PG8_WAIT_L(n) asm volatile("s_waitcnt lgkmcnt(" #n ")" ::: "memory")
; #define PG8_BAR __builtin_amdgcn_s_barrier()
; #define PG8_SCHED __builtin_amdgcn_sched_barrier(0)
; template <class Epi, class Sched, bool ALIGN_EPI = false, bool SP2 = false>
; __device__ __forceinline__ void gemm_phase(PG8_LAS unsigned char* lds, const Gemm g, const Sched& S, const Epi& E, int wave_s) {
;     ...
;             PG8_LDA(At, 0, 1); PG8_STAGE(PG8_SB(0, 0), b2, voffB); PG8_STAGE(PG8_SB(0, 1), b2 + hstepB, voffB); PG8_STAGE(PG8_SA(0, 0), a2, voffA);
;             PG8_WAIT_V(8); PG8_WAIT_L(0); PG8_BAR; PG8_MMA(1, 0, At, B0); PG8_MMA(1, 1, At, B1); PG8_BAR; PG8_SCHED;
;             PG8_LDB(B0, 1, 0); PG8_LDB(B1, 1, 1); PG8_SCHED; PG8_LDA(At, 1, 0); PG8_STAGE(PG8_SA(0, 1), a2 + hstepA, voffA);
;             PG8_WAIT_V(8); PG8_WAIT_L(0); PG8_BAR; PG8_MMA(0, 0, At, B0); PG8_MMA(0, 1, At, B1); PG8_BAR; PG8_SCHED;
	v_mfma_f32_16x16x32_bf16 v[62:65], v[118:121], v[162:165], 0
	v_mfma_f32_16x16x32_bf16 v[58:61], v[130:133], v[162:165], 0
	v_mfma_f32_16x16x32_bf16 v[46:49], v[118:121], v[170:173], 0
	v_mfma_f32_16x16x32_bf16 v[42:45], v[130:133], v[170:173], 0
	v_mfma_f32_16x16x32_bf16 v[30:33], v[118:121], v[178:181], 0
	v_mfma_f32_16x16x32_bf16 v[26:29], v[130:133], v[178:181], 0
	v_mfma_f32_16x16x32_bf16 v[14:17], v[118:121], v[186:189], 0
	v_mfma_f32_16x16x32_bf16 v[10:13], v[130:133], v[186:189], 0
	v_mfma_f32_16x16x32_bf16 v[62:65], v[126:129], v[166:169], v[62:65]
	v_mfma_f32_16x16x32_bf16 v[58:61], v[134:137], v[166:169], v[58:61]
	v_mfma_f32_16x16x32_bf16 v[46:49], v[126:129], v[174:177], v[46:49]
	v_mfma_f32_16x16x32_bf16 v[42:45], v[134:137], v[174:177], v[42:45]
	v_mfma_f32_16x16x32_bf16 v[30:33], v[126:129], v[182:185], v[30:33]
	v_mfma_f32_16x16x32_bf16 v[26:29], v[134:137], v[182:185], v[26:29]
	v_mfma_f32_16x16x32_bf16 v[14:17], v[126:129], v[202:205], v[14:17]
	v_mfma_f32_16x16x32_bf16 v[10:13], v[134:137], v[202:205], v[10:13]
	v_mfma_f32_16x16x32_bf16 v[54:57], v[138:141], v[162:165], 0
	v_mfma_f32_16x16x32_bf16 v[50:53], v[154:157], v[162:165], 0
	v_mfma_f32_16x16x32_bf16 v[38:41], v[138:141], v[170:173], 0
	v_mfma_f32_16x16x32_bf16 v[34:37], v[154:157], v[170:173], 0
	v_mfma_f32_16x16x32_bf16 v[22:25], v[138:141], v[178:181], 0
	v_mfma_f32_16x16x32_bf16 v[18:21], v[154:157], v[178:181], 0
	v_mfma_f32_16x16x32_bf16 v[6:9], v[138:141], v[186:189], 0
	v_mfma_f32_16x16x32_bf16 v[2:5], v[154:157], v[186:189], 0
	v_mfma_f32_16x16x32_bf16 v[54:57], v[142:145], v[166:169], v[54:57]
	v_mfma_f32_16x16x32_bf16 v[50:53], v[158:161], v[166:169], v[50:53]
	v_mfma_f32_16x16x32_bf16 v[38:41], v[142:145], v[174:177], v[38:41]
	v_mfma_f32_16x16x32_bf16 v[34:37], v[158:161], v[174:177], v[34:37]
	v_mfma_f32_16x16x32_bf16 v[22:25], v[142:145], v[182:185], v[22:25]
	v_mfma_f32_16x16x32_bf16 v[18:21], v[158:161], v[182:185], v[18:21]
	v_mfma_f32_16x16x32_bf16 v[6:9], v[142:145], v[202:205], v[6:9]
	v_mfma_f32_16x16x32_bf16 v[2:5], v[158:161], v[202:205], v[2:5]
	s_barrier
	s_add_i32 s84, 0, 0x18000
	s_add_i32 s85, 0, 0x1c000
	v_add_u32_e32 v134, s84, v207
	v_add_u32_e32 v158, s85, v207
	ds_read_b128 v[118:121], v134
	ds_read_b128 v[126:129], v134 offset:1024
	ds_read_b128 v[130:133], v134 offset:2048
	ds_read_b128 v[134:137], v134 offset:3072
	ds_read_b128 v[138:141], v158
	ds_read_b128 v[142:145], v158 offset:1024
	ds_read_b128 v[154:157], v158 offset:2048
	ds_read_b128 v[158:161], v158 offset:3072
	s_add_u32 s40, s40, 0x80000
	s_addc_u32 s41, s41, 0
	s_mov_b32 m0, s37
	v_lshl_add_u64 v[218:219], s[40:41], 0, v[196:197]
	ds_read_b128 v[162:165], v208 offset:32768
	ds_read_b128 v[166:169], v208 offset:33792
	ds_read_b128 v[170:173], v208 offset:34816
	ds_read_b128 v[174:177], v208 offset:35840
	ds_read_b128 v[178:181], v208 offset:36864
	ds_read_b128 v[182:185], v208 offset:37888
	ds_read_b128 v[186:189], v208 offset:38912
	ds_read_b128 v[202:205], v208 offset:39936
	global_load_lds_dwordx4 v[218:219], off
	v_lshl_add_u64 v[218:219], s[40:41], 0, v[192:193]
	s_mov_b32 m0, s42
	s_nop 0
	global_load_lds_dwordx4 v[218:219], off
	s_waitcnt vmcnt(8)
	s_waitcnt lgkmcnt(0)
	s_barrier
	v_mfma_f32_16x16x32_bf16 v[150:153], v[118:121], v[162:165], v[150:153]
	v_mfma_f32_16x16x32_bf16 v[146:149], v[130:133], v[162:165], v[146:149]
	v_mfma_f32_16x16x32_bf16 v[110:113], v[118:121], v[170:173], v[110:113]
	v_mfma_f32_16x16x32_bf16 v[106:109], v[130:133], v[170:173], v[106:109]
	v_mfma_f32_16x16x32_bf16 v[94:97], v[118:121], v[178:181], v[94:97]
	v_mfma_f32_16x16x32_bf16 v[90:93], v[130:133], v[178:181], v[90:93]
	v_mfma_f32_16x16x32_bf16 v[78:81], v[118:121], v[186:189], v[78:81]
	v_mfma_f32_16x16x32_bf16 v[74:77], v[130:133], v[186:189], v[74:77]
	v_mfma_f32_16x16x32_bf16 v[150:153], v[126:129], v[166:169], v[150:153]
	v_mfma_f32_16x16x32_bf16 v[146:149], v[134:137], v[166:169], v[146:149]
	v_mfma_f32_16x16x32_bf16 v[110:113], v[126:129], v[174:177], v[110:113]
	v_mfma_f32_16x16x32_bf16 v[106:109], v[134:137], v[174:177], v[106:109]
	v_mfma_f32_16x16x32_bf16 v[94:97], v[126:129], v[182:185], v[94:97]
	v_mfma_f32_16x16x32_bf16 v[90:93], v[134:137], v[182:185], v[90:93]
	v_mfma_f32_16x16x32_bf16 v[78:81], v[126:129], v[202:205], v[78:81]
	v_mfma_f32_16x16x32_bf16 v[74:77], v[134:137], v[202:205], v[74:77]
	v_mfma_f32_16x16x32_bf16 v[122:125], v[138:141], v[162:165], v[122:125]
	v_mfma_f32_16x16x32_bf16 v[114:117], v[154:157], v[162:165], v[114:117]
	v_mfma_f32_16x16x32_bf16 v[102:105], v[138:141], v[170:173], v[102:105]
	v_mfma_f32_16x16x32_bf16 v[98:101], v[154:157], v[170:173], v[98:101]
	v_mfma_f32_16x16x32_bf16 v[86:89], v[138:141], v[178:181], v[86:89]
	v_mfma_f32_16x16x32_bf16 v[82:85], v[154:157], v[178:181], v[82:85]
	v_mfma_f32_16x16x32_bf16 v[70:73], v[138:141], v[186:189], v[70:73]
	v_mfma_f32_16x16x32_bf16 v[66:69], v[154:157], v[186:189], v[66:69]
	v_mfma_f32_16x16x32_bf16 v[122:125], v[142:145], v[166:169], v[122:125]
	v_mfma_f32_16x16x32_bf16 v[114:117], v[158:161], v[166:169], v[114:117]
	v_mfma_f32_16x16x32_bf16 v[102:105], v[142:145], v[174:177], v[102:105]
	v_mfma_f32_16x16x32_bf16 v[98:101], v[158:161], v[174:177], v[98:101]
	v_mfma_f32_16x16x32_bf16 v[86:89], v[142:145], v[182:185], v[86:89]
	v_mfma_f32_16x16x32_bf16 v[82:85], v[158:161], v[182:185], v[82:85]
	v_mfma_f32_16x16x32_bf16 v[70:73], v[142:145], v[202:205], v[70:73]
	v_mfma_f32_16x16x32_bf16 v[66:69], v[158:161], v[202:205], v[66:69]
	s_barrier
; #define PG8_STAGE(bufoff, gbase, voff) do { _Pragma("unroll") for (int _i = 0; _i < 2; ++_i) \
;         __builtin_amdgcn_global_load_lds((const unsigned*)((const char*)(gbase) + (voff)[_i]), (PG8_LAS unsigned*)(lds + (bufoff) + ldsw + _i * 8192), 16, 0, 0); } while (0)
; #define PG8_LDA(dst, b, h) do { _Pragma("unroll") for (int m = 0; m < 4; ++m) _Pragma("unroll") for (int k = 0; k < 2; ++k) dst[m][k] = *(const PG8_LAS bf16x8*)(lds + PG8_SA(b, h) + aoff + m * 2048 + k * 1024); } while (0)
; #define PG8_LDB(dst, b, h) do { _Pragma("unroll") for (int n = 0; n < 2; ++n) _Pragma("unroll") for (int k = 0; k < 2; ++k) dst[n][k] = *(const PG8_LAS bf16x8*)(lds + PG8_SB(b, h) + boff + n * 2048 + k * 1024); } while (0)
; #define PG8_WAIT_V(n) asm volatile("s_waitcnt vmcnt(" #n ")" ::: "memory")
; #define PG8_WAIT_L(n) asm volatile("s_waitcnt lgkmcnt(" #n ")" ::: "memory")
; #define PG8_BAR __builtin_amdgcn_s_barrier()
; #define PG8_SCHED __builtin_amdgcn_sched_barrier(0)
; template <class Epi, class Sched, bool ALIGN_EPI = false, bool SP2 = false>
; __device__ __forceinline__ void gemm_phase(PG8_LAS unsigned char* lds, const Gemm g, const Sched& S, const Epi& E, int wave_s) {
;     ...
;         for (int t = 0; t < nt; t += 2) {
;             const bool last = (t == nt - 2);
;             const char* a1 = cA + (size_t)(t + 1) * kstep;
;             const char* a2 = last ? nA : cA + (size_t)(t + 2) * kstep; const char* b2 = last ? nB : cB + (size_t)(t + 2) * kstep;
;             const char* a3 = a2 + kstep; const char* b3 = b2 + kstep;
;             if (last && has_next) S.a_ready(nxt);
;             if constexpr (SP2) {
;             PG8_LDB(B0, 0, 0); PG8_LDB(B1, 0, 1); PG8_SCHED; PG8_LDA(At, 0, 0); PG8_STAGE(PG8_SA(1, 1), a1 + hstepA, voffA);
;             PG8_WAIT_V(8); PG8_WAIT_L(0); PG8_BAR; PG8_MMA(0, 0, At, B0); PG8_MMA(0, 1, At, B1); PG8_BAR; PG8_SCHED;
;             PG8_LDA(At, 0, 1); PG8_STAGE(PG8_SB(0, 0), b2, voffB); PG8_STAGE(PG8_SB(0, 1), b2 + hstepB, voffB); PG8_STAGE(PG8_SA(0, 0), a2, voffA);
;     ...
;             PG8_LDA(At, 1, 1); PG8_STAGE(PG8_SB(1, 0), b3, voffB); PG8_STAGE(PG8_SB(1, 1), b3 + hstepB, voffB); PG8_STAGE(PG8_SA(1, 0), a3, voffA);
;             PG8_WAIT_V(8); PG8_WAIT_L(0); PG8_BAR; PG8_MMA(1, 0, At, B0); PG8_MMA(1, 1, At, B1); PG8_BAR; PG8_SCHED;
	s_add_i32 s40, s84, s34
	v_lshl_add_u64 v[210:211], v[210:211], 0, s[60:61]
	s_mov_b32 m0, s40
	ds_read_b128 v[162:165], v208 offset:49152
	ds_read_b128 v[166:169], v208 offset:50176
	ds_read_b128 v[170:173], v208 offset:51200
	ds_read_b128 v[174:177], v208 offset:52224
	ds_read_b128 v[178:181], v208 offset:53248
	ds_read_b128 v[182:185], v208 offset:54272
	ds_read_b128 v[186:189], v208 offset:55296
	ds_read_b128 v[202:205], v208 offset:56320
	global_load_lds_dwordx4 v[210:211], off
	s_add_i32 m0, s40, 0x2000
	s_add_u32 s30, s30, 0x80080
	v_lshl_add_u64 v[210:211], v[212:213], 0, s[60:61]
	s_addc_u32 s31, s31, 0
	s_add_i32 s40, s85, s34
	global_load_lds_dwordx4 v[210:211], off
	v_lshl_add_u64 v[210:211], s[30:31], 0, v[194:195]
	s_mov_b32 m0, s40
	s_nop 0
	global_load_lds_dwordx4 v[210:211], off
	v_lshl_add_u64 v[210:211], s[30:31], 0, v[190:191]
	s_add_i32 m0, s40, 0x2000
	s_nop 0
	global_load_lds_dwordx4 v[210:211], off
	v_lshl_add_u64 v[210:211], v[214:215], 0, s[60:61]
	s_mov_b32 m0, s46
	s_nop 0
	global_load_lds_dwordx4 v[210:211], off
	v_lshl_add_u64 v[210:211], v[216:217], 0, s[60:61]
	s_mov_b32 m0, s47
	s_nop 0
	global_load_lds_dwordx4 v[210:211], off
	s_waitcnt vmcnt(8)
	s_waitcnt lgkmcnt(0)
	s_barrier
	v_mfma_f32_16x16x32_bf16 v[62:65], v[118:121], v[162:165], v[62:65]
	v_mfma_f32_16x16x32_bf16 v[58:61], v[130:133], v[162:165], v[58:61]
	v_mfma_f32_16x16x32_bf16 v[46:49], v[118:121], v[170:173], v[46:49]
	v_mfma_f32_16x16x32_bf16 v[42:45], v[130:133], v[170:173], v[42:45]
	v_mfma_f32_16x16x32_bf16 v[30:33], v[118:121], v[178:181], v[30:33]
	v_mfma_f32_16x16x32_bf16 v[26:29], v[130:133], v[178:181], v[26:29]
	v_mfma_f32_16x16x32_bf16 v[14:17], v[118:121], v[186:189], v[14:17]
	v_mfma_f32_16x16x32_bf16 v[10:13], v[130:133], v[186:189], v[10:13]
	v_mfma_f32_16x16x32_bf16 v[62:65], v[126:129], v[166:169], v[62:65]
	v_mfma_f32_16x16x32_bf16 v[58:61], v[134:137], v[166:169], v[58:61]
	v_mfma_f32_16x16x32_bf16 v[46:49], v[126:129], v[174:177], v[46:49]
	v_mfma_f32_16x16x32_bf16 v[42:45], v[134:137], v[174:177], v[42:45]
	v_mfma_f32_16x16x32_bf16 v[30:33], v[126:129], v[182:185], v[30:33]
	v_mfma_f32_16x16x32_bf16 v[26:29], v[134:137], v[182:185], v[26:29]
	v_mfma_f32_16x16x32_bf16 v[14:17], v[126:129], v[202:205], v[14:17]
	v_mfma_f32_16x16x32_bf16 v[10:13], v[134:137], v[202:205], v[10:13]
	v_mfma_f32_16x16x32_bf16 v[54:57], v[138:141], v[162:165], v[54:57]
	v_mfma_f32_16x16x32_bf16 v[50:53], v[154:157], v[162:165], v[50:53]
	v_mfma_f32_16x16x32_bf16 v[38:41], v[138:141], v[170:173], v[38:41]
	v_mfma_f32_16x16x32_bf16 v[34:37], v[154:157], v[170:173], v[34:37]
	v_mfma_f32_16x16x32_bf16 v[22:25], v[138:141], v[178:181], v[22:25]
	v_mfma_f32_16x16x32_bf16 v[18:21], v[154:157], v[178:181], v[18:21]
	v_mfma_f32_16x16x32_bf16 v[6:9], v[138:141], v[186:189], v[6:9]
	v_mfma_f32_16x16x32_bf16 v[2:5], v[154:157], v[186:189], v[2:5]
	v_mfma_f32_16x16x32_bf16 v[54:57], v[142:145], v[166:169], v[54:57]
	v_mfma_f32_16x16x32_bf16 v[50:53], v[158:161], v[166:169], v[50:53]
	v_mfma_f32_16x16x32_bf16 v[38:41], v[142:145], v[174:177], v[38:41]
	v_mfma_f32_16x16x32_bf16 v[34:37], v[158:161], v[174:177], v[34:37]
	v_mfma_f32_16x16x32_bf16 v[22:25], v[142:145], v[182:185], v[22:25]
	v_mfma_f32_16x16x32_bf16 v[18:21], v[158:161], v[182:185], v[18:21]
	v_mfma_f32_16x16x32_bf16 v[6:9], v[142:145], v[202:205], v[6:9]
	v_mfma_f32_16x16x32_bf16 v[2:5], v[158:161], v[202:205], v[2:5]
	s_barrier
	s_add_i32 s81, s81, 2
	s_add_u32 s4, s4, 0x100
	s_addc_u32 s5, s5, 0
	s_add_u32 s21, s21, 0x100
	s_addc_u32 s27, s27, 0
	s_cmp_gt_u32 s81, 29
.LBB0_602:
	s_add_u32 s30, s4, 0xfff80080
	s_addc_u32 s31, s5, -1
	s_add_i32 s84, 0, 0x10000
	s_cmp_eq_u32 s81, 28
	s_cselect_b32 s41, s29, s31
	s_cselect_b32 s40, s28, s30
	s_cselect_b32 s31, s2, s27
	s_cselect_b32 s30, s3, s21
	s_add_i32 s90, 0, 0x14000
	v_add_u32_e32 v134, s84, v207
	v_add_u32_e32 v158, s90, v207
	ds_read_b128 v[118:121], v134
	ds_read_b128 v[126:129], v134 offset:1024
	ds_read_b128 v[130:133], v134 offset:2048
	ds_read_b128 v[134:137], v134 offset:3072
	ds_read_b128 v[138:141], v158
	ds_read_b128 v[142:145], v158 offset:1024
	ds_read_b128 v[154:157], v158 offset:2048
	ds_read_b128 v[158:161], v158 offset:3072
	v_lshl_add_u64 v[210:211], s[4:5], 0, v[198:199]
	s_add_i32 m0, s35, 0xc000
	ds_read_b128 v[162:165], v208
	ds_read_b128 v[166:169], v208 offset:1024
	ds_read_b128 v[170:173], v208 offset:2048
	ds_read_b128 v[174:177], v208 offset:3072
	ds_read_b128 v[178:181], v208 offset:4096
	ds_read_b128 v[182:185], v208 offset:5120
	ds_read_b128 v[186:189], v208 offset:6144
	ds_read_b128 v[202:205], v208 offset:7168
	global_load_lds_dwordx4 v[210:211], off
	v_lshl_add_u64 v[210:211], s[4:5], 0, v[200:201]
	s_add_i32 m0, s35, 0xe000
	s_nop 0
	global_load_lds_dwordx4 v[210:211], off
	s_waitcnt vmcnt(8)
	s_waitcnt lgkmcnt(0)
	s_barrier
; #define PG8_STAGE(bufoff, gbase, voff) do { _Pragma("unroll") for (int _i = 0; _i < 2; ++_i) \
;         __builtin_amdgcn_global_load_lds((const unsigned*)((const char*)(gbase) + (voff)[_i]), (PG8_LAS unsigned*)(lds + (bufoff) + ldsw + _i * 8192), 16, 0, 0); } while (0)
; #define PG8_LDA(dst, b, h) do { _Pragma("unroll") for (int m = 0; m < 4; ++m) _Pragma("unroll") for (int k = 0; k < 2; ++k) dst[m][k] = *(const PG8_LAS bf16x8*)(lds + PG8_SA(b, h) + aoff + m * 2048 + k * 1024); } while (0)
; #define PG8_LDB(dst, b, h) do { _Pragma("unroll") for (int n = 0; n < 2; ++n) _Pragma("unroll") for (int k = 0; k < 2; ++k) dst[n][k] = *(const PG8_LAS bf16x8*)(lds + PG8_SB(b, h) + boff + n * 2048 + k * 1024); } while (0)
; #define PG8_MMA(ai, bj, At, Bt) do { __builtin_amdgcn_s_setprio(1); _Pragma("unroll") for (int m = 0; m < 4; ++m) _Pragma("unroll") for (int n = 0; n < 2; ++n) _Pragma("unroll") for (int k = 0; k < 2; ++k) \
;         acc[ai][bj][m][n] = __builtin_amdgcn_mfma_f32_16x16x32_bf16(Bt[n][k], At[m][k], acc[ai][bj][m][n], 0, 0, 0); __builtin_amdgcn_s_setprio(0); } while (0)
; #define PG8_WAIT_V(n) asm volatile("s_waitcnt vmcnt(" #n ")" ::: "memory")
; #define PG8_WAIT_L(n) asm volatile("s_waitcnt lgkmcnt(" #n ")" ::: "memory")
; #define PG8_BAR __builtin_amdgcn_s_barrier()
; #define PG8_SCHED __builtin_amdgcn_sched_barrier(0)
; template <class Epi, class Sched, bool ALIGN_EPI = false, bool SP2 = false>
; __device__ __forceinline__ void gemm_phase(PG8_LAS unsigned char* lds, const Gemm g, const Sched& S, const Epi& E, int wave_s) {
;     ...
;             PG8_LDB(B0, 0, 0); PG8_LDB(B1, 0, 1); PG8_SCHED; PG8_LDA(At, 0, 0); PG8_STAGE(PG8_SA(1, 1), a1 + hstepA, voffA);
;             PG8_WAIT_V(8); PG8_WAIT_L(0); PG8_BAR; PG8_MMA(0, 0, At, B0); PG8_MMA(0, 1, At, B1); PG8_BAR; PG8_SCHED;
;             PG8_LDA(At, 0, 1); PG8_STAGE(PG8_SB(0, 0), b2, voffB); PG8_STAGE(PG8_SB(0, 1), b2 + hstepB, voffB); PG8_STAGE(PG8_SA(0, 0), a2, voffA);
;             PG8_WAIT_V(8); PG8_WAIT_L(0); PG8_BAR; PG8_MMA(1, 0, At, B0); PG8_MMA(1, 1, At, B1); PG8_BAR; PG8_SCHED;
	v_mfma_f32_16x16x32_bf16 v[150:153], v[118:121], v[162:165], v[150:153]
	v_mfma_f32_16x16x32_bf16 v[146:149], v[130:133], v[162:165], v[146:149]
	v_mfma_f32_16x16x32_bf16 v[110:113], v[118:121], v[170:173], v[110:113]
	v_mfma_f32_16x16x32_bf16 v[106:109], v[130:133], v[170:173], v[106:109]
	v_mfma_f32_16x16x32_bf16 v[94:97], v[118:121], v[178:181], v[94:97]
	v_mfma_f32_16x16x32_bf16 v[90:93], v[130:133], v[178:181], v[90:93]
	v_mfma_f32_16x16x32_bf16 v[78:81], v[118:121], v[186:189], v[78:81]
	v_mfma_f32_16x16x32_bf16 v[74:77], v[130:133], v[186:189], v[74:77]
	v_mfma_f32_16x16x32_bf16 v[150:153], v[126:129], v[166:169], v[150:153]
	v_mfma_f32_16x16x32_bf16 v[146:149], v[134:137], v[166:169], v[146:149]
	v_mfma_f32_16x16x32_bf16 v[110:113], v[126:129], v[174:177], v[110:113]
	v_mfma_f32_16x16x32_bf16 v[106:109], v[134:137], v[174:177], v[106:109]
	v_mfma_f32_16x16x32_bf16 v[94:97], v[126:129], v[182:185], v[94:97]
	v_mfma_f32_16x16x32_bf16 v[90:93], v[134:137], v[182:185], v[90:93]
	v_mfma_f32_16x16x32_bf16 v[78:81], v[126:129], v[202:205], v[78:81]
	v_mfma_f32_16x16x32_bf16 v[74:77], v[134:137], v[202:205], v[74:77]
	v_mfma_f32_16x16x32_bf16 v[122:125], v[138:141], v[162:165], v[122:125]
	v_mfma_f32_16x16x32_bf16 v[114:117], v[154:157], v[162:165], v[114:117]
	v_mfma_f32_16x16x32_bf16 v[102:105], v[138:141], v[170:173], v[102:105]
	v_mfma_f32_16x16x32_bf16 v[98:101], v[154:157], v[170:173], v[98:101]
	v_mfma_f32_16x16x32_bf16 v[86:89], v[138:141], v[178:181], v[86:89]
	v_mfma_f32_16x16x32_bf16 v[82:85], v[154:157], v[178:181], v[82:85]
	v_mfma_f32_16x16x32_bf16 v[70:73], v[138:141], v[186:189], v[70:73]
	v_mfma_f32_16x16x32_bf16 v[66:69], v[154:157], v[186:189], v[66:69]
	v_mfma_f32_16x16x32_bf16 v[122:125], v[142:145], v[166:169], v[122:125]
	v_mfma_f32_16x16x32_bf16 v[114:117], v[158:161], v[166:169], v[114:117]
	v_mfma_f32_16x16x32_bf16 v[102:105], v[142:145], v[174:177], v[102:105]
	v_mfma_f32_16x16x32_bf16 v[98:101], v[158:161], v[174:177], v[98:101]
	v_mfma_f32_16x16x32_bf16 v[86:89], v[142:145], v[182:185], v[86:89]
	v_mfma_f32_16x16x32_bf16 v[82:85], v[158:161], v[182:185], v[82:85]
	v_mfma_f32_16x16x32_bf16 v[70:73], v[142:145], v[202:205], v[70:73]
	v_mfma_f32_16x16x32_bf16 v[66:69], v[158:161], v[202:205], v[66:69]
	s_barrier
	s_add_i32 s84, s84, s34
	v_lshl_add_u64 v[210:211], s[30:31], 0, v[194:195]
	s_mov_b32 m0, s84
	ds_read_b128 v[162:165], v208 offset:16384
	ds_read_b128 v[166:169], v208 offset:17408
	ds_read_b128 v[170:173], v208 offset:18432
	ds_read_b128 v[174:177], v208 offset:19456
	ds_read_b128 v[178:181], v208 offset:20480
	ds_read_b128 v[182:185], v208 offset:21504
	ds_read_b128 v[186:189], v208 offset:22528
	ds_read_b128 v[202:205], v208 offset:23552
	global_load_lds_dwordx4 v[210:211], off
	s_add_i32 m0, s84, 0x2000
	s_add_u32 s84, s30, 0x80000
	v_lshl_add_u64 v[212:213], s[30:31], 0, v[190:191]
	s_addc_u32 s85, s31, 0
	s_add_i32 s90, s90, s34
	global_load_lds_dwordx4 v[212:213], off
	v_lshl_add_u64 v[214:215], s[84:85], 0, v[194:195]
	s_mov_b32 m0, s90
	v_lshl_add_u64 v[216:217], s[40:41], 0, v[192:193]
	global_load_lds_dwordx4 v[214:215], off
	v_lshl_add_u64 v[214:215], s[84:85], 0, v[190:191]
	s_add_i32 m0, s90, 0x2000
	s_nop 0
	global_load_lds_dwordx4 v[214:215], off
	v_lshl_add_u64 v[214:215], s[40:41], 0, v[196:197]
	s_mov_b32 m0, s35
	s_nop 0
	global_load_lds_dwordx4 v[214:215], off
	s_mov_b32 m0, s36
	s_nop 0
	global_load_lds_dwordx4 v[216:217], off
	s_waitcnt vmcnt(8)
	s_waitcnt lgkmcnt(0)
	s_barrier
	v_mfma_f32_16x16x32_bf16 v[62:65], v[118:121], v[162:165], v[62:65]
	v_mfma_f32_16x16x32_bf16 v[58:61], v[130:133], v[162:165], v[58:61]
	v_mfma_f32_16x16x32_bf16 v[46:49], v[118:121], v[170:173], v[46:49]
	v_mfma_f32_16x16x32_bf16 v[42:45], v[130:133], v[170:173], v[42:45]
	v_mfma_f32_16x16x32_bf16 v[30:33], v[118:121], v[178:181], v[30:33]
	v_mfma_f32_16x16x32_bf16 v[26:29], v[130:133], v[178:181], v[26:29]
	v_mfma_f32_16x16x32_bf16 v[14:17], v[118:121], v[186:189], v[14:17]
	v_mfma_f32_16x16x32_bf16 v[10:13], v[130:133], v[186:189], v[10:13]
	v_mfma_f32_16x16x32_bf16 v[62:65], v[126:129], v[166:169], v[62:65]
	v_mfma_f32_16x16x32_bf16 v[58:61], v[134:137], v[166:169], v[58:61]
	v_mfma_f32_16x16x32_bf16 v[46:49], v[126:129], v[174:177], v[46:49]
	v_mfma_f32_16x16x32_bf16 v[42:45], v[134:137], v[174:177], v[42:45]
	v_mfma_f32_16x16x32_bf16 v[30:33], v[126:129], v[182:185], v[30:33]
	v_mfma_f32_16x16x32_bf16 v[26:29], v[134:137], v[182:185], v[26:29]
	v_mfma_f32_16x16x32_bf16 v[14:17], v[126:129], v[202:205], v[14:17]
	v_mfma_f32_16x16x32_bf16 v[10:13], v[134:137], v[202:205], v[10:13]
	v_mfma_f32_16x16x32_bf16 v[54:57], v[138:141], v[162:165], v[54:57]
	v_mfma_f32_16x16x32_bf16 v[50:53], v[154:157], v[162:165], v[50:53]
	v_mfma_f32_16x16x32_bf16 v[38:41], v[138:141], v[170:173], v[38:41]
	v_mfma_f32_16x16x32_bf16 v[34:37], v[154:157], v[170:173], v[34:37]
	v_mfma_f32_16x16x32_bf16 v[22:25], v[138:141], v[178:181], v[22:25]
	v_mfma_f32_16x16x32_bf16 v[18:21], v[154:157], v[178:181], v[18:21]
	v_mfma_f32_16x16x32_bf16 v[6:9], v[138:141], v[186:189], v[6:9]
	v_mfma_f32_16x16x32_bf16 v[2:5], v[154:157], v[186:189], v[2:5]
	v_mfma_f32_16x16x32_bf16 v[54:57], v[142:145], v[166:169], v[54:57]
	v_mfma_f32_16x16x32_bf16 v[50:53], v[158:161], v[166:169], v[50:53]
	v_mfma_f32_16x16x32_bf16 v[38:41], v[142:145], v[174:177], v[38:41]
	v_mfma_f32_16x16x32_bf16 v[34:37], v[158:161], v[174:177], v[34:37]
	v_mfma_f32_16x16x32_bf16 v[22:25], v[142:145], v[182:185], v[22:25]
	v_mfma_f32_16x16x32_bf16 v[18:21], v[158:161], v[182:185], v[18:21]
	v_mfma_f32_16x16x32_bf16 v[6:9], v[142:145], v[202:205], v[6:9]
	v_mfma_f32_16x16x32_bf16 v[2:5], v[158:161], v[202:205], v[2:5]
	s_barrier
; #define PG8_STAGE(bufoff, gbase, voff) do { _Pragma("unroll") for (int _i = 0; _i < 2; ++_i) \
;         __builtin_amdgcn_global_load_lds((const unsigned*)((const char*)(gbase) + (voff)[_i]), (PG8_LAS unsigned*)(lds + (bufoff) + ldsw + _i * 8192), 16, 0, 0); } while (0)
; #define PG8_LDA(dst, b, h) do { _Pragma("unroll") for (int m = 0; m < 4; ++m) _Pragma("unroll") for (int k = 0; k < 2; ++k) dst[m][k] = *(const PG8_LAS bf16x8*)(lds + PG8_SA(b, h) + aoff + m * 2048 + k * 1024); } while (0)
; #define PG8_LDB(dst, b, h) do { _Pragma("unroll") for (int n = 0; n < 2; ++n) _Pragma("unroll") for (int k = 0; k < 2; ++k) dst[n][k] = *(const PG8_LAS bf16x8*)(lds + PG8_SB(b, h) + boff + n * 2048 + k * 1024); } while (0)
; #define PG8_MMA(ai, bj, At, Bt) do { __builtin_amdgcn_s_setprio(1); _Pragma("unroll") for (int m = 0; m < 4; ++m) _Pragma("unroll") for (int n = 0; n < 2; ++n) _Pragma("unroll") for (int k = 0; k < 2; ++k) \
;         acc[ai][bj][m][n] = __builtin_amdgcn_mfma_f32_16x16x32_bf16(Bt[n][k], At[m][k], acc[ai][bj][m][n], 0, 0, 0); __builtin_amdgcn_s_setprio(0); } while (0)
; #define PG8_WAIT_V(n) asm volatile("s_waitcnt vmcnt(" #n ")" ::: "memory")
; #define PG8_WAIT_L(n) asm volatile("s_waitcnt lgkmcnt(" #n ")" ::: "memory")
; #define PG8_BAR __builtin_amdgcn_s_barrier()
; #define PG8_SCHED __builtin_amdgcn_sched_barrier(0)
; template <class Epi, class Sched, bool ALIGN_EPI = false, bool SP2 = false>
; __device__ __forceinline__ void gemm_phase(PG8_LAS unsigned char* lds, const Gemm g, const Sched& S, const Epi& E, int wave_s) {
;     ...
;             PG8_LDB(B0, 1, 0); PG8_LDB(B1, 1, 1); PG8_SCHED; PG8_LDA(At, 1, 0); PG8_STAGE(PG8_SA(0, 1), a2 + hstepA, voffA);
;             PG8_WAIT_V(8); PG8_WAIT_L(0); PG8_BAR; PG8_MMA(0, 0, At, B0); PG8_MMA(0, 1, At, B1); PG8_BAR; PG8_SCHED;
	s_add_i32 s84, 0, 0x18000
	s_add_i32 s85, 0, 0x1c000
	v_add_u32_e32 v134, s84, v207
	v_add_u32_e32 v158, s85, v207
	ds_read_b128 v[118:121], v134
	ds_read_b128 v[126:129], v134 offset:1024
	ds_read_b128 v[130:133], v134 offset:2048
	ds_read_b128 v[134:137], v134 offset:3072
	ds_read_b128 v[138:141], v158
	ds_read_b128 v[142:145], v158 offset:1024
	ds_read_b128 v[154:157], v158 offset:2048
	ds_read_b128 v[158:161], v158 offset:3072
	s_add_u32 s40, s40, 0x80000
	s_addc_u32 s41, s41, 0
	s_mov_b32 m0, s37
	v_lshl_add_u64 v[218:219], s[40:41], 0, v[196:197]
	ds_read_b128 v[162:165], v208 offset:32768
	ds_read_b128 v[166:169], v208 offset:33792
	ds_read_b128 v[170:173], v208 offset:34816
	ds_read_b128 v[174:177], v208 offset:35840
	ds_read_b128 v[178:181], v208 offset:36864
	ds_read_b128 v[182:185], v208 offset:37888
	ds_read_b128 v[186:189], v208 offset:38912
	ds_read_b128 v[202:205], v208 offset:39936
	global_load_lds_dwordx4 v[218:219], off
	v_lshl_add_u64 v[218:219], s[40:41], 0, v[192:193]
	s_mov_b32 m0, s42
	s_nop 0
	global_load_lds_dwordx4 v[218:219], off
	s_waitcnt vmcnt(8)
	s_waitcnt lgkmcnt(0)
	s_barrier
	v_mfma_f32_16x16x32_bf16 v[150:153], v[118:121], v[162:165], v[150:153]
	v_mfma_f32_16x16x32_bf16 v[146:149], v[130:133], v[162:165], v[146:149]
	v_mfma_f32_16x16x32_bf16 v[110:113], v[118:121], v[170:173], v[110:113]
	v_mfma_f32_16x16x32_bf16 v[106:109], v[130:133], v[170:173], v[106:109]
	v_mfma_f32_16x16x32_bf16 v[94:97], v[118:121], v[178:181], v[94:97]
	v_mfma_f32_16x16x32_bf16 v[90:93], v[130:133], v[178:181], v[90:93]
	v_mfma_f32_16x16x32_bf16 v[78:81], v[118:121], v[186:189], v[78:81]
	v_mfma_f32_16x16x32_bf16 v[74:77], v[130:133], v[186:189], v[74:77]
	v_mfma_f32_16x16x32_bf16 v[150:153], v[126:129], v[166:169], v[150:153]
	v_mfma_f32_16x16x32_bf16 v[146:149], v[134:137], v[166:169], v[146:149]
	v_mfma_f32_16x16x32_bf16 v[110:113], v[126:129], v[174:177], v[110:113]
	v_mfma_f32_16x16x32_bf16 v[106:109], v[134:137], v[174:177], v[106:109]
	v_mfma_f32_16x16x32_bf16 v[94:97], v[126:129], v[182:185], v[94:97]
	v_mfma_f32_16x16x32_bf16 v[90:93], v[134:137], v[182:185], v[90:93]
	v_mfma_f32_16x16x32_bf16 v[78:81], v[126:129], v[202:205], v[78:81]
	v_mfma_f32_16x16x32_bf16 v[74:77], v[134:137], v[202:205], v[74:77]
	v_mfma_f32_16x16x32_bf16 v[122:125], v[138:141], v[162:165], v[122:125]
	v_mfma_f32_16x16x32_bf16 v[114:117], v[154:157], v[162:165], v[114:117]
	v_mfma_f32_16x16x32_bf16 v[102:105], v[138:141], v[170:173], v[102:105]
	v_mfma_f32_16x16x32_bf16 v[98:101], v[154:157], v[170:173], v[98:101]
	v_mfma_f32_16x16x32_bf16 v[86:89], v[138:141], v[178:181], v[86:89]
	v_mfma_f32_16x16x32_bf16 v[82:85], v[154:157], v[178:181], v[82:85]
	v_mfma_f32_16x16x32_bf16 v[70:73], v[138:141], v[186:189], v[70:73]
	v_mfma_f32_16x16x32_bf16 v[66:69], v[154:157], v[186:189], v[66:69]
	v_mfma_f32_16x16x32_bf16 v[122:125], v[142:145], v[166:169], v[122:125]
	v_mfma_f32_16x16x32_bf16 v[114:117], v[158:161], v[166:169], v[114:117]
	v_mfma_f32_16x16x32_bf16 v[102:105], v[142:145], v[174:177], v[102:105]
	v_mfma_f32_16x16x32_bf16 v[98:101], v[158:161], v[174:177], v[98:101]
	v_mfma_f32_16x16x32_bf16 v[86:89], v[142:145], v[182:185], v[86:89]
	v_mfma_f32_16x16x32_bf16 v[82:85], v[158:161], v[182:185], v[82:85]
	v_mfma_f32_16x16x32_bf16 v[70:73], v[142:145], v[202:205], v[70:73]
	v_mfma_f32_16x16x32_bf16 v[66:69], v[158:161], v[202:205], v[66:69]
	s_barrier
; #define PG8_STAGE(bufoff, gbase, voff) do { _Pragma("unroll") for (int _i = 0; _i < 2; ++_i) \
;         __builtin_amdgcn_global_load_lds((const unsigned*)((const char*)(gbase) + (voff)[_i]), (PG8_LAS unsigned*)(lds + (bufoff) + ldsw + _i * 8192), 16, 0, 0); } while (0)
; #define PG8_LDA(dst, b, h) do { _Pragma("unroll") for (int m = 0; m < 4; ++m) _Pragma("unroll") for (int k = 0; k < 2; ++k) dst[m][k] = *(const PG8_LAS bf16x8*)(lds + PG8_SA(b, h) + aoff + m * 2048 + k * 1024); } while (0)
; #define PG8_MMA(ai, bj, At, Bt) do { __builtin_amdgcn_s_setprio(1); _Pragma("unroll") for (int m = 0; m < 4; ++m) _Pragma("unroll") for (int n = 0; n < 2; ++n) _Pragma("unroll") for (int k = 0; k < 2; ++k) \
;         acc[ai][bj][m][n] = __builtin_amdgcn_mfma_f32_16x16x32_bf16(Bt[n][k], At[m][k], acc[ai][bj][m][n], 0, 0, 0); __builtin_amdgcn_s_setprio(0); } while (0)
; #define PG8_WAIT_V(n) asm volatile("s_waitcnt vmcnt(" #n ")" ::: "memory")
; #define PG8_WAIT_L(n) asm volatile("s_waitcnt lgkmcnt(" #n ")" ::: "memory")
; #define PG8_BAR __builtin_amdgcn_s_barrier()
; #define PG8_SCHED __builtin_amdgcn_sched_barrier(0)
; template <class Epi, class Sched, bool ALIGN_EPI = false, bool SP2 = false>
; __device__ __forceinline__ void gemm_phase(PG8_LAS unsigned char* lds, const Gemm g, const Sched& S, const Epi& E, int wave_s) {
;     ...
;         for (int t = 0; t < nt; t += 2) {
;             const bool last = (t == nt - 2);
;             const char* a1 = cA + (size_t)(t + 1) * kstep;
;             const char* a2 = last ? nA : cA + (size_t)(t + 2) * kstep; const char* b2 = last ? nB : cB + (size_t)(t + 2) * kstep;
;     ...
;             PG8_LDA(At, 1, 1); PG8_STAGE(PG8_SB(1, 0), b3, voffB); PG8_STAGE(PG8_SB(1, 1), b3 + hstepB, voffB); PG8_STAGE(PG8_SA(1, 0), a3, voffA);
;             PG8_WAIT_V(8); PG8_WAIT_L(0); PG8_BAR; PG8_MMA(1, 0, At, B0); PG8_MMA(1, 1, At, B1); PG8_BAR; PG8_SCHED;
	s_add_i32 s40, s84, s34
	v_lshl_add_u64 v[210:211], v[210:211], 0, s[60:61]
	s_mov_b32 m0, s40
	ds_read_b128 v[162:165], v208 offset:49152
	ds_read_b128 v[166:169], v208 offset:50176
	ds_read_b128 v[170:173], v208 offset:51200
	ds_read_b128 v[174:177], v208 offset:52224
	ds_read_b128 v[178:181], v208 offset:53248
	ds_read_b128 v[182:185], v208 offset:54272
	ds_read_b128 v[186:189], v208 offset:55296
	ds_read_b128 v[202:205], v208 offset:56320
	global_load_lds_dwordx4 v[210:211], off
	s_add_i32 m0, s40, 0x2000
	s_add_u32 s30, s30, 0x80080
	v_lshl_add_u64 v[210:211], v[212:213], 0, s[60:61]
	s_addc_u32 s31, s31, 0
	s_add_i32 s40, s85, s34
	global_load_lds_dwordx4 v[210:211], off
	v_lshl_add_u64 v[210:211], s[30:31], 0, v[194:195]
	s_mov_b32 m0, s40
	s_nop 0
	global_load_lds_dwordx4 v[210:211], off
	v_lshl_add_u64 v[210:211], s[30:31], 0, v[190:191]
	s_add_i32 m0, s40, 0x2000
	s_nop 0
	global_load_lds_dwordx4 v[210:211], off
	v_lshl_add_u64 v[210:211], v[214:215], 0, s[60:61]
	s_mov_b32 m0, s46
	s_nop 0
	global_load_lds_dwordx4 v[210:211], off
	v_lshl_add_u64 v[210:211], v[216:217], 0, s[60:61]
	s_mov_b32 m0, s47
	s_nop 0
	global_load_lds_dwordx4 v[210:211], off
	s_waitcnt vmcnt(8)
	s_waitcnt lgkmcnt(0)
	s_barrier
	v_mfma_f32_16x16x32_bf16 v[62:65], v[118:121], v[162:165], v[62:65]
	v_mfma_f32_16x16x32_bf16 v[58:61], v[130:133], v[162:165], v[58:61]
	v_mfma_f32_16x16x32_bf16 v[46:49], v[118:121], v[170:173], v[46:49]
	v_mfma_f32_16x16x32_bf16 v[42:45], v[130:133], v[170:173], v[42:45]
	v_mfma_f32_16x16x32_bf16 v[30:33], v[118:121], v[178:181], v[30:33]
	v_mfma_f32_16x16x32_bf16 v[26:29], v[130:133], v[178:181], v[26:29]
	v_mfma_f32_16x16x32_bf16 v[14:17], v[118:121], v[186:189], v[14:17]
	v_mfma_f32_16x16x32_bf16 v[10:13], v[130:133], v[186:189], v[10:13]
	v_mfma_f32_16x16x32_bf16 v[62:65], v[126:129], v[166:169], v[62:65]
	v_mfma_f32_16x16x32_bf16 v[58:61], v[134:137], v[166:169], v[58:61]
	v_mfma_f32_16x16x32_bf16 v[46:49], v[126:129], v[174:177], v[46:49]
	v_mfma_f32_16x16x32_bf16 v[42:45], v[134:137], v[174:177], v[42:45]
	v_mfma_f32_16x16x32_bf16 v[30:33], v[126:129], v[182:185], v[30:33]
	v_mfma_f32_16x16x32_bf16 v[26:29], v[134:137], v[182:185], v[26:29]
	v_mfma_f32_16x16x32_bf16 v[14:17], v[126:129], v[202:205], v[14:17]
	v_mfma_f32_16x16x32_bf16 v[10:13], v[134:137], v[202:205], v[10:13]
	v_mfma_f32_16x16x32_bf16 v[54:57], v[138:141], v[162:165], v[54:57]
	v_mfma_f32_16x16x32_bf16 v[50:53], v[154:157], v[162:165], v[50:53]
	v_mfma_f32_16x16x32_bf16 v[38:41], v[138:141], v[170:173], v[38:41]
	v_mfma_f32_16x16x32_bf16 v[34:37], v[154:157], v[170:173], v[34:37]
	v_mfma_f32_16x16x32_bf16 v[22:25], v[138:141], v[178:181], v[22:25]
	v_mfma_f32_16x16x32_bf16 v[18:21], v[154:157], v[178:181], v[18:21]
	v_mfma_f32_16x16x32_bf16 v[6:9], v[138:141], v[186:189], v[6:9]
	v_mfma_f32_16x16x32_bf16 v[2:5], v[154:157], v[186:189], v[2:5]
	v_mfma_f32_16x16x32_bf16 v[54:57], v[142:145], v[166:169], v[54:57]
	v_mfma_f32_16x16x32_bf16 v[50:53], v[158:161], v[166:169], v[50:53]
	v_mfma_f32_16x16x32_bf16 v[38:41], v[142:145], v[174:177], v[38:41]
	v_mfma_f32_16x16x32_bf16 v[34:37], v[158:161], v[174:177], v[34:37]
	v_mfma_f32_16x16x32_bf16 v[22:25], v[142:145], v[182:185], v[22:25]
	v_mfma_f32_16x16x32_bf16 v[18:21], v[158:161], v[182:185], v[18:21]
	v_mfma_f32_16x16x32_bf16 v[6:9], v[142:145], v[202:205], v[6:9]
	v_mfma_f32_16x16x32_bf16 v[2:5], v[158:161], v[202:205], v[2:5]
	s_barrier
	s_add_i32 s81, s81, 2
	s_add_u32 s4, s4, 0x100
	s_addc_u32 s5, s5, 0
	s_add_u32 s21, s21, 0x100
	s_addc_u32 s27, s27, 0
	s_cmp_gt_u32 s81, 29
	s_cbranch_scc0 .LBB0_602
	s_and_b64 vcc, exec, s[14:15]
	s_cbranch_vccz .LBB0_605
	s_barrier

; #define PG8_STAGE(bufoff, gbase, voff) do { _Pragma("unroll") for (int _i = 0; _i < 2; ++_i) \
;         __builtin_amdgcn_global_load_lds((const unsigned*)((const char*)(gbase) + (voff)[_i]), (PG8_LAS unsigned*)(lds + (bufoff) + ldsw + _i * 8192), 16, 0, 0); } while (0)
; #define PG8_LDA(dst, b, h) do { _Pragma("unroll") for (int m = 0; m < 4; ++m) _Pragma("unroll") for (int k = 0; k < 2; ++k) dst[m][k] = *(const PG8_LAS bf16x8*)(lds + PG8_SA(b, h) + aoff + m * 2048 + k * 1024); } while (0)
; #define PG8_LDB(dst, b, h) do { _Pragma("unroll") for (int n = 0; n < 2; ++n) _Pragma("unroll") for (int k = 0; k < 2; ++k) dst[n][k] = *(const PG8_LAS bf16x8*)(lds + PG8_SB(b, h) + boff + n * 2048 + k * 1024); } while (0)
; #define PG8_MMA(ai, bj, At, Bt) do { __builtin_amdgcn_s_setprio(1); _Pragma("unroll") for (int m = 0; m < 4; ++m) _Pragma("unroll") for (int n = 0; n < 2; ++n) _Pragma("unroll") for (int k = 0; k < 2; ++k) \
;         acc[ai][bj][m][n] = __builtin_amdgcn_mfma_f32_16x16x32_bf16(Bt[n][k], At[m][k], acc[ai][bj][m][n], 0, 0, 0); __builtin_amdgcn_s_setprio(0); } while (0)
; #define PG8_WAIT_V(n) asm volatile("s_waitcnt vmcnt(" #n ")" ::: "memory")
; #define PG8_BAR __builtin_amdgcn_s_barrier()
; template <class Epi, class Sched, bool ALIGN_EPI = false, bool SP2 = false>
; __device__ __forceinline__ void gemm_phase(PG8_LAS unsigned char* lds, const Gemm g, const Sched& S, const Epi& E, int wave_s) {
;     ...
;         const bool has_next = S.next(ui + 1, nxt);
;         const char* nA = has_next ? (const char*)g.A + (size_t)nxt.pm * tstepA + (size_t)(nxt.pn / g.npg) * (size_t)(K * 2) : cA; const char* nB = has_next ? (const char*)g.Bt + (size_t)nxt.pn * tstepB : cB;
;         for (int t = 0; t < nt; t += 2) {
;             const bool last = (t == nt - 2);
;             const char* a1 = cA + (size_t)(t + 1) * kstep;
;             const char* a2 = last ? nA : cA + (size_t)(t + 2) * kstep; const char* b2 = last ? nB : cB + (size_t)(t + 2) * kstep;
;             const char* a3 = a2 + kstep; const char* b3 = b2 + kstep;
;             if (last && has_next) S.a_ready(nxt);
;             if constexpr (SP2) {
;             PG8_LDB(B0, 0, 0); PG8_LDB(B1, 0, 1); PG8_SCHED; PG8_LDA(At, 0, 0); PG8_STAGE(PG8_SA(1, 1), a1 + hstepA, voffA);
;             PG8_WAIT_V(8); PG8_WAIT_L(0); PG8_BAR; PG8_MMA(0, 0, At, B0); PG8_MMA(0, 1, At, B1); PG8_BAR; PG8_SCHED;
.LBB0_690:
	s_ashr_i32 s89, s88, 31
	s_lshl_b64 s[2:3], s[88:89], 20
	s_add_u32 s28, s22, s2
	s_addc_u32 s29, s23, s3
	s_and_b64 s[2:3], s[4:5], exec
	s_cselect_b32 s2, s29, s41
	s_cselect_b32 s3, s28, s40
	s_add_u32 s89, s40, 0x100
	s_addc_u32 s91, s41, 0
	s_mov_b32 vcc_lo, -2
	s_add_u32 s4, s30, 0x100
	s_addc_u32 s5, s31, 0
	s_add_i32 vcc_hi, 0, 0x10000
	s_cmp_eq_u32 vcc_lo, 28
	s_cselect_b32 s41, s21, s5
	s_cselect_b32 s40, s20, s4
	s_cselect_b32 s7, s2, s91
	s_cselect_b32 s6, s3, s89
	s_add_i32 s86, 0, 0x14000
	v_add_u32_e32 v142, vcc_hi, v251
	v_add_u32_e32 v158, s86, v251
	ds_read_b128 v[126:129], v142
	ds_read_b128 v[134:137], v142 offset:1024
	ds_read_b128 v[138:141], v142 offset:2048
	ds_read_b128 v[142:145], v142 offset:3072
	ds_read_b128 v[146:149], v158
	ds_read_b128 v[150:153], v158 offset:1024
	ds_read_b128 v[154:157], v158 offset:2048
	ds_read_b128 v[158:161], v158 offset:3072
	v_lshl_add_u64 v[194:195], s[30:31], 0, v[244:245]
	s_add_i32 m0, s36, 0xc000
	ds_read_b128 v[162:165], v252
	ds_read_b128 v[166:169], v252 offset:1024
	ds_read_b128 v[170:173], v252 offset:2048
	ds_read_b128 v[174:177], v252 offset:3072
	ds_read_b128 v[178:181], v252 offset:4096
	ds_read_b128 v[182:185], v252 offset:5120
	ds_read_b128 v[186:189], v252 offset:6144
	ds_read_b128 v[190:193], v252 offset:7168
	global_load_lds_dwordx4 v[194:195], off
	v_lshl_add_u64 v[194:195], s[30:31], 0, v[246:247]
	s_add_i32 m0, s36, 0xe000
	s_nop 0
	global_load_lds_dwordx4 v[194:195], off
	s_waitcnt vmcnt(8)
	s_waitcnt lgkmcnt(0)
	s_barrier
	v_mfma_f32_16x16x32_bf16 v[130:133], v[126:129], v[162:165], 0
	v_mfma_f32_16x16x32_bf16 v[118:121], v[138:141], v[162:165], 0
	v_mfma_f32_16x16x32_bf16 v[110:113], v[126:129], v[170:173], 0
	v_mfma_f32_16x16x32_bf16 v[98:101], v[138:141], v[170:173], 0
	v_mfma_f32_16x16x32_bf16 v[62:65], v[126:129], v[178:181], 0
	v_mfma_f32_16x16x32_bf16 v[58:61], v[138:141], v[178:181], 0
	v_mfma_f32_16x16x32_bf16 v[46:49], v[126:129], v[186:189], 0
	v_mfma_f32_16x16x32_bf16 v[42:45], v[138:141], v[186:189], 0
	v_mfma_f32_16x16x32_bf16 v[130:133], v[134:137], v[166:169], v[130:133]
	v_mfma_f32_16x16x32_bf16 v[118:121], v[142:145], v[166:169], v[118:121]
	v_mfma_f32_16x16x32_bf16 v[110:113], v[134:137], v[174:177], v[110:113]
	v_mfma_f32_16x16x32_bf16 v[98:101], v[142:145], v[174:177], v[98:101]
	v_mfma_f32_16x16x32_bf16 v[62:65], v[134:137], v[182:185], v[62:65]
	v_mfma_f32_16x16x32_bf16 v[58:61], v[142:145], v[182:185], v[58:61]
	v_mfma_f32_16x16x32_bf16 v[46:49], v[134:137], v[190:193], v[46:49]
	v_mfma_f32_16x16x32_bf16 v[42:45], v[142:145], v[190:193], v[42:45]
	v_mfma_f32_16x16x32_bf16 v[102:105], v[146:149], v[162:165], 0
	v_mfma_f32_16x16x32_bf16 v[74:77], v[154:157], v[162:165], 0
	v_mfma_f32_16x16x32_bf16 v[78:81], v[146:149], v[170:173], 0
	v_mfma_f32_16x16x32_bf16 v[90:93], v[154:157], v[170:173], 0
	v_mfma_f32_16x16x32_bf16 v[34:37], v[146:149], v[178:181], 0
	v_mfma_f32_16x16x32_bf16 v[26:29], v[154:157], v[178:181], 0
	v_mfma_f32_16x16x32_bf16 v[14:17], v[146:149], v[186:189], 0
	v_mfma_f32_16x16x32_bf16 v[2:5], v[154:157], v[186:189], 0
	v_mfma_f32_16x16x32_bf16 v[102:105], v[150:153], v[166:169], v[102:105]
	v_mfma_f32_16x16x32_bf16 v[74:77], v[158:161], v[166:169], v[74:77]
	v_mfma_f32_16x16x32_bf16 v[78:81], v[150:153], v[174:177], v[78:81]
	v_mfma_f32_16x16x32_bf16 v[90:93], v[158:161], v[174:177], v[90:93]
	v_mfma_f32_16x16x32_bf16 v[34:37], v[150:153], v[182:185], v[34:37]
	v_mfma_f32_16x16x32_bf16 v[26:29], v[158:161], v[182:185], v[26:29]
	v_mfma_f32_16x16x32_bf16 v[14:17], v[150:153], v[190:193], v[14:17]
	v_mfma_f32_16x16x32_bf16 v[2:5], v[158:161], v[190:193], v[2:5]
	s_barrier
	s_add_i32 s30, vcc_hi, s35
	v_lshl_add_u64 v[194:195], s[6:7], 0, v[238:239]
	s_mov_b32 m0, s30
	ds_read_b128 v[162:165], v252 offset:16384
	ds_read_b128 v[166:169], v252 offset:17408
	ds_read_b128 v[170:173], v252 offset:18432
	ds_read_b128 v[174:177], v252 offset:19456
	ds_read_b128 v[178:181], v252 offset:20480
	ds_read_b128 v[182:185], v252 offset:21504
	ds_read_b128 v[186:189], v252 offset:22528
	ds_read_b128 v[190:193], v252 offset:23552
	global_load_lds_dwordx4 v[194:195], off
	s_add_i32 m0, s30, 0x2000
	s_add_u32 s30, s6, 0x80000
	v_lshl_add_u64 v[196:197], s[6:7], 0, v[242:243]
	s_addc_u32 s31, s7, 0
	s_add_i32 s86, s86, s35
	global_load_lds_dwordx4 v[196:197], off
	v_lshl_add_u64 v[198:199], s[30:31], 0, v[238:239]
	s_mov_b32 m0, s86
	v_lshl_add_u64 v[200:201], s[40:41], 0, v[240:241]
	global_load_lds_dwordx4 v[198:199], off
	v_lshl_add_u64 v[198:199], s[30:31], 0, v[242:243]
	s_add_i32 m0, s86, 0x2000
	s_nop 0
	global_load_lds_dwordx4 v[198:199], off
	v_lshl_add_u64 v[198:199], s[40:41], 0, v[236:237]
	s_mov_b32 m0, s36
	s_nop 0
	global_load_lds_dwordx4 v[198:199], off
	s_mov_b32 m0, s37
	s_nop 0
	global_load_lds_dwordx4 v[200:201], off
	s_waitcnt vmcnt(8)
	s_waitcnt lgkmcnt(0)
	s_barrier
; #define PG8_STAGE(bufoff, gbase, voff) do { _Pragma("unroll") for (int _i = 0; _i < 2; ++_i) \
;         __builtin_amdgcn_global_load_lds((const unsigned*)((const char*)(gbase) + (voff)[_i]), (PG8_LAS unsigned*)(lds + (bufoff) + ldsw + _i * 8192), 16, 0, 0); } while (0)
; #define PG8_LDA(dst, b, h) do { _Pragma("unroll") for (int m = 0; m < 4; ++m) _Pragma("unroll") for (int k = 0; k < 2; ++k) dst[m][k] = *(const PG8_LAS bf16x8*)(lds + PG8_SA(b, h) + aoff + m * 2048 + k * 1024); } while (0)
; #define PG8_LDB(dst, b, h) do { _Pragma("unroll") for (int n = 0; n < 2; ++n) _Pragma("unroll") for (int k = 0; k < 2; ++k) dst[n][k] = *(const PG8_LAS bf16x8*)(lds + PG8_SB(b, h) + boff + n * 2048 + k * 1024); } while (0)
; #define PG8_MMA(ai, bj, At, Bt) do { __builtin_amdgcn_s_setprio(1); _Pragma("unroll") for (int m = 0; m < 4; ++m) _Pragma("unroll") for (int n = 0; n < 2; ++n) _Pragma("unroll") for (int k = 0; k < 2; ++k) \
;         acc[ai][bj][m][n] = __builtin_amdgcn_mfma_f32_16x16x32_bf16(Bt[n][k], At[m][k], acc[ai][bj][m][n], 0, 0, 0); __builtin_amdgcn_s_setprio(0); } while (0)
; #define PG8_WAIT_V(n) asm volatile("s_waitcnt vmcnt(" #n ")" ::: "memory")
; #define PG8_WAIT_L(n) asm volatile("s_waitcnt lgkmcnt(" #n ")" ::: "memory")
; #define PG8_BAR __builtin_amdgcn_s_barrier()
; #define PG8_SCHED __builtin_amdgcn_sched_barrier(0)
; template <class Epi, class Sched, bool ALIGN_EPI = false, bool SP2 = false>
; __device__ __forceinline__ void gemm_phase(PG8_LAS unsigned char* lds, const Gemm g, const Sched& S, const Epi& E, int wave_s) {
;     ...
;             PG8_LDA(At, 0, 1); PG8_STAGE(PG8_SB(0, 0), b2, voffB); PG8_STAGE(PG8_SB(0, 1), b2 + hstepB, voffB); PG8_STAGE(PG8_SA(0, 0), a2, voffA);
;             PG8_WAIT_V(8); PG8_WAIT_L(0); PG8_BAR; PG8_MMA(1, 0, At, B0); PG8_MMA(1, 1, At, B1); PG8_BAR; PG8_SCHED;
;             PG8_LDB(B0, 1, 0); PG8_LDB(B1, 1, 1); PG8_SCHED; PG8_LDA(At, 1, 0); PG8_STAGE(PG8_SA(0, 1), a2 + hstepA, voffA);
;             PG8_WAIT_V(8); PG8_WAIT_L(0); PG8_BAR; PG8_MMA(0, 0, At, B0); PG8_MMA(0, 1, At, B1); PG8_BAR; PG8_SCHED;
	v_mfma_f32_16x16x32_bf16 v[54:57], v[126:129], v[162:165], 0
	v_mfma_f32_16x16x32_bf16 v[50:53], v[138:141], v[162:165], 0
	v_mfma_f32_16x16x32_bf16 v[38:41], v[126:129], v[170:173], 0
	v_mfma_f32_16x16x32_bf16 v[30:33], v[138:141], v[170:173], 0
	v_mfma_f32_16x16x32_bf16 v[86:89], v[126:129], v[178:181], 0
	v_mfma_f32_16x16x32_bf16 v[122:125], v[138:141], v[178:181], 0
	v_mfma_f32_16x16x32_bf16 v[114:117], v[126:129], v[186:189], 0
	v_mfma_f32_16x16x32_bf16 v[106:109], v[138:141], v[186:189], 0
	v_mfma_f32_16x16x32_bf16 v[54:57], v[134:137], v[166:169], v[54:57]
	v_mfma_f32_16x16x32_bf16 v[50:53], v[142:145], v[166:169], v[50:53]
	v_mfma_f32_16x16x32_bf16 v[38:41], v[134:137], v[174:177], v[38:41]
	v_mfma_f32_16x16x32_bf16 v[30:33], v[142:145], v[174:177], v[30:33]
	v_mfma_f32_16x16x32_bf16 v[86:89], v[134:137], v[182:185], v[86:89]
	v_mfma_f32_16x16x32_bf16 v[122:125], v[142:145], v[182:185], v[122:125]
	v_mfma_f32_16x16x32_bf16 v[114:117], v[134:137], v[190:193], v[114:117]
	v_mfma_f32_16x16x32_bf16 v[106:109], v[142:145], v[190:193], v[106:109]
	v_mfma_f32_16x16x32_bf16 v[22:25], v[146:149], v[162:165], 0
	v_mfma_f32_16x16x32_bf16 v[18:21], v[154:157], v[162:165], 0
	v_mfma_f32_16x16x32_bf16 v[10:13], v[146:149], v[170:173], 0
	v_mfma_f32_16x16x32_bf16 v[6:9], v[154:157], v[170:173], 0
	v_mfma_f32_16x16x32_bf16 v[82:85], v[146:149], v[178:181], 0
	v_mfma_f32_16x16x32_bf16 v[94:97], v[154:157], v[178:181], 0
	v_mfma_f32_16x16x32_bf16 v[70:73], v[146:149], v[186:189], 0
	v_mfma_f32_16x16x32_bf16 v[66:69], v[154:157], v[186:189], 0
	v_mfma_f32_16x16x32_bf16 v[22:25], v[150:153], v[166:169], v[22:25]
	v_mfma_f32_16x16x32_bf16 v[18:21], v[158:161], v[166:169], v[18:21]
	v_mfma_f32_16x16x32_bf16 v[10:13], v[150:153], v[174:177], v[10:13]
	v_mfma_f32_16x16x32_bf16 v[6:9], v[158:161], v[174:177], v[6:9]
	v_mfma_f32_16x16x32_bf16 v[82:85], v[150:153], v[182:185], v[82:85]
	v_mfma_f32_16x16x32_bf16 v[94:97], v[158:161], v[182:185], v[94:97]
	v_mfma_f32_16x16x32_bf16 v[70:73], v[150:153], v[190:193], v[70:73]
	v_mfma_f32_16x16x32_bf16 v[66:69], v[158:161], v[190:193], v[66:69]
	s_barrier
	s_add_i32 s86, 0, 0x18000
	s_add_i32 s87, 0, 0x1c000
	v_add_u32_e32 v142, s86, v251
	v_add_u32_e32 v158, s87, v251
	ds_read_b128 v[126:129], v142
	ds_read_b128 v[134:137], v142 offset:1024
	ds_read_b128 v[138:141], v142 offset:2048
	ds_read_b128 v[142:145], v142 offset:3072
	ds_read_b128 v[146:149], v158
	ds_read_b128 v[150:153], v158 offset:1024
	ds_read_b128 v[154:157], v158 offset:2048
	ds_read_b128 v[158:161], v158 offset:3072
	s_add_u32 s30, s40, 0x4000
	s_addc_u32 s31, s41, 0
	s_mov_b32 m0, s42
	v_lshl_add_u64 v[202:203], s[30:31], 0, v[236:237]
	ds_read_b128 v[162:165], v252 offset:32768
	ds_read_b128 v[166:169], v252 offset:33792
	ds_read_b128 v[170:173], v252 offset:34816
	ds_read_b128 v[174:177], v252 offset:35840
	ds_read_b128 v[178:181], v252 offset:36864
	ds_read_b128 v[182:185], v252 offset:37888
	ds_read_b128 v[186:189], v252 offset:38912
	ds_read_b128 v[190:193], v252 offset:39936
	global_load_lds_dwordx4 v[202:203], off
	v_lshl_add_u64 v[202:203], s[30:31], 0, v[240:241]
	s_mov_b32 m0, s43
	s_nop 0
	global_load_lds_dwordx4 v[202:203], off
	s_waitcnt vmcnt(8)
	s_waitcnt lgkmcnt(0)
	s_barrier
	v_mfma_f32_16x16x32_bf16 v[130:133], v[126:129], v[162:165], v[130:133]
	v_mfma_f32_16x16x32_bf16 v[118:121], v[138:141], v[162:165], v[118:121]
	v_mfma_f32_16x16x32_bf16 v[110:113], v[126:129], v[170:173], v[110:113]
	v_mfma_f32_16x16x32_bf16 v[98:101], v[138:141], v[170:173], v[98:101]
	v_mfma_f32_16x16x32_bf16 v[62:65], v[126:129], v[178:181], v[62:65]
	v_mfma_f32_16x16x32_bf16 v[58:61], v[138:141], v[178:181], v[58:61]
	v_mfma_f32_16x16x32_bf16 v[46:49], v[126:129], v[186:189], v[46:49]
	v_mfma_f32_16x16x32_bf16 v[42:45], v[138:141], v[186:189], v[42:45]
	v_mfma_f32_16x16x32_bf16 v[130:133], v[134:137], v[166:169], v[130:133]
	v_mfma_f32_16x16x32_bf16 v[118:121], v[142:145], v[166:169], v[118:121]
	v_mfma_f32_16x16x32_bf16 v[110:113], v[134:137], v[174:177], v[110:113]
	v_mfma_f32_16x16x32_bf16 v[98:101], v[142:145], v[174:177], v[98:101]
	v_mfma_f32_16x16x32_bf16 v[62:65], v[134:137], v[182:185], v[62:65]
	v_mfma_f32_16x16x32_bf16 v[58:61], v[142:145], v[182:185], v[58:61]
	v_mfma_f32_16x16x32_bf16 v[46:49], v[134:137], v[190:193], v[46:49]
	v_mfma_f32_16x16x32_bf16 v[42:45], v[142:145], v[190:193], v[42:45]
	v_mfma_f32_16x16x32_bf16 v[102:105], v[146:149], v[162:165], v[102:105]
	v_mfma_f32_16x16x32_bf16 v[74:77], v[154:157], v[162:165], v[74:77]
	v_mfma_f32_16x16x32_bf16 v[78:81], v[146:149], v[170:173], v[78:81]
	v_mfma_f32_16x16x32_bf16 v[90:93], v[154:157], v[170:173], v[90:93]
	v_mfma_f32_16x16x32_bf16 v[34:37], v[146:149], v[178:181], v[34:37]
	v_mfma_f32_16x16x32_bf16 v[26:29], v[154:157], v[178:181], v[26:29]
	v_mfma_f32_16x16x32_bf16 v[14:17], v[146:149], v[186:189], v[14:17]
	v_mfma_f32_16x16x32_bf16 v[2:5], v[154:157], v[186:189], v[2:5]
	v_mfma_f32_16x16x32_bf16 v[102:105], v[150:153], v[166:169], v[102:105]
	v_mfma_f32_16x16x32_bf16 v[74:77], v[158:161], v[166:169], v[74:77]
	v_mfma_f32_16x16x32_bf16 v[78:81], v[150:153], v[174:177], v[78:81]
	v_mfma_f32_16x16x32_bf16 v[90:93], v[158:161], v[174:177], v[90:93]
	v_mfma_f32_16x16x32_bf16 v[34:37], v[150:153], v[182:185], v[34:37]
	v_mfma_f32_16x16x32_bf16 v[26:29], v[158:161], v[182:185], v[26:29]
	v_mfma_f32_16x16x32_bf16 v[14:17], v[150:153], v[190:193], v[14:17]
	v_mfma_f32_16x16x32_bf16 v[2:5], v[158:161], v[190:193], v[2:5]
	s_barrier
; #define PG8_STAGE(bufoff, gbase, voff) do { _Pragma("unroll") for (int _i = 0; _i < 2; ++_i) \
;         __builtin_amdgcn_global_load_lds((const unsigned*)((const char*)(gbase) + (voff)[_i]), (PG8_LAS unsigned*)(lds + (bufoff) + ldsw + _i * 8192), 16, 0, 0); } while (0)
; #define PG8_LDA(dst, b, h) do { _Pragma("unroll") for (int m = 0; m < 4; ++m) _Pragma("unroll") for (int k = 0; k < 2; ++k) dst[m][k] = *(const PG8_LAS bf16x8*)(lds + PG8_SA(b, h) + aoff + m * 2048 + k * 1024); } while (0)
; #define PG8_LDB(dst, b, h) do { _Pragma("unroll") for (int n = 0; n < 2; ++n) _Pragma("unroll") for (int k = 0; k < 2; ++k) dst[n][k] = *(const PG8_LAS bf16x8*)(lds + PG8_SB(b, h) + boff + n * 2048 + k * 1024); } while (0)
; #define PG8_WAIT_V(n) asm volatile("s_waitcnt vmcnt(" #n ")" ::: "memory")
; #define PG8_WAIT_L(n) asm volatile("s_waitcnt lgkmcnt(" #n ")" ::: "memory")
; #define PG8_BAR __builtin_amdgcn_s_barrier()
; #define PG8_SCHED __builtin_amdgcn_sched_barrier(0)
; template <class Epi, class Sched, bool ALIGN_EPI = false, bool SP2 = false>
; __device__ __forceinline__ void gemm_phase(PG8_LAS unsigned char* lds, const Gemm g, const Sched& S, const Epi& E, int wave_s) {
;     ...
;         for (int t = 0; t < nt; t += 2) {
;             const bool last = (t == nt - 2);
;             const char* a1 = cA + (size_t)(t + 1) * kstep;
;             const char* a2 = last ? nA : cA + (size_t)(t + 2) * kstep; const char* b2 = last ? nB : cB + (size_t)(t + 2) * kstep;
;             const char* a3 = a2 + kstep; const char* b3 = b2 + kstep;
;             if (last && has_next) S.a_ready(nxt);
;             if constexpr (SP2) {
;             PG8_LDB(B0, 0, 0); PG8_LDB(B1, 0, 1); PG8_SCHED; PG8_LDA(At, 0, 0); PG8_STAGE(PG8_SA(1, 1), a1 + hstepA, voffA);
;             PG8_WAIT_V(8); PG8_WAIT_L(0); PG8_BAR; PG8_MMA(0, 0, At, B0); PG8_MMA(0, 1, At, B1); PG8_BAR; PG8_SCHED;
;             PG8_LDA(At, 0, 1); PG8_STAGE(PG8_SB(0, 0), b2, voffB); PG8_STAGE(PG8_SB(0, 1), b2 + hstepB, voffB); PG8_STAGE(PG8_SA(0, 0), a2, voffA);
;     ...
;             PG8_LDA(At, 1, 1); PG8_STAGE(PG8_SB(1, 0), b3, voffB); PG8_STAGE(PG8_SB(1, 1), b3 + hstepB, voffB); PG8_STAGE(PG8_SA(1, 0), a3, voffA);
;             PG8_WAIT_V(8); PG8_WAIT_L(0); PG8_BAR; PG8_MMA(1, 0, At, B0); PG8_MMA(1, 1, At, B1); PG8_BAR; PG8_SCHED;
	s_add_i32 s30, s86, s35
	v_lshl_add_u64 v[194:195], v[194:195], 0, s[60:61]
	s_mov_b32 m0, s30
	ds_read_b128 v[162:165], v252 offset:49152
	ds_read_b128 v[166:169], v252 offset:50176
	ds_read_b128 v[170:173], v252 offset:51200
	ds_read_b128 v[174:177], v252 offset:52224
	ds_read_b128 v[178:181], v252 offset:53248
	ds_read_b128 v[182:185], v252 offset:54272
	ds_read_b128 v[186:189], v252 offset:55296
	ds_read_b128 v[190:193], v252 offset:56320
	global_load_lds_dwordx4 v[194:195], off
	s_add_i32 m0, s30, 0x2000
	s_add_u32 s6, s6, 0x80080
	v_lshl_add_u64 v[194:195], v[196:197], 0, s[60:61]
	s_addc_u32 s7, s7, 0
	s_add_i32 s30, s87, s35
	global_load_lds_dwordx4 v[194:195], off
	v_lshl_add_u64 v[194:195], s[6:7], 0, v[238:239]
	s_mov_b32 m0, s30
	s_nop 0
	global_load_lds_dwordx4 v[194:195], off
	v_lshl_add_u64 v[194:195], s[6:7], 0, v[242:243]
	s_add_i32 m0, s30, 0x2000
	s_nop 0
	global_load_lds_dwordx4 v[194:195], off
	v_lshl_add_u64 v[194:195], v[198:199], 0, s[60:61]
	s_mov_b32 m0, s77
	s_nop 0
	global_load_lds_dwordx4 v[194:195], off
	v_lshl_add_u64 v[194:195], v[200:201], 0, s[60:61]
	s_mov_b32 m0, s94
	s_nop 0
	global_load_lds_dwordx4 v[194:195], off
	s_waitcnt vmcnt(8)
	s_waitcnt lgkmcnt(0)
	s_barrier
	v_mfma_f32_16x16x32_bf16 v[54:57], v[126:129], v[162:165], v[54:57]
	v_mfma_f32_16x16x32_bf16 v[50:53], v[138:141], v[162:165], v[50:53]
	v_mfma_f32_16x16x32_bf16 v[38:41], v[126:129], v[170:173], v[38:41]
	v_mfma_f32_16x16x32_bf16 v[30:33], v[138:141], v[170:173], v[30:33]
	v_mfma_f32_16x16x32_bf16 v[86:89], v[126:129], v[178:181], v[86:89]
	v_mfma_f32_16x16x32_bf16 v[122:125], v[138:141], v[178:181], v[122:125]
	v_mfma_f32_16x16x32_bf16 v[114:117], v[126:129], v[186:189], v[114:117]
	v_mfma_f32_16x16x32_bf16 v[106:109], v[138:141], v[186:189], v[106:109]
	v_mfma_f32_16x16x32_bf16 v[54:57], v[134:137], v[166:169], v[54:57]
	v_mfma_f32_16x16x32_bf16 v[50:53], v[142:145], v[166:169], v[50:53]
	v_mfma_f32_16x16x32_bf16 v[38:41], v[134:137], v[174:177], v[38:41]
	v_mfma_f32_16x16x32_bf16 v[30:33], v[142:145], v[174:177], v[30:33]
	v_mfma_f32_16x16x32_bf16 v[86:89], v[134:137], v[182:185], v[86:89]
	v_mfma_f32_16x16x32_bf16 v[122:125], v[142:145], v[182:185], v[122:125]
	v_mfma_f32_16x16x32_bf16 v[114:117], v[134:137], v[190:193], v[114:117]
	v_mfma_f32_16x16x32_bf16 v[106:109], v[142:145], v[190:193], v[106:109]
	v_mfma_f32_16x16x32_bf16 v[22:25], v[146:149], v[162:165], v[22:25]
	v_mfma_f32_16x16x32_bf16 v[18:21], v[154:157], v[162:165], v[18:21]
	v_mfma_f32_16x16x32_bf16 v[10:13], v[146:149], v[170:173], v[10:13]
	v_mfma_f32_16x16x32_bf16 v[6:9], v[154:157], v[170:173], v[6:9]
	v_mfma_f32_16x16x32_bf16 v[82:85], v[146:149], v[178:181], v[82:85]
	v_mfma_f32_16x16x32_bf16 v[94:97], v[154:157], v[178:181], v[94:97]
	v_mfma_f32_16x16x32_bf16 v[70:73], v[146:149], v[186:189], v[70:73]
	v_mfma_f32_16x16x32_bf16 v[66:69], v[154:157], v[186:189], v[66:69]
	v_mfma_f32_16x16x32_bf16 v[22:25], v[150:153], v[166:169], v[22:25]
	v_mfma_f32_16x16x32_bf16 v[18:21], v[158:161], v[166:169], v[18:21]
	v_mfma_f32_16x16x32_bf16 v[10:13], v[150:153], v[174:177], v[10:13]
	v_mfma_f32_16x16x32_bf16 v[6:9], v[158:161], v[174:177], v[6:9]
	v_mfma_f32_16x16x32_bf16 v[82:85], v[150:153], v[182:185], v[82:85]
	v_mfma_f32_16x16x32_bf16 v[94:97], v[158:161], v[182:185], v[94:97]
	v_mfma_f32_16x16x32_bf16 v[70:73], v[150:153], v[190:193], v[70:73]
	v_mfma_f32_16x16x32_bf16 v[66:69], v[158:161], v[190:193], v[66:69]
	s_barrier
	s_add_i32 vcc_lo, vcc_lo, 2
	s_add_u32 s89, s89, 0x100
	s_addc_u32 s91, s91, 0
	s_cmp_gt_u32 vcc_lo, 29
	s_mov_b64 s[30:31], s[4:5]
.LBB0_691:
	s_add_u32 s4, s30, 0x100
	s_addc_u32 s5, s31, 0
	s_add_i32 vcc_hi, 0, 0x10000
	s_cmp_eq_u32 vcc_lo, 28
	s_cselect_b32 s41, s21, s5
	s_cselect_b32 s40, s20, s4
	s_cselect_b32 s7, s2, s91
	s_cselect_b32 s6, s3, s89
	s_add_i32 s86, 0, 0x14000
	v_add_u32_e32 v142, vcc_hi, v251
	v_add_u32_e32 v158, s86, v251
	ds_read_b128 v[126:129], v142
	ds_read_b128 v[134:137], v142 offset:1024
	ds_read_b128 v[138:141], v142 offset:2048
	ds_read_b128 v[142:145], v142 offset:3072
	ds_read_b128 v[146:149], v158
	ds_read_b128 v[150:153], v158 offset:1024
	ds_read_b128 v[154:157], v158 offset:2048
	ds_read_b128 v[158:161], v158 offset:3072
	v_lshl_add_u64 v[194:195], s[30:31], 0, v[244:245]
	s_add_i32 m0, s36, 0xc000
	ds_read_b128 v[162:165], v252
	ds_read_b128 v[166:169], v252 offset:1024
	ds_read_b128 v[170:173], v252 offset:2048
	ds_read_b128 v[174:177], v252 offset:3072
	ds_read_b128 v[178:181], v252 offset:4096
	ds_read_b128 v[182:185], v252 offset:5120
	ds_read_b128 v[186:189], v252 offset:6144
	ds_read_b128 v[190:193], v252 offset:7168
	global_load_lds_dwordx4 v[194:195], off
	v_lshl_add_u64 v[194:195], s[30:31], 0, v[246:247]
	s_add_i32 m0, s36, 0xe000
	s_nop 0
	global_load_lds_dwordx4 v[194:195], off
	s_waitcnt vmcnt(8)
	s_waitcnt lgkmcnt(0)
	s_barrier
; #define PG8_STAGE(bufoff, gbase, voff) do { _Pragma("unroll") for (int _i = 0; _i < 2; ++_i) \
;         __builtin_amdgcn_global_load_lds((const unsigned*)((const char*)(gbase) + (voff)[_i]), (PG8_LAS unsigned*)(lds + (bufoff) + ldsw + _i * 8192), 16, 0, 0); } while (0)
; #define PG8_LDA(dst, b, h) do { _Pragma("unroll") for (int m = 0; m < 4; ++m) _Pragma("unroll") for (int k = 0; k < 2; ++k) dst[m][k] = *(const PG8_LAS bf16x8*)(lds + PG8_SA(b, h) + aoff + m * 2048 + k * 1024); } while (0)
; #define PG8_LDB(dst, b, h) do { _Pragma("unroll") for (int n = 0; n < 2; ++n) _Pragma("unroll") for (int k = 0; k < 2; ++k) dst[n][k] = *(const PG8_LAS bf16x8*)(lds + PG8_SB(b, h) + boff + n * 2048 + k * 1024); } while (0)
; #define PG8_MMA(ai, bj, At, Bt) do { __builtin_amdgcn_s_setprio(1); _Pragma("unroll") for (int m = 0; m < 4; ++m) _Pragma("unroll") for (int n = 0; n < 2; ++n) _Pragma("unroll") for (int k = 0; k < 2; ++k) \
;         acc[ai][bj][m][n] = __builtin_amdgcn_mfma_f32_16x16x32_bf16(Bt[n][k], At[m][k], acc[ai][bj][m][n], 0, 0, 0); __builtin_amdgcn_s_setprio(0); } while (0)
; #define PG8_WAIT_V(n) asm volatile("s_waitcnt vmcnt(" #n ")" ::: "memory")
; #define PG8_WAIT_L(n) asm volatile("s_waitcnt lgkmcnt(" #n ")" ::: "memory")
; #define PG8_BAR __builtin_amdgcn_s_barrier()
; #define PG8_SCHED __builtin_amdgcn_sched_barrier(0)
; template <class Epi, class Sched, bool ALIGN_EPI = false, bool SP2 = false>
; __device__ __forceinline__ void gemm_phase(PG8_LAS unsigned char* lds, const Gemm g, const Sched& S, const Epi& E, int wave_s) {
;     ...
;             PG8_LDB(B0, 0, 0); PG8_LDB(B1, 0, 1); PG8_SCHED; PG8_LDA(At, 0, 0); PG8_STAGE(PG8_SA(1, 1), a1 + hstepA, voffA);
;             PG8_WAIT_V(8); PG8_WAIT_L(0); PG8_BAR; PG8_MMA(0, 0, At, B0); PG8_MMA(0, 1, At, B1); PG8_BAR; PG8_SCHED;
;             PG8_LDA(At, 0, 1); PG8_STAGE(PG8_SB(0, 0), b2, voffB); PG8_STAGE(PG8_SB(0, 1), b2 + hstepB, voffB); PG8_STAGE(PG8_SA(0, 0), a2, voffA);
;             PG8_WAIT_V(8); PG8_WAIT_L(0); PG8_BAR; PG8_MMA(1, 0, At, B0); PG8_MMA(1, 1, At, B1); PG8_BAR; PG8_SCHED;
	v_mfma_f32_16x16x32_bf16 v[130:133], v[126:129], v[162:165], v[130:133]
	v_mfma_f32_16x16x32_bf16 v[118:121], v[138:141], v[162:165], v[118:121]
	v_mfma_f32_16x16x32_bf16 v[110:113], v[126:129], v[170:173], v[110:113]
	v_mfma_f32_16x16x32_bf16 v[98:101], v[138:141], v[170:173], v[98:101]
	v_mfma_f32_16x16x32_bf16 v[62:65], v[126:129], v[178:181], v[62:65]
	v_mfma_f32_16x16x32_bf16 v[58:61], v[138:141], v[178:181], v[58:61]
	v_mfma_f32_16x16x32_bf16 v[46:49], v[126:129], v[186:189], v[46:49]
	v_mfma_f32_16x16x32_bf16 v[42:45], v[138:141], v[186:189], v[42:45]
	v_mfma_f32_16x16x32_bf16 v[130:133], v[134:137], v[166:169], v[130:133]
	v_mfma_f32_16x16x32_bf16 v[118:121], v[142:145], v[166:169], v[118:121]
	v_mfma_f32_16x16x32_bf16 v[110:113], v[134:137], v[174:177], v[110:113]
	v_mfma_f32_16x16x32_bf16 v[98:101], v[142:145], v[174:177], v[98:101]
	v_mfma_f32_16x16x32_bf16 v[62:65], v[134:137], v[182:185], v[62:65]
	v_mfma_f32_16x16x32_bf16 v[58:61], v[142:145], v[182:185], v[58:61]
	v_mfma_f32_16x16x32_bf16 v[46:49], v[134:137], v[190:193], v[46:49]
	v_mfma_f32_16x16x32_bf16 v[42:45], v[142:145], v[190:193], v[42:45]
	v_mfma_f32_16x16x32_bf16 v[102:105], v[146:149], v[162:165], v[102:105]
	v_mfma_f32_16x16x32_bf16 v[74:77], v[154:157], v[162:165], v[74:77]
	v_mfma_f32_16x16x32_bf16 v[78:81], v[146:149], v[170:173], v[78:81]
	v_mfma_f32_16x16x32_bf16 v[90:93], v[154:157], v[170:173], v[90:93]
	v_mfma_f32_16x16x32_bf16 v[34:37], v[146:149], v[178:181], v[34:37]
	v_mfma_f32_16x16x32_bf16 v[26:29], v[154:157], v[178:181], v[26:29]
	v_mfma_f32_16x16x32_bf16 v[14:17], v[146:149], v[186:189], v[14:17]
	v_mfma_f32_16x16x32_bf16 v[2:5], v[154:157], v[186:189], v[2:5]
	v_mfma_f32_16x16x32_bf16 v[102:105], v[150:153], v[166:169], v[102:105]
	v_mfma_f32_16x16x32_bf16 v[74:77], v[158:161], v[166:169], v[74:77]
	v_mfma_f32_16x16x32_bf16 v[78:81], v[150:153], v[174:177], v[78:81]
	v_mfma_f32_16x16x32_bf16 v[90:93], v[158:161], v[174:177], v[90:93]
	v_mfma_f32_16x16x32_bf16 v[34:37], v[150:153], v[182:185], v[34:37]
	v_mfma_f32_16x16x32_bf16 v[26:29], v[158:161], v[182:185], v[26:29]
	v_mfma_f32_16x16x32_bf16 v[14:17], v[150:153], v[190:193], v[14:17]
	v_mfma_f32_16x16x32_bf16 v[2:5], v[158:161], v[190:193], v[2:5]
	s_barrier
	s_add_i32 s30, vcc_hi, s35
	v_lshl_add_u64 v[194:195], s[6:7], 0, v[238:239]
	s_mov_b32 m0, s30
	ds_read_b128 v[162:165], v252 offset:16384
	ds_read_b128 v[166:169], v252 offset:17408
	ds_read_b128 v[170:173], v252 offset:18432
	ds_read_b128 v[174:177], v252 offset:19456
	ds_read_b128 v[178:181], v252 offset:20480
	ds_read_b128 v[182:185], v252 offset:21504
	ds_read_b128 v[186:189], v252 offset:22528
	ds_read_b128 v[190:193], v252 offset:23552
	global_load_lds_dwordx4 v[194:195], off
	s_add_i32 m0, s30, 0x2000
	s_add_u32 s30, s6, 0x80000
	v_lshl_add_u64 v[196:197], s[6:7], 0, v[242:243]
	s_addc_u32 s31, s7, 0
	s_add_i32 s86, s86, s35
	global_load_lds_dwordx4 v[196:197], off
	v_lshl_add_u64 v[198:199], s[30:31], 0, v[238:239]
	s_mov_b32 m0, s86
	v_lshl_add_u64 v[200:201], s[40:41], 0, v[240:241]
	global_load_lds_dwordx4 v[198:199], off
	v_lshl_add_u64 v[198:199], s[30:31], 0, v[242:243]
	s_add_i32 m0, s86, 0x2000
	s_nop 0
	global_load_lds_dwordx4 v[198:199], off
	v_lshl_add_u64 v[198:199], s[40:41], 0, v[236:237]
	s_mov_b32 m0, s36
	s_nop 0
	global_load_lds_dwordx4 v[198:199], off
	s_mov_b32 m0, s37
	s_nop 0
	global_load_lds_dwordx4 v[200:201], off
	s_waitcnt vmcnt(8)
	s_waitcnt lgkmcnt(0)
	s_barrier
	v_mfma_f32_16x16x32_bf16 v[54:57], v[126:129], v[162:165], v[54:57]
	v_mfma_f32_16x16x32_bf16 v[50:53], v[138:141], v[162:165], v[50:53]
	v_mfma_f32_16x16x32_bf16 v[38:41], v[126:129], v[170:173], v[38:41]
	v_mfma_f32_16x16x32_bf16 v[30:33], v[138:141], v[170:173], v[30:33]
	v_mfma_f32_16x16x32_bf16 v[86:89], v[126:129], v[178:181], v[86:89]
	v_mfma_f32_16x16x32_bf16 v[122:125], v[138:141], v[178:181], v[122:125]
	v_mfma_f32_16x16x32_bf16 v[114:117], v[126:129], v[186:189], v[114:117]
	v_mfma_f32_16x16x32_bf16 v[106:109], v[138:141], v[186:189], v[106:109]
	v_mfma_f32_16x16x32_bf16 v[54:57], v[134:137], v[166:169], v[54:57]
	v_mfma_f32_16x16x32_bf16 v[50:53], v[142:145], v[166:169], v[50:53]
	v_mfma_f32_16x16x32_bf16 v[38:41], v[134:137], v[174:177], v[38:41]
	v_mfma_f32_16x16x32_bf16 v[30:33], v[142:145], v[174:177], v[30:33]
	v_mfma_f32_16x16x32_bf16 v[86:89], v[134:137], v[182:185], v[86:89]
	v_mfma_f32_16x16x32_bf16 v[122:125], v[142:145], v[182:185], v[122:125]
	v_mfma_f32_16x16x32_bf16 v[114:117], v[134:137], v[190:193], v[114:117]
	v_mfma_f32_16x16x32_bf16 v[106:109], v[142:145], v[190:193], v[106:109]
	v_mfma_f32_16x16x32_bf16 v[22:25], v[146:149], v[162:165], v[22:25]
	v_mfma_f32_16x16x32_bf16 v[18:21], v[154:157], v[162:165], v[18:21]
	v_mfma_f32_16x16x32_bf16 v[10:13], v[146:149], v[170:173], v[10:13]
	v_mfma_f32_16x16x32_bf16 v[6:9], v[154:157], v[170:173], v[6:9]
	v_mfma_f32_16x16x32_bf16 v[82:85], v[146:149], v[178:181], v[82:85]
	v_mfma_f32_16x16x32_bf16 v[94:97], v[154:157], v[178:181], v[94:97]
	v_mfma_f32_16x16x32_bf16 v[70:73], v[146:149], v[186:189], v[70:73]
	v_mfma_f32_16x16x32_bf16 v[66:69], v[154:157], v[186:189], v[66:69]
	v_mfma_f32_16x16x32_bf16 v[22:25], v[150:153], v[166:169], v[22:25]
	v_mfma_f32_16x16x32_bf16 v[18:21], v[158:161], v[166:169], v[18:21]
	v_mfma_f32_16x16x32_bf16 v[10:13], v[150:153], v[174:177], v[10:13]
	v_mfma_f32_16x16x32_bf16 v[6:9], v[158:161], v[174:177], v[6:9]
	v_mfma_f32_16x16x32_bf16 v[82:85], v[150:153], v[182:185], v[82:85]
	v_mfma_f32_16x16x32_bf16 v[94:97], v[158:161], v[182:185], v[94:97]
	v_mfma_f32_16x16x32_bf16 v[70:73], v[150:153], v[190:193], v[70:73]
	v_mfma_f32_16x16x32_bf16 v[66:69], v[158:161], v[190:193], v[66:69]
	s_barrier
; #define PG8_STAGE(bufoff, gbase, voff) do { _Pragma("unroll") for (int _i = 0; _i < 2; ++_i) \
;         __builtin_amdgcn_global_load_lds((const unsigned*)((const char*)(gbase) + (voff)[_i]), (PG8_LAS unsigned*)(lds + (bufoff) + ldsw + _i * 8192), 16, 0, 0); } while (0)
; #define PG8_LDA(dst, b, h) do { _Pragma("unroll") for (int m = 0; m < 4; ++m) _Pragma("unroll") for (int k = 0; k < 2; ++k) dst[m][k] = *(const PG8_LAS bf16x8*)(lds + PG8_SA(b, h) + aoff + m * 2048 + k * 1024); } while (0)
; #define PG8_LDB(dst, b, h) do { _Pragma("unroll") for (int n = 0; n < 2; ++n) _Pragma("unroll") for (int k = 0; k < 2; ++k) dst[n][k] = *(const PG8_LAS bf16x8*)(lds + PG8_SB(b, h) + boff + n * 2048 + k * 1024); } while (0)
; #define PG8_MMA(ai, bj, At, Bt) do { __builtin_amdgcn_s_setprio(1); _Pragma("unroll") for (int m = 0; m < 4; ++m) _Pragma("unroll") for (int n = 0; n < 2; ++n) _Pragma("unroll") for (int k = 0; k < 2; ++k) \
;         acc[ai][bj][m][n] = __builtin_amdgcn_mfma_f32_16x16x32_bf16(Bt[n][k], At[m][k], acc[ai][bj][m][n], 0, 0, 0); __builtin_amdgcn_s_setprio(0); } while (0)
; #define PG8_WAIT_V(n) asm volatile("s_waitcnt vmcnt(" #n ")" ::: "memory")
; #define PG8_WAIT_L(n) asm volatile("s_waitcnt lgkmcnt(" #n ")" ::: "memory")
; #define PG8_BAR __builtin_amdgcn_s_barrier()
; #define PG8_SCHED __builtin_amdgcn_sched_barrier(0)
; template <class Epi, class Sched, bool ALIGN_EPI = false, bool SP2 = false>
; __device__ __forceinline__ void gemm_phase(PG8_LAS unsigned char* lds, const Gemm g, const Sched& S, const Epi& E, int wave_s) {
;     ...
;             PG8_LDB(B0, 1, 0); PG8_LDB(B1, 1, 1); PG8_SCHED; PG8_LDA(At, 1, 0); PG8_STAGE(PG8_SA(0, 1), a2 + hstepA, voffA);
;             PG8_WAIT_V(8); PG8_WAIT_L(0); PG8_BAR; PG8_MMA(0, 0, At, B0); PG8_MMA(0, 1, At, B1); PG8_BAR; PG8_SCHED;
	s_add_i32 s86, 0, 0x18000
	s_add_i32 s87, 0, 0x1c000
	v_add_u32_e32 v142, s86, v251
	v_add_u32_e32 v158, s87, v251
	ds_read_b128 v[126:129], v142
	ds_read_b128 v[134:137], v142 offset:1024
	ds_read_b128 v[138:141], v142 offset:2048
	ds_read_b128 v[142:145], v142 offset:3072
	ds_read_b128 v[146:149], v158
	ds_read_b128 v[150:153], v158 offset:1024
	ds_read_b128 v[154:157], v158 offset:2048
	ds_read_b128 v[158:161], v158 offset:3072
	s_add_u32 s30, s40, 0x4000
	s_addc_u32 s31, s41, 0
	s_mov_b32 m0, s42
	v_lshl_add_u64 v[202:203], s[30:31], 0, v[236:237]
	ds_read_b128 v[162:165], v252 offset:32768
	ds_read_b128 v[166:169], v252 offset:33792
	ds_read_b128 v[170:173], v252 offset:34816
	ds_read_b128 v[174:177], v252 offset:35840
	ds_read_b128 v[178:181], v252 offset:36864
	ds_read_b128 v[182:185], v252 offset:37888
	ds_read_b128 v[186:189], v252 offset:38912
	ds_read_b128 v[190:193], v252 offset:39936
	global_load_lds_dwordx4 v[202:203], off
	v_lshl_add_u64 v[202:203], s[30:31], 0, v[240:241]
	s_mov_b32 m0, s43
	s_nop 0
	global_load_lds_dwordx4 v[202:203], off
	s_waitcnt vmcnt(8)
	s_waitcnt lgkmcnt(0)
	s_barrier
	v_mfma_f32_16x16x32_bf16 v[130:133], v[126:129], v[162:165], v[130:133]
	v_mfma_f32_16x16x32_bf16 v[118:121], v[138:141], v[162:165], v[118:121]
	v_mfma_f32_16x16x32_bf16 v[110:113], v[126:129], v[170:173], v[110:113]
	v_mfma_f32_16x16x32_bf16 v[98:101], v[138:141], v[170:173], v[98:101]
	v_mfma_f32_16x16x32_bf16 v[62:65], v[126:129], v[178:181], v[62:65]
	v_mfma_f32_16x16x32_bf16 v[58:61], v[138:141], v[178:181], v[58:61]
	v_mfma_f32_16x16x32_bf16 v[46:49], v[126:129], v[186:189], v[46:49]
	v_mfma_f32_16x16x32_bf16 v[42:45], v[138:141], v[186:189], v[42:45]
	v_mfma_f32_16x16x32_bf16 v[130:133], v[134:137], v[166:169], v[130:133]
	v_mfma_f32_16x16x32_bf16 v[118:121], v[142:145], v[166:169], v[118:121]
	v_mfma_f32_16x16x32_bf16 v[110:113], v[134:137], v[174:177], v[110:113]
	v_mfma_f32_16x16x32_bf16 v[98:101], v[142:145], v[174:177], v[98:101]
	v_mfma_f32_16x16x32_bf16 v[62:65], v[134:137], v[182:185], v[62:65]
	v_mfma_f32_16x16x32_bf16 v[58:61], v[142:145], v[182:185], v[58:61]
	v_mfma_f32_16x16x32_bf16 v[46:49], v[134:137], v[190:193], v[46:49]
	v_mfma_f32_16x16x32_bf16 v[42:45], v[142:145], v[190:193], v[42:45]
	v_mfma_f32_16x16x32_bf16 v[102:105], v[146:149], v[162:165], v[102:105]
	v_mfma_f32_16x16x32_bf16 v[74:77], v[154:157], v[162:165], v[74:77]
	v_mfma_f32_16x16x32_bf16 v[78:81], v[146:149], v[170:173], v[78:81]
	v_mfma_f32_16x16x32_bf16 v[90:93], v[154:157], v[170:173], v[90:93]
	v_mfma_f32_16x16x32_bf16 v[34:37], v[146:149], v[178:181], v[34:37]
	v_mfma_f32_16x16x32_bf16 v[26:29], v[154:157], v[178:181], v[26:29]
	v_mfma_f32_16x16x32_bf16 v[14:17], v[146:149], v[186:189], v[14:17]
	v_mfma_f32_16x16x32_bf16 v[2:5], v[154:157], v[186:189], v[2:5]
	v_mfma_f32_16x16x32_bf16 v[102:105], v[150:153], v[166:169], v[102:105]
	v_mfma_f32_16x16x32_bf16 v[74:77], v[158:161], v[166:169], v[74:77]
	v_mfma_f32_16x16x32_bf16 v[78:81], v[150:153], v[174:177], v[78:81]
	v_mfma_f32_16x16x32_bf16 v[90:93], v[158:161], v[174:177], v[90:93]
	v_mfma_f32_16x16x32_bf16 v[34:37], v[150:153], v[182:185], v[34:37]
	v_mfma_f32_16x16x32_bf16 v[26:29], v[158:161], v[182:185], v[26:29]
	v_mfma_f32_16x16x32_bf16 v[14:17], v[150:153], v[190:193], v[14:17]
	v_mfma_f32_16x16x32_bf16 v[2:5], v[158:161], v[190:193], v[2:5]
	s_barrier
; #define PG8_STAGE(bufoff, gbase, voff) do { _Pragma("unroll") for (int _i = 0; _i < 2; ++_i) \
;         __builtin_amdgcn_global_load_lds((const unsigned*)((const char*)(gbase) + (voff)[_i]), (PG8_LAS unsigned*)(lds + (bufoff) + ldsw + _i * 8192), 16, 0, 0); } while (0)
; #define PG8_LDA(dst, b, h) do { _Pragma("unroll") for (int m = 0; m < 4; ++m) _Pragma("unroll") for (int k = 0; k < 2; ++k) dst[m][k] = *(const PG8_LAS bf16x8*)(lds + PG8_SA(b, h) + aoff + m * 2048 + k * 1024); } while (0)
; #define PG8_MMA(ai, bj, At, Bt) do { __builtin_amdgcn_s_setprio(1); _Pragma("unroll") for (int m = 0; m < 4; ++m) _Pragma("unroll") for (int n = 0; n < 2; ++n) _Pragma("unroll") for (int k = 0; k < 2; ++k) \
;         acc[ai][bj][m][n] = __builtin_amdgcn_mfma_f32_16x16x32_bf16(Bt[n][k], At[m][k], acc[ai][bj][m][n], 0, 0, 0); __builtin_amdgcn_s_setprio(0); } while (0)
; #define PG8_WAIT_V(n) asm volatile("s_waitcnt vmcnt(" #n ")" ::: "memory")
; #define PG8_WAIT_L(n) asm volatile("s_waitcnt lgkmcnt(" #n ")" ::: "memory")
; #define PG8_BAR __builtin_amdgcn_s_barrier()
; #define PG8_SCHED __builtin_amdgcn_sched_barrier(0)
; template <class Epi, class Sched, bool ALIGN_EPI = false, bool SP2 = false>
; __device__ __forceinline__ void gemm_phase(PG8_LAS unsigned char* lds, const Gemm g, const Sched& S, const Epi& E, int wave_s) {
;     ...
;         for (int t = 0; t < nt; t += 2) {
;             const bool last = (t == nt - 2);
;             const char* a1 = cA + (size_t)(t + 1) * kstep;
;             const char* a2 = last ? nA : cA + (size_t)(t + 2) * kstep; const char* b2 = last ? nB : cB + (size_t)(t + 2) * kstep;
;     ...
;             PG8_LDA(At, 1, 1); PG8_STAGE(PG8_SB(1, 0), b3, voffB); PG8_STAGE(PG8_SB(1, 1), b3 + hstepB, voffB); PG8_STAGE(PG8_SA(1, 0), a3, voffA);
;             PG8_WAIT_V(8); PG8_WAIT_L(0); PG8_BAR; PG8_MMA(1, 0, At, B0); PG8_MMA(1, 1, At, B1); PG8_BAR; PG8_SCHED;
	s_add_i32 s30, s86, s35
	v_lshl_add_u64 v[194:195], v[194:195], 0, s[60:61]
	s_mov_b32 m0, s30
	ds_read_b128 v[162:165], v252 offset:49152
	ds_read_b128 v[166:169], v252 offset:50176
	ds_read_b128 v[170:173], v252 offset:51200
	ds_read_b128 v[174:177], v252 offset:52224
	ds_read_b128 v[178:181], v252 offset:53248
	ds_read_b128 v[182:185], v252 offset:54272
	ds_read_b128 v[186:189], v252 offset:55296
	ds_read_b128 v[190:193], v252 offset:56320
	global_load_lds_dwordx4 v[194:195], off
	s_add_i32 m0, s30, 0x2000
	s_add_u32 s6, s6, 0x80080
	v_lshl_add_u64 v[194:195], v[196:197], 0, s[60:61]
	s_addc_u32 s7, s7, 0
	s_add_i32 s30, s87, s35
	global_load_lds_dwordx4 v[194:195], off
	v_lshl_add_u64 v[194:195], s[6:7], 0, v[238:239]
	s_mov_b32 m0, s30
	s_nop 0
	global_load_lds_dwordx4 v[194:195], off
	v_lshl_add_u64 v[194:195], s[6:7], 0, v[242:243]
	s_add_i32 m0, s30, 0x2000
	s_nop 0
	global_load_lds_dwordx4 v[194:195], off
	v_lshl_add_u64 v[194:195], v[198:199], 0, s[60:61]
	s_mov_b32 m0, s77
	s_nop 0
	global_load_lds_dwordx4 v[194:195], off
	v_lshl_add_u64 v[194:195], v[200:201], 0, s[60:61]
	s_mov_b32 m0, s94
	s_nop 0
	global_load_lds_dwordx4 v[194:195], off
	s_waitcnt vmcnt(8)
	s_waitcnt lgkmcnt(0)
	s_barrier
	v_mfma_f32_16x16x32_bf16 v[54:57], v[126:129], v[162:165], v[54:57]
	v_mfma_f32_16x16x32_bf16 v[50:53], v[138:141], v[162:165], v[50:53]
	v_mfma_f32_16x16x32_bf16 v[38:41], v[126:129], v[170:173], v[38:41]
	v_mfma_f32_16x16x32_bf16 v[30:33], v[138:141], v[170:173], v[30:33]
	v_mfma_f32_16x16x32_bf16 v[86:89], v[126:129], v[178:181], v[86:89]
	v_mfma_f32_16x16x32_bf16 v[122:125], v[138:141], v[178:181], v[122:125]
	v_mfma_f32_16x16x32_bf16 v[114:117], v[126:129], v[186:189], v[114:117]
	v_mfma_f32_16x16x32_bf16 v[106:109], v[138:141], v[186:189], v[106:109]
	v_mfma_f32_16x16x32_bf16 v[54:57], v[134:137], v[166:169], v[54:57]
	v_mfma_f32_16x16x32_bf16 v[50:53], v[142:145], v[166:169], v[50:53]
	v_mfma_f32_16x16x32_bf16 v[38:41], v[134:137], v[174:177], v[38:41]
	v_mfma_f32_16x16x32_bf16 v[30:33], v[142:145], v[174:177], v[30:33]
	v_mfma_f32_16x16x32_bf16 v[86:89], v[134:137], v[182:185], v[86:89]
	v_mfma_f32_16x16x32_bf16 v[122:125], v[142:145], v[182:185], v[122:125]
	v_mfma_f32_16x16x32_bf16 v[114:117], v[134:137], v[190:193], v[114:117]
	v_mfma_f32_16x16x32_bf16 v[106:109], v[142:145], v[190:193], v[106:109]
	v_mfma_f32_16x16x32_bf16 v[22:25], v[146:149], v[162:165], v[22:25]
	v_mfma_f32_16x16x32_bf16 v[18:21], v[154:157], v[162:165], v[18:21]
	v_mfma_f32_16x16x32_bf16 v[10:13], v[146:149], v[170:173], v[10:13]
	v_mfma_f32_16x16x32_bf16 v[6:9], v[154:157], v[170:173], v[6:9]
	v_mfma_f32_16x16x32_bf16 v[82:85], v[146:149], v[178:181], v[82:85]
	v_mfma_f32_16x16x32_bf16 v[94:97], v[154:157], v[178:181], v[94:97]
	v_mfma_f32_16x16x32_bf16 v[70:73], v[146:149], v[186:189], v[70:73]
	v_mfma_f32_16x16x32_bf16 v[66:69], v[154:157], v[186:189], v[66:69]
	v_mfma_f32_16x16x32_bf16 v[22:25], v[150:153], v[166:169], v[22:25]
	v_mfma_f32_16x16x32_bf16 v[18:21], v[158:161], v[166:169], v[18:21]
	v_mfma_f32_16x16x32_bf16 v[10:13], v[150:153], v[174:177], v[10:13]
	v_mfma_f32_16x16x32_bf16 v[6:9], v[158:161], v[174:177], v[6:9]
	v_mfma_f32_16x16x32_bf16 v[82:85], v[150:153], v[182:185], v[82:85]
	v_mfma_f32_16x16x32_bf16 v[94:97], v[158:161], v[182:185], v[94:97]
	v_mfma_f32_16x16x32_bf16 v[70:73], v[150:153], v[190:193], v[70:73]
	v_mfma_f32_16x16x32_bf16 v[66:69], v[158:161], v[190:193], v[66:69]
	s_barrier
	s_add_i32 vcc_lo, vcc_lo, 2
	s_add_u32 s89, s89, 0x100
	s_addc_u32 s91, s91, 0
	s_cmp_gt_u32 vcc_lo, 29
	s_mov_b64 s[30:31], s[4:5]
	s_cbranch_scc0 .LBB0_691
	s_and_b64 vcc, exec, s[26:27]
	s_cbranch_vccz .LBB0_694
	s_barrier

; #define PG8_STAGE(bufoff, gbase, voff) do { _Pragma("unroll") for (int _i = 0; _i < 2; ++_i) \
;         __builtin_amdgcn_global_load_lds((const unsigned*)((const char*)(gbase) + (voff)[_i]), (PG8_LAS unsigned*)(lds + (bufoff) + ldsw + _i * 8192), 16, 0, 0); } while (0)
; #define PG8_LDA(dst, b, h) do { _Pragma("unroll") for (int m = 0; m < 4; ++m) _Pragma("unroll") for (int k = 0; k < 2; ++k) dst[m][k] = *(const PG8_LAS bf16x8*)(lds + PG8_SA(b, h) + aoff + m * 2048 + k * 1024); } while (0)
; #define PG8_LDB(dst, b, h) do { _Pragma("unroll") for (int n = 0; n < 2; ++n) _Pragma("unroll") for (int k = 0; k < 2; ++k) dst[n][k] = *(const PG8_LAS bf16x8*)(lds + PG8_SB(b, h) + boff + n * 2048 + k * 1024); } while (0)
; #define PG8_MMA(ai, bj, At, Bt) do { __builtin_amdgcn_s_setprio(1); _Pragma("unroll") for (int m = 0; m < 4; ++m) _Pragma("unroll") for (int n = 0; n < 2; ++n) _Pragma("unroll") for (int k = 0; k < 2; ++k) \
;         acc[ai][bj][m][n] = __builtin_amdgcn_mfma_f32_16x16x32_bf16(Bt[n][k], At[m][k], acc[ai][bj][m][n], 0, 0, 0); __builtin_amdgcn_s_setprio(0); } while (0)
; #define PG8_WAIT_V(n) asm volatile("s_waitcnt vmcnt(" #n ")" ::: "memory")
; #define PG8_BAR __builtin_amdgcn_s_barrier()
; template <class Epi, class Sched, bool ALIGN_EPI = false, bool SP2 = false>
; __device__ __forceinline__ void gemm_phase(PG8_LAS unsigned char* lds, const Gemm g, const Sched& S, const Epi& E, int wave_s) {
;     ...
;         const bool has_next = S.next(ui + 1, nxt);
;         const char* nA = has_next ? (const char*)g.A + (size_t)nxt.pm * tstepA + (size_t)(nxt.pn / g.npg) * (size_t)(K * 2) : cA; const char* nB = has_next ? (const char*)g.Bt + (size_t)nxt.pn * tstepB : cB;
;         for (int t = 0; t < nt; t += 2) {
;             const bool last = (t == nt - 2);
;             const char* a1 = cA + (size_t)(t + 1) * kstep;
;             const char* a2 = last ? nA : cA + (size_t)(t + 2) * kstep; const char* b2 = last ? nB : cB + (size_t)(t + 2) * kstep;
;             const char* a3 = a2 + kstep; const char* b3 = b2 + kstep;
;             if (last && has_next) S.a_ready(nxt);
;             if constexpr (SP2) {
;             PG8_LDB(B0, 0, 0); PG8_LDB(B1, 0, 1); PG8_SCHED; PG8_LDA(At, 0, 0); PG8_STAGE(PG8_SA(1, 1), a1 + hstepA, voffA);
;             PG8_WAIT_V(8); PG8_WAIT_L(0); PG8_BAR; PG8_MMA(0, 0, At, B0); PG8_MMA(0, 1, At, B1); PG8_BAR; PG8_SCHED;
.LBB0_785:
	s_add_u32 s2, s30, 0x100
	s_addc_u32 s3, s31, 0
	s_mov_b32 s81, -2
	s_add_u32 s4, s8, 0x100
	s_addc_u32 s5, s9, 0
	s_add_i32 s84, 0, 0x10000
	s_cmpk_eq_i32 s81, 0x54
	s_cselect_b32 s31, s95, s5
	s_cselect_b32 s30, s94, s4
	s_cselect_b32 s7, s97, s3
	s_cselect_b32 s6, s96, s2
	s_add_i32 s85, 0, 0x14000
	v_add_u32_e32 v110, s84, v211
	v_add_u32_e32 v150, s85, v211
	ds_read_b128 v[78:81], v110
	ds_read_b128 v[86:89], v110 offset:1024
	ds_read_b128 v[102:105], v110 offset:2048
	ds_read_b128 v[110:113], v110 offset:3072
	ds_read_b128 v[122:125], v150
	ds_read_b128 v[134:137], v150 offset:1024
	ds_read_b128 v[146:149], v150 offset:2048
	ds_read_b128 v[150:153], v150 offset:3072
	v_lshl_add_u64 v[206:207], s[8:9], 0, v[198:199]
	s_add_i32 m0, s35, 0xc000
	ds_read_b128 v[162:165], v212
	ds_read_b128 v[166:169], v212 offset:1024
	ds_read_b128 v[170:173], v212 offset:2048
	ds_read_b128 v[174:177], v212 offset:3072
	ds_read_b128 v[178:181], v212 offset:4096
	ds_read_b128 v[182:185], v212 offset:5120
	ds_read_b128 v[186:189], v212 offset:6144
	ds_read_b128 v[202:205], v212 offset:7168
	global_load_lds_dwordx4 v[206:207], off
	v_lshl_add_u64 v[206:207], s[8:9], 0, v[200:201]
	s_add_i32 m0, s35, 0xe000
	s_nop 0
	global_load_lds_dwordx4 v[206:207], off
	s_waitcnt vmcnt(8)
	s_waitcnt lgkmcnt(0)
	s_barrier
	v_mfma_f32_16x16x32_bf16 v[158:161], v[78:81], v[162:165], 0
	v_mfma_f32_16x16x32_bf16 v[154:157], v[102:105], v[162:165], 0
	v_mfma_f32_16x16x32_bf16 v[130:133], v[78:81], v[170:173], 0
	v_mfma_f32_16x16x32_bf16 v[126:129], v[102:105], v[170:173], 0
	v_mfma_f32_16x16x32_bf16 v[106:109], v[78:81], v[178:181], 0
	v_mfma_f32_16x16x32_bf16 v[98:101], v[102:105], v[178:181], 0
	v_mfma_f32_16x16x32_bf16 v[82:85], v[78:81], v[186:189], 0
	v_mfma_f32_16x16x32_bf16 v[74:77], v[102:105], v[186:189], 0
	v_mfma_f32_16x16x32_bf16 v[158:161], v[86:89], v[166:169], v[158:161]
	v_mfma_f32_16x16x32_bf16 v[154:157], v[110:113], v[166:169], v[154:157]
	v_mfma_f32_16x16x32_bf16 v[130:133], v[86:89], v[174:177], v[130:133]
	v_mfma_f32_16x16x32_bf16 v[126:129], v[110:113], v[174:177], v[126:129]
	v_mfma_f32_16x16x32_bf16 v[106:109], v[86:89], v[182:185], v[106:109]
	v_mfma_f32_16x16x32_bf16 v[98:101], v[110:113], v[182:185], v[98:101]
	v_mfma_f32_16x16x32_bf16 v[82:85], v[86:89], v[202:205], v[82:85]
	v_mfma_f32_16x16x32_bf16 v[74:77], v[110:113], v[202:205], v[74:77]
	v_mfma_f32_16x16x32_bf16 v[142:145], v[122:125], v[162:165], 0
	v_mfma_f32_16x16x32_bf16 v[138:141], v[146:149], v[162:165], 0
	v_mfma_f32_16x16x32_bf16 v[118:121], v[122:125], v[170:173], 0
	v_mfma_f32_16x16x32_bf16 v[114:117], v[146:149], v[170:173], 0
	v_mfma_f32_16x16x32_bf16 v[94:97], v[122:125], v[178:181], 0
	v_mfma_f32_16x16x32_bf16 v[90:93], v[146:149], v[178:181], 0
	v_mfma_f32_16x16x32_bf16 v[70:73], v[122:125], v[186:189], 0
	v_mfma_f32_16x16x32_bf16 v[66:69], v[146:149], v[186:189], 0
	v_mfma_f32_16x16x32_bf16 v[142:145], v[134:137], v[166:169], v[142:145]
	v_mfma_f32_16x16x32_bf16 v[138:141], v[150:153], v[166:169], v[138:141]
	v_mfma_f32_16x16x32_bf16 v[118:121], v[134:137], v[174:177], v[118:121]
	v_mfma_f32_16x16x32_bf16 v[114:117], v[150:153], v[174:177], v[114:117]
	v_mfma_f32_16x16x32_bf16 v[94:97], v[134:137], v[182:185], v[94:97]
	v_mfma_f32_16x16x32_bf16 v[90:93], v[150:153], v[182:185], v[90:93]
	v_mfma_f32_16x16x32_bf16 v[70:73], v[134:137], v[202:205], v[70:73]
	v_mfma_f32_16x16x32_bf16 v[66:69], v[150:153], v[202:205], v[66:69]
	s_barrier
	s_add_i32 s8, s84, s22
	v_lshl_add_u64 v[206:207], s[6:7], 0, v[194:195]
	s_mov_b32 m0, s8
	ds_read_b128 v[162:165], v212 offset:16384
	ds_read_b128 v[166:169], v212 offset:17408
	ds_read_b128 v[170:173], v212 offset:18432
	ds_read_b128 v[174:177], v212 offset:19456
	ds_read_b128 v[178:181], v212 offset:20480
	ds_read_b128 v[182:185], v212 offset:21504
	ds_read_b128 v[186:189], v212 offset:22528
	ds_read_b128 v[202:205], v212 offset:23552
	global_load_lds_dwordx4 v[206:207], off
	s_add_i32 m0, s8, 0x2000
	s_add_u32 s8, s6, 0x160000
	v_lshl_add_u64 v[208:209], s[6:7], 0, v[190:191]
	s_addc_u32 s9, s7, 0
	s_add_i32 s84, s85, s22
	global_load_lds_dwordx4 v[208:209], off
	v_lshl_add_u64 v[214:215], s[8:9], 0, v[194:195]
	s_mov_b32 m0, s84
	v_lshl_add_u64 v[216:217], s[30:31], 0, v[192:193]
	global_load_lds_dwordx4 v[214:215], off
	v_lshl_add_u64 v[214:215], s[8:9], 0, v[190:191]
	s_add_i32 m0, s84, 0x2000
	s_nop 0
	global_load_lds_dwordx4 v[214:215], off
	v_lshl_add_u64 v[214:215], s[30:31], 0, v[196:197]
	s_mov_b32 m0, s35
	s_nop 0
	global_load_lds_dwordx4 v[214:215], off
	s_mov_b32 m0, s36
	s_nop 0
	global_load_lds_dwordx4 v[216:217], off
	s_waitcnt vmcnt(8)
	s_waitcnt lgkmcnt(0)
	s_barrier
; #define PG8_STAGE(bufoff, gbase, voff) do { _Pragma("unroll") for (int _i = 0; _i < 2; ++_i) \
;         __builtin_amdgcn_global_load_lds((const unsigned*)((const char*)(gbase) + (voff)[_i]), (PG8_LAS unsigned*)(lds + (bufoff) + ldsw + _i * 8192), 16, 0, 0); } while (0)
; #define PG8_LDA(dst, b, h) do { _Pragma("unroll") for (int m = 0; m < 4; ++m) _Pragma("unroll") for (int k = 0; k < 2; ++k) dst[m][k] = *(const PG8_LAS bf16x8*)(lds + PG8_SA(b, h) + aoff + m * 2048 + k * 1024); } while (0)
; #define PG8_LDB(dst, b, h) do { _Pragma("unroll") for (int n = 0; n < 2; ++n) _Pragma("unroll") for (int k = 0; k < 2; ++k) dst[n][k] = *(const PG8_LAS bf16x8*)(lds + PG8_SB(b, h) + boff + n * 2048 + k * 1024); } while (0)
; #define PG8_MMA(ai, bj, At, Bt) do { __builtin_amdgcn_s_setprio(1); _Pragma("unroll") for (int m = 0; m < 4; ++m) _Pragma("unroll") for (int n = 0; n < 2; ++n) _Pragma("unroll") for (int k = 0; k < 2; ++k) \
;         acc[ai][bj][m][n] = __builtin_amdgcn_mfma_f32_16x16x32_bf16(Bt[n][k], At[m][k], acc[ai][bj][m][n], 0, 0, 0); __builtin_amdgcn_s_setprio(0); } while (0)
; #define PG8_WAIT_V(n) asm volatile("s_waitcnt vmcnt(" #n ")" ::: "memory")
; #define PG8_WAIT_L(n) asm volatile("s_waitcnt lgkmcnt(" #n ")" ::: "memory")
; #define PG8_BAR __builtin_amdgcn_s_barrier()
; #define PG8_SCHED __builtin_amdgcn_sched_barrier(0)
; template <class Epi, class Sched, bool ALIGN_EPI = false, bool SP2 = false>
; __device__ __forceinline__ void gemm_phase(PG8_LAS unsigned char* lds, const Gemm g, const Sched& S, const Epi& E, int wave_s) {
;     ...
;             PG8_LDA(At, 0, 1); PG8_STAGE(PG8_SB(0, 0), b2, voffB); PG8_STAGE(PG8_SB(0, 1), b2 + hstepB, voffB); PG8_STAGE(PG8_SA(0, 0), a2, voffA);
;             PG8_WAIT_V(8); PG8_WAIT_L(0); PG8_BAR; PG8_MMA(1, 0, At, B0); PG8_MMA(1, 1, At, B1); PG8_BAR; PG8_SCHED;
;             PG8_LDB(B0, 1, 0); PG8_LDB(B1, 1, 1); PG8_SCHED; PG8_LDA(At, 1, 0); PG8_STAGE(PG8_SA(0, 1), a2 + hstepA, voffA);
;             PG8_WAIT_V(8); PG8_WAIT_L(0); PG8_BAR; PG8_MMA(0, 0, At, B0); PG8_MMA(0, 1, At, B1); PG8_BAR; PG8_SCHED;
	v_mfma_f32_16x16x32_bf16 v[62:65], v[78:81], v[162:165], 0
	v_mfma_f32_16x16x32_bf16 v[58:61], v[102:105], v[162:165], 0
	v_mfma_f32_16x16x32_bf16 v[46:49], v[78:81], v[170:173], 0
	v_mfma_f32_16x16x32_bf16 v[42:45], v[102:105], v[170:173], 0
	v_mfma_f32_16x16x32_bf16 v[30:33], v[78:81], v[178:181], 0
	v_mfma_f32_16x16x32_bf16 v[26:29], v[102:105], v[178:181], 0
	v_mfma_f32_16x16x32_bf16 v[14:17], v[78:81], v[186:189], 0
	v_mfma_f32_16x16x32_bf16 v[10:13], v[102:105], v[186:189], 0
	v_mfma_f32_16x16x32_bf16 v[62:65], v[86:89], v[166:169], v[62:65]
	v_mfma_f32_16x16x32_bf16 v[58:61], v[110:113], v[166:169], v[58:61]
	v_mfma_f32_16x16x32_bf16 v[46:49], v[86:89], v[174:177], v[46:49]
	v_mfma_f32_16x16x32_bf16 v[42:45], v[110:113], v[174:177], v[42:45]
	v_mfma_f32_16x16x32_bf16 v[30:33], v[86:89], v[182:185], v[30:33]
	v_mfma_f32_16x16x32_bf16 v[26:29], v[110:113], v[182:185], v[26:29]
	v_mfma_f32_16x16x32_bf16 v[14:17], v[86:89], v[202:205], v[14:17]
	v_mfma_f32_16x16x32_bf16 v[10:13], v[110:113], v[202:205], v[10:13]
	v_mfma_f32_16x16x32_bf16 v[54:57], v[122:125], v[162:165], 0
	v_mfma_f32_16x16x32_bf16 v[50:53], v[146:149], v[162:165], 0
	v_mfma_f32_16x16x32_bf16 v[38:41], v[122:125], v[170:173], 0
	v_mfma_f32_16x16x32_bf16 v[34:37], v[146:149], v[170:173], 0
	v_mfma_f32_16x16x32_bf16 v[22:25], v[122:125], v[178:181], 0
	v_mfma_f32_16x16x32_bf16 v[18:21], v[146:149], v[178:181], 0
	v_mfma_f32_16x16x32_bf16 v[6:9], v[122:125], v[186:189], 0
	v_mfma_f32_16x16x32_bf16 v[2:5], v[146:149], v[186:189], 0
	v_mfma_f32_16x16x32_bf16 v[54:57], v[134:137], v[166:169], v[54:57]
	v_mfma_f32_16x16x32_bf16 v[50:53], v[150:153], v[166:169], v[50:53]
	v_mfma_f32_16x16x32_bf16 v[38:41], v[134:137], v[174:177], v[38:41]
	v_mfma_f32_16x16x32_bf16 v[34:37], v[150:153], v[174:177], v[34:37]
	v_mfma_f32_16x16x32_bf16 v[22:25], v[134:137], v[182:185], v[22:25]
	v_mfma_f32_16x16x32_bf16 v[18:21], v[150:153], v[182:185], v[18:21]
	v_mfma_f32_16x16x32_bf16 v[6:9], v[134:137], v[202:205], v[6:9]
	v_mfma_f32_16x16x32_bf16 v[2:5], v[150:153], v[202:205], v[2:5]
	s_barrier
	s_add_i32 s84, 0, 0x18000
	s_add_i32 s85, 0, 0x1c000
	v_add_u32_e32 v110, s84, v211
	v_add_u32_e32 v150, s85, v211
	ds_read_b128 v[78:81], v110
	ds_read_b128 v[86:89], v110 offset:1024
	ds_read_b128 v[102:105], v110 offset:2048
	ds_read_b128 v[110:113], v110 offset:3072
	ds_read_b128 v[122:125], v150
	ds_read_b128 v[134:137], v150 offset:1024
	ds_read_b128 v[146:149], v150 offset:2048
	ds_read_b128 v[150:153], v150 offset:3072
	s_add_u32 s8, s30, 0x160000
	s_addc_u32 s9, s31, 0
	s_mov_b32 m0, s37
	v_lshl_add_u64 v[218:219], s[8:9], 0, v[196:197]
	ds_read_b128 v[162:165], v212 offset:32768
	ds_read_b128 v[166:169], v212 offset:33792
	ds_read_b128 v[170:173], v212 offset:34816
	ds_read_b128 v[174:177], v212 offset:35840
	ds_read_b128 v[178:181], v212 offset:36864
	ds_read_b128 v[182:185], v212 offset:37888
	ds_read_b128 v[186:189], v212 offset:38912
	ds_read_b128 v[202:205], v212 offset:39936
	global_load_lds_dwordx4 v[218:219], off
	v_lshl_add_u64 v[218:219], s[8:9], 0, v[192:193]
	s_mov_b32 m0, s40
	s_nop 0
	global_load_lds_dwordx4 v[218:219], off
	s_waitcnt vmcnt(8)
	s_waitcnt lgkmcnt(0)
	s_barrier
	v_mfma_f32_16x16x32_bf16 v[158:161], v[78:81], v[162:165], v[158:161]
	v_mfma_f32_16x16x32_bf16 v[154:157], v[102:105], v[162:165], v[154:157]
	v_mfma_f32_16x16x32_bf16 v[130:133], v[78:81], v[170:173], v[130:133]
	v_mfma_f32_16x16x32_bf16 v[126:129], v[102:105], v[170:173], v[126:129]
	v_mfma_f32_16x16x32_bf16 v[106:109], v[78:81], v[178:181], v[106:109]
	v_mfma_f32_16x16x32_bf16 v[98:101], v[102:105], v[178:181], v[98:101]
	v_mfma_f32_16x16x32_bf16 v[82:85], v[78:81], v[186:189], v[82:85]
	v_mfma_f32_16x16x32_bf16 v[74:77], v[102:105], v[186:189], v[74:77]
	v_mfma_f32_16x16x32_bf16 v[158:161], v[86:89], v[166:169], v[158:161]
	v_mfma_f32_16x16x32_bf16 v[154:157], v[110:113], v[166:169], v[154:157]
	v_mfma_f32_16x16x32_bf16 v[130:133], v[86:89], v[174:177], v[130:133]
	v_mfma_f32_16x16x32_bf16 v[126:129], v[110:113], v[174:177], v[126:129]
	v_mfma_f32_16x16x32_bf16 v[106:109], v[86:89], v[182:185], v[106:109]
	v_mfma_f32_16x16x32_bf16 v[98:101], v[110:113], v[182:185], v[98:101]
	v_mfma_f32_16x16x32_bf16 v[82:85], v[86:89], v[202:205], v[82:85]
	v_mfma_f32_16x16x32_bf16 v[74:77], v[110:113], v[202:205], v[74:77]
	v_mfma_f32_16x16x32_bf16 v[142:145], v[122:125], v[162:165], v[142:145]
	v_mfma_f32_16x16x32_bf16 v[138:141], v[146:149], v[162:165], v[138:141]
	v_mfma_f32_16x16x32_bf16 v[118:121], v[122:125], v[170:173], v[118:121]
	v_mfma_f32_16x16x32_bf16 v[114:117], v[146:149], v[170:173], v[114:117]
	v_mfma_f32_16x16x32_bf16 v[94:97], v[122:125], v[178:181], v[94:97]
	v_mfma_f32_16x16x32_bf16 v[90:93], v[146:149], v[178:181], v[90:93]
	v_mfma_f32_16x16x32_bf16 v[70:73], v[122:125], v[186:189], v[70:73]
	v_mfma_f32_16x16x32_bf16 v[66:69], v[146:149], v[186:189], v[66:69]
	v_mfma_f32_16x16x32_bf16 v[142:145], v[134:137], v[166:169], v[142:145]
	v_mfma_f32_16x16x32_bf16 v[138:141], v[150:153], v[166:169], v[138:141]
	v_mfma_f32_16x16x32_bf16 v[118:121], v[134:137], v[174:177], v[118:121]
	v_mfma_f32_16x16x32_bf16 v[114:117], v[150:153], v[174:177], v[114:117]
	v_mfma_f32_16x16x32_bf16 v[94:97], v[134:137], v[182:185], v[94:97]
	v_mfma_f32_16x16x32_bf16 v[90:93], v[150:153], v[182:185], v[90:93]
	v_mfma_f32_16x16x32_bf16 v[70:73], v[134:137], v[202:205], v[70:73]
	v_mfma_f32_16x16x32_bf16 v[66:69], v[150:153], v[202:205], v[66:69]
	s_barrier
; #define PG8_STAGE(bufoff, gbase, voff) do { _Pragma("unroll") for (int _i = 0; _i < 2; ++_i) \
;         __builtin_amdgcn_global_load_lds((const unsigned*)((const char*)(gbase) + (voff)[_i]), (PG8_LAS unsigned*)(lds + (bufoff) + ldsw + _i * 8192), 16, 0, 0); } while (0)
; #define PG8_LDA(dst, b, h) do { _Pragma("unroll") for (int m = 0; m < 4; ++m) _Pragma("unroll") for (int k = 0; k < 2; ++k) dst[m][k] = *(const PG8_LAS bf16x8*)(lds + PG8_SA(b, h) + aoff + m * 2048 + k * 1024); } while (0)
; #define PG8_LDB(dst, b, h) do { _Pragma("unroll") for (int n = 0; n < 2; ++n) _Pragma("unroll") for (int k = 0; k < 2; ++k) dst[n][k] = *(const PG8_LAS bf16x8*)(lds + PG8_SB(b, h) + boff + n * 2048 + k * 1024); } while (0)
; #define PG8_WAIT_V(n) asm volatile("s_waitcnt vmcnt(" #n ")" ::: "memory")
; #define PG8_WAIT_L(n) asm volatile("s_waitcnt lgkmcnt(" #n ")" ::: "memory")
; #define PG8_BAR __builtin_amdgcn_s_barrier()
; #define PG8_SCHED __builtin_amdgcn_sched_barrier(0)
; template <class Epi, class Sched, bool ALIGN_EPI = false, bool SP2 = false>
; __device__ __forceinline__ void gemm_phase(PG8_LAS unsigned char* lds, const Gemm g, const Sched& S, const Epi& E, int wave_s) {
;     ...
;         for (int t = 0; t < nt; t += 2) {
;             const bool last = (t == nt - 2);
;             const char* a1 = cA + (size_t)(t + 1) * kstep;
;             const char* a2 = last ? nA : cA + (size_t)(t + 2) * kstep; const char* b2 = last ? nB : cB + (size_t)(t + 2) * kstep;
;             const char* a3 = a2 + kstep; const char* b3 = b2 + kstep;
;             if (last && has_next) S.a_ready(nxt);
;             if constexpr (SP2) {
;             PG8_LDB(B0, 0, 0); PG8_LDB(B1, 0, 1); PG8_SCHED; PG8_LDA(At, 0, 0); PG8_STAGE(PG8_SA(1, 1), a1 + hstepA, voffA);
;             PG8_WAIT_V(8); PG8_WAIT_L(0); PG8_BAR; PG8_MMA(0, 0, At, B0); PG8_MMA(0, 1, At, B1); PG8_BAR; PG8_SCHED;
;             PG8_LDA(At, 0, 1); PG8_STAGE(PG8_SB(0, 0), b2, voffB); PG8_STAGE(PG8_SB(0, 1), b2 + hstepB, voffB); PG8_STAGE(PG8_SA(0, 0), a2, voffA);
;     ...
;             PG8_LDA(At, 1, 1); PG8_STAGE(PG8_SB(1, 0), b3, voffB); PG8_STAGE(PG8_SB(1, 1), b3 + hstepB, voffB); PG8_STAGE(PG8_SA(1, 0), a3, voffA);
;             PG8_WAIT_V(8); PG8_WAIT_L(0); PG8_BAR; PG8_MMA(1, 0, At, B0); PG8_MMA(1, 1, At, B1); PG8_BAR; PG8_SCHED;
	s_add_i32 s8, s84, s22
	v_lshl_add_u64 v[206:207], v[206:207], 0, s[60:61]
	s_mov_b32 m0, s8
	ds_read_b128 v[162:165], v212 offset:49152
	ds_read_b128 v[166:169], v212 offset:50176
	ds_read_b128 v[170:173], v212 offset:51200
	ds_read_b128 v[174:177], v212 offset:52224
	ds_read_b128 v[178:181], v212 offset:53248
	ds_read_b128 v[182:185], v212 offset:54272
	ds_read_b128 v[186:189], v212 offset:55296
	ds_read_b128 v[202:205], v212 offset:56320
	global_load_lds_dwordx4 v[206:207], off
	s_add_i32 m0, s8, 0x2000
	s_add_u32 s6, s6, 0x160080
	v_lshl_add_u64 v[206:207], v[208:209], 0, s[60:61]
	s_addc_u32 s7, s7, 0
	s_add_i32 s8, s85, s22
	global_load_lds_dwordx4 v[206:207], off
	v_lshl_add_u64 v[206:207], s[6:7], 0, v[194:195]
	s_mov_b32 m0, s8
	s_nop 0
	global_load_lds_dwordx4 v[206:207], off
	v_lshl_add_u64 v[206:207], s[6:7], 0, v[190:191]
	s_add_i32 m0, s8, 0x2000
	s_nop 0
	global_load_lds_dwordx4 v[206:207], off
	v_lshl_add_u64 v[206:207], v[214:215], 0, s[60:61]
	s_mov_b32 m0, s44
	s_nop 0
	global_load_lds_dwordx4 v[206:207], off
	v_lshl_add_u64 v[206:207], v[216:217], 0, s[60:61]
	s_mov_b32 m0, s45
	s_nop 0
	global_load_lds_dwordx4 v[206:207], off
	s_waitcnt vmcnt(8)
	s_waitcnt lgkmcnt(0)
	s_barrier
	v_mfma_f32_16x16x32_bf16 v[62:65], v[78:81], v[162:165], v[62:65]
	v_mfma_f32_16x16x32_bf16 v[58:61], v[102:105], v[162:165], v[58:61]
	v_mfma_f32_16x16x32_bf16 v[46:49], v[78:81], v[170:173], v[46:49]
	v_mfma_f32_16x16x32_bf16 v[42:45], v[102:105], v[170:173], v[42:45]
	v_mfma_f32_16x16x32_bf16 v[30:33], v[78:81], v[178:181], v[30:33]
	v_mfma_f32_16x16x32_bf16 v[26:29], v[102:105], v[178:181], v[26:29]
	v_mfma_f32_16x16x32_bf16 v[14:17], v[78:81], v[186:189], v[14:17]
	v_mfma_f32_16x16x32_bf16 v[10:13], v[102:105], v[186:189], v[10:13]
	v_mfma_f32_16x16x32_bf16 v[62:65], v[86:89], v[166:169], v[62:65]
	v_mfma_f32_16x16x32_bf16 v[58:61], v[110:113], v[166:169], v[58:61]
	v_mfma_f32_16x16x32_bf16 v[46:49], v[86:89], v[174:177], v[46:49]
	v_mfma_f32_16x16x32_bf16 v[42:45], v[110:113], v[174:177], v[42:45]
	v_mfma_f32_16x16x32_bf16 v[30:33], v[86:89], v[182:185], v[30:33]
	v_mfma_f32_16x16x32_bf16 v[26:29], v[110:113], v[182:185], v[26:29]
	v_mfma_f32_16x16x32_bf16 v[14:17], v[86:89], v[202:205], v[14:17]
	v_mfma_f32_16x16x32_bf16 v[10:13], v[110:113], v[202:205], v[10:13]
	v_mfma_f32_16x16x32_bf16 v[54:57], v[122:125], v[162:165], v[54:57]
	v_mfma_f32_16x16x32_bf16 v[50:53], v[146:149], v[162:165], v[50:53]
	v_mfma_f32_16x16x32_bf16 v[38:41], v[122:125], v[170:173], v[38:41]
	v_mfma_f32_16x16x32_bf16 v[34:37], v[146:149], v[170:173], v[34:37]
	v_mfma_f32_16x16x32_bf16 v[22:25], v[122:125], v[178:181], v[22:25]
	v_mfma_f32_16x16x32_bf16 v[18:21], v[146:149], v[178:181], v[18:21]
	v_mfma_f32_16x16x32_bf16 v[6:9], v[122:125], v[186:189], v[6:9]
	v_mfma_f32_16x16x32_bf16 v[2:5], v[146:149], v[186:189], v[2:5]
	v_mfma_f32_16x16x32_bf16 v[54:57], v[134:137], v[166:169], v[54:57]
	v_mfma_f32_16x16x32_bf16 v[50:53], v[150:153], v[166:169], v[50:53]
	v_mfma_f32_16x16x32_bf16 v[38:41], v[134:137], v[174:177], v[38:41]
	v_mfma_f32_16x16x32_bf16 v[34:37], v[150:153], v[174:177], v[34:37]
	v_mfma_f32_16x16x32_bf16 v[22:25], v[134:137], v[182:185], v[22:25]
	v_mfma_f32_16x16x32_bf16 v[18:21], v[150:153], v[182:185], v[18:21]
	v_mfma_f32_16x16x32_bf16 v[6:9], v[134:137], v[202:205], v[6:9]
	v_mfma_f32_16x16x32_bf16 v[2:5], v[150:153], v[202:205], v[2:5]
	s_barrier
	s_add_i32 s81, s81, 2
	s_add_u32 s2, s2, 0x100
	s_addc_u32 s3, s3, 0
	s_cmpk_gt_u32 s81, 0x55
	s_mov_b64 s[8:9], s[4:5]
.LBB0_786:
	s_add_u32 s4, s8, 0x100
	s_addc_u32 s5, s9, 0
	s_add_i32 s84, 0, 0x10000
	s_cmpk_eq_i32 s81, 0x54
	s_cselect_b32 s31, s95, s5
	s_cselect_b32 s30, s94, s4
	s_cselect_b32 s7, s97, s3
	s_cselect_b32 s6, s96, s2
	s_add_i32 s85, 0, 0x14000
	v_add_u32_e32 v110, s84, v211
	v_add_u32_e32 v150, s85, v211
	ds_read_b128 v[78:81], v110
	ds_read_b128 v[86:89], v110 offset:1024
	ds_read_b128 v[102:105], v110 offset:2048
	ds_read_b128 v[110:113], v110 offset:3072
	ds_read_b128 v[122:125], v150
	ds_read_b128 v[134:137], v150 offset:1024
	ds_read_b128 v[146:149], v150 offset:2048
	ds_read_b128 v[150:153], v150 offset:3072
	v_lshl_add_u64 v[206:207], s[8:9], 0, v[198:199]
	s_add_i32 m0, s35, 0xc000
	ds_read_b128 v[162:165], v212
	ds_read_b128 v[166:169], v212 offset:1024
	ds_read_b128 v[170:173], v212 offset:2048
	ds_read_b128 v[174:177], v212 offset:3072
	ds_read_b128 v[178:181], v212 offset:4096
	ds_read_b128 v[182:185], v212 offset:5120
	ds_read_b128 v[186:189], v212 offset:6144
	ds_read_b128 v[202:205], v212 offset:7168
	global_load_lds_dwordx4 v[206:207], off
	v_lshl_add_u64 v[206:207], s[8:9], 0, v[200:201]
	s_add_i32 m0, s35, 0xe000
	s_nop 0
	global_load_lds_dwordx4 v[206:207], off
	s_waitcnt vmcnt(8)
	s_waitcnt lgkmcnt(0)
	s_barrier
; #define PG8_STAGE(bufoff, gbase, voff) do { _Pragma("unroll") for (int _i = 0; _i < 2; ++_i) \
;         __builtin_amdgcn_global_load_lds((const unsigned*)((const char*)(gbase) + (voff)[_i]), (PG8_LAS unsigned*)(lds + (bufoff) + ldsw + _i * 8192), 16, 0, 0); } while (0)
; #define PG8_LDA(dst, b, h) do { _Pragma("unroll") for (int m = 0; m < 4; ++m) _Pragma("unroll") for (int k = 0; k < 2; ++k) dst[m][k] = *(const PG8_LAS bf16x8*)(lds + PG8_SA(b, h) + aoff + m * 2048 + k * 1024); } while (0)
; #define PG8_LDB(dst, b, h) do { _Pragma("unroll") for (int n = 0; n < 2; ++n) _Pragma("unroll") for (int k = 0; k < 2; ++k) dst[n][k] = *(const PG8_LAS bf16x8*)(lds + PG8_SB(b, h) + boff + n * 2048 + k * 1024); } while (0)
; #define PG8_MMA(ai, bj, At, Bt) do { __builtin_amdgcn_s_setprio(1); _Pragma("unroll") for (int m = 0; m < 4; ++m) _Pragma("unroll") for (int n = 0; n < 2; ++n) _Pragma("unroll") for (int k = 0; k < 2; ++k) \
;         acc[ai][bj][m][n] = __builtin_amdgcn_mfma_f32_16x16x32_bf16(Bt[n][k], At[m][k], acc[ai][bj][m][n], 0, 0, 0); __builtin_amdgcn_s_setprio(0); } while (0)
; #define PG8_WAIT_V(n) asm volatile("s_waitcnt vmcnt(" #n ")" ::: "memory")
; #define PG8_WAIT_L(n) asm volatile("s_waitcnt lgkmcnt(" #n ")" ::: "memory")
; #define PG8_BAR __builtin_amdgcn_s_barrier()
; #define PG8_SCHED __builtin_amdgcn_sched_barrier(0)
; template <class Epi, class Sched, bool ALIGN_EPI = false, bool SP2 = false>
; __device__ __forceinline__ void gemm_phase(PG8_LAS unsigned char* lds, const Gemm g, const Sched& S, const Epi& E, int wave_s) {
;     ...
;             PG8_LDB(B0, 0, 0); PG8_LDB(B1, 0, 1); PG8_SCHED; PG8_LDA(At, 0, 0); PG8_STAGE(PG8_SA(1, 1), a1 + hstepA, voffA);
;             PG8_WAIT_V(8); PG8_WAIT_L(0); PG8_BAR; PG8_MMA(0, 0, At, B0); PG8_MMA(0, 1, At, B1); PG8_BAR; PG8_SCHED;
;             PG8_LDA(At, 0, 1); PG8_STAGE(PG8_SB(0, 0), b2, voffB); PG8_STAGE(PG8_SB(0, 1), b2 + hstepB, voffB); PG8_STAGE(PG8_SA(0, 0), a2, voffA);
;             PG8_WAIT_V(8); PG8_WAIT_L(0); PG8_BAR; PG8_MMA(1, 0, At, B0); PG8_MMA(1, 1, At, B1); PG8_BAR; PG8_SCHED;
	v_mfma_f32_16x16x32_bf16 v[158:161], v[78:81], v[162:165], v[158:161]
	v_mfma_f32_16x16x32_bf16 v[154:157], v[102:105], v[162:165], v[154:157]
	v_mfma_f32_16x16x32_bf16 v[130:133], v[78:81], v[170:173], v[130:133]
	v_mfma_f32_16x16x32_bf16 v[126:129], v[102:105], v[170:173], v[126:129]
	v_mfma_f32_16x16x32_bf16 v[106:109], v[78:81], v[178:181], v[106:109]
	v_mfma_f32_16x16x32_bf16 v[98:101], v[102:105], v[178:181], v[98:101]
	v_mfma_f32_16x16x32_bf16 v[82:85], v[78:81], v[186:189], v[82:85]
	v_mfma_f32_16x16x32_bf16 v[74:77], v[102:105], v[186:189], v[74:77]
	v_mfma_f32_16x16x32_bf16 v[158:161], v[86:89], v[166:169], v[158:161]
	v_mfma_f32_16x16x32_bf16 v[154:157], v[110:113], v[166:169], v[154:157]
	v_mfma_f32_16x16x32_bf16 v[130:133], v[86:89], v[174:177], v[130:133]
	v_mfma_f32_16x16x32_bf16 v[126:129], v[110:113], v[174:177], v[126:129]
	v_mfma_f32_16x16x32_bf16 v[106:109], v[86:89], v[182:185], v[106:109]
	v_mfma_f32_16x16x32_bf16 v[98:101], v[110:113], v[182:185], v[98:101]
	v_mfma_f32_16x16x32_bf16 v[82:85], v[86:89], v[202:205], v[82:85]
	v_mfma_f32_16x16x32_bf16 v[74:77], v[110:113], v[202:205], v[74:77]
	v_mfma_f32_16x16x32_bf16 v[142:145], v[122:125], v[162:165], v[142:145]
	v_mfma_f32_16x16x32_bf16 v[138:141], v[146:149], v[162:165], v[138:141]
	v_mfma_f32_16x16x32_bf16 v[118:121], v[122:125], v[170:173], v[118:121]
	v_mfma_f32_16x16x32_bf16 v[114:117], v[146:149], v[170:173], v[114:117]
	v_mfma_f32_16x16x32_bf16 v[94:97], v[122:125], v[178:181], v[94:97]
	v_mfma_f32_16x16x32_bf16 v[90:93], v[146:149], v[178:181], v[90:93]
	v_mfma_f32_16x16x32_bf16 v[70:73], v[122:125], v[186:189], v[70:73]
	v_mfma_f32_16x16x32_bf16 v[66:69], v[146:149], v[186:189], v[66:69]
	v_mfma_f32_16x16x32_bf16 v[142:145], v[134:137], v[166:169], v[142:145]
	v_mfma_f32_16x16x32_bf16 v[138:141], v[150:153], v[166:169], v[138:141]
	v_mfma_f32_16x16x32_bf16 v[118:121], v[134:137], v[174:177], v[118:121]
	v_mfma_f32_16x16x32_bf16 v[114:117], v[150:153], v[174:177], v[114:117]
	v_mfma_f32_16x16x32_bf16 v[94:97], v[134:137], v[182:185], v[94:97]
	v_mfma_f32_16x16x32_bf16 v[90:93], v[150:153], v[182:185], v[90:93]
	v_mfma_f32_16x16x32_bf16 v[70:73], v[134:137], v[202:205], v[70:73]
	v_mfma_f32_16x16x32_bf16 v[66:69], v[150:153], v[202:205], v[66:69]
	s_barrier
	s_add_i32 s8, s84, s22
	v_lshl_add_u64 v[206:207], s[6:7], 0, v[194:195]
	s_mov_b32 m0, s8
	ds_read_b128 v[162:165], v212 offset:16384
	ds_read_b128 v[166:169], v212 offset:17408
	ds_read_b128 v[170:173], v212 offset:18432
	ds_read_b128 v[174:177], v212 offset:19456
	ds_read_b128 v[178:181], v212 offset:20480
	ds_read_b128 v[182:185], v212 offset:21504
	ds_read_b128 v[186:189], v212 offset:22528
	ds_read_b128 v[202:205], v212 offset:23552
	global_load_lds_dwordx4 v[206:207], off
	s_add_i32 m0, s8, 0x2000
	s_add_u32 s8, s6, 0x160000
	v_lshl_add_u64 v[208:209], s[6:7], 0, v[190:191]
	s_addc_u32 s9, s7, 0
	s_add_i32 s84, s85, s22
	global_load_lds_dwordx4 v[208:209], off
	v_lshl_add_u64 v[214:215], s[8:9], 0, v[194:195]
	s_mov_b32 m0, s84
	v_lshl_add_u64 v[216:217], s[30:31], 0, v[192:193]
	global_load_lds_dwordx4 v[214:215], off
	v_lshl_add_u64 v[214:215], s[8:9], 0, v[190:191]
	s_add_i32 m0, s84, 0x2000
	s_nop 0
	global_load_lds_dwordx4 v[214:215], off
	v_lshl_add_u64 v[214:215], s[30:31], 0, v[196:197]
	s_mov_b32 m0, s35
	s_nop 0
	global_load_lds_dwordx4 v[214:215], off
	s_mov_b32 m0, s36
	s_nop 0
	global_load_lds_dwordx4 v[216:217], off
	s_waitcnt vmcnt(8)
	s_waitcnt lgkmcnt(0)
	s_barrier
	v_mfma_f32_16x16x32_bf16 v[62:65], v[78:81], v[162:165], v[62:65]
	v_mfma_f32_16x16x32_bf16 v[58:61], v[102:105], v[162:165], v[58:61]
	v_mfma_f32_16x16x32_bf16 v[46:49], v[78:81], v[170:173], v[46:49]
	v_mfma_f32_16x16x32_bf16 v[42:45], v[102:105], v[170:173], v[42:45]
	v_mfma_f32_16x16x32_bf16 v[30:33], v[78:81], v[178:181], v[30:33]
	v_mfma_f32_16x16x32_bf16 v[26:29], v[102:105], v[178:181], v[26:29]
	v_mfma_f32_16x16x32_bf16 v[14:17], v[78:81], v[186:189], v[14:17]
	v_mfma_f32_16x16x32_bf16 v[10:13], v[102:105], v[186:189], v[10:13]
	v_mfma_f32_16x16x32_bf16 v[62:65], v[86:89], v[166:169], v[62:65]
	v_mfma_f32_16x16x32_bf16 v[58:61], v[110:113], v[166:169], v[58:61]
	v_mfma_f32_16x16x32_bf16 v[46:49], v[86:89], v[174:177], v[46:49]
	v_mfma_f32_16x16x32_bf16 v[42:45], v[110:113], v[174:177], v[42:45]
	v_mfma_f32_16x16x32_bf16 v[30:33], v[86:89], v[182:185], v[30:33]
	v_mfma_f32_16x16x32_bf16 v[26:29], v[110:113], v[182:185], v[26:29]
	v_mfma_f32_16x16x32_bf16 v[14:17], v[86:89], v[202:205], v[14:17]
	v_mfma_f32_16x16x32_bf16 v[10:13], v[110:113], v[202:205], v[10:13]
	v_mfma_f32_16x16x32_bf16 v[54:57], v[122:125], v[162:165], v[54:57]
	v_mfma_f32_16x16x32_bf16 v[50:53], v[146:149], v[162:165], v[50:53]
	v_mfma_f32_16x16x32_bf16 v[38:41], v[122:125], v[170:173], v[38:41]
	v_mfma_f32_16x16x32_bf16 v[34:37], v[146:149], v[170:173], v[34:37]
	v_mfma_f32_16x16x32_bf16 v[22:25], v[122:125], v[178:181], v[22:25]
	v_mfma_f32_16x16x32_bf16 v[18:21], v[146:149], v[178:181], v[18:21]
	v_mfma_f32_16x16x32_bf16 v[6:9], v[122:125], v[186:189], v[6:9]
	v_mfma_f32_16x16x32_bf16 v[2:5], v[146:149], v[186:189], v[2:5]
	v_mfma_f32_16x16x32_bf16 v[54:57], v[134:137], v[166:169], v[54:57]
	v_mfma_f32_16x16x32_bf16 v[50:53], v[150:153], v[166:169], v[50:53]
	v_mfma_f32_16x16x32_bf16 v[38:41], v[134:137], v[174:177], v[38:41]
	v_mfma_f32_16x16x32_bf16 v[34:37], v[150:153], v[174:177], v[34:37]
	v_mfma_f32_16x16x32_bf16 v[22:25], v[134:137], v[182:185], v[22:25]
	v_mfma_f32_16x16x32_bf16 v[18:21], v[150:153], v[182:185], v[18:21]
	v_mfma_f32_16x16x32_bf16 v[6:9], v[134:137], v[202:205], v[6:9]
	v_mfma_f32_16x16x32_bf16 v[2:5], v[150:153], v[202:205], v[2:5]
	s_barrier
; #define PG8_STAGE(bufoff, gbase, voff) do { _Pragma("unroll") for (int _i = 0; _i < 2; ++_i) \
;         __builtin_amdgcn_global_load_lds((const unsigned*)((const char*)(gbase) + (voff)[_i]), (PG8_LAS unsigned*)(lds + (bufoff) + ldsw + _i * 8192), 16, 0, 0); } while (0)
; #define PG8_LDA(dst, b, h) do { _Pragma("unroll") for (int m = 0; m < 4; ++m) _Pragma("unroll") for (int k = 0; k < 2; ++k) dst[m][k] = *(const PG8_LAS bf16x8*)(lds + PG8_SA(b, h) + aoff + m * 2048 + k * 1024); } while (0)
; #define PG8_LDB(dst, b, h) do { _Pragma("unroll") for (int n = 0; n < 2; ++n) _Pragma("unroll") for (int k = 0; k < 2; ++k) dst[n][k] = *(const PG8_LAS bf16x8*)(lds + PG8_SB(b, h) + boff + n * 2048 + k * 1024); } while (0)
; #define PG8_MMA(ai, bj, At, Bt) do { __builtin_amdgcn_s_setprio(1); _Pragma("unroll") for (int m = 0; m < 4; ++m) _Pragma("unroll") for (int n = 0; n < 2; ++n) _Pragma("unroll") for (int k = 0; k < 2; ++k) \
;         acc[ai][bj][m][n] = __builtin_amdgcn_mfma_f32_16x16x32_bf16(Bt[n][k], At[m][k], acc[ai][bj][m][n], 0, 0, 0); __builtin_amdgcn_s_setprio(0); } while (0)
; #define PG8_WAIT_V(n) asm volatile("s_waitcnt vmcnt(" #n ")" ::: "memory")
; #define PG8_WAIT_L(n) asm volatile("s_waitcnt lgkmcnt(" #n ")" ::: "memory")
; #define PG8_BAR __builtin_amdgcn_s_barrier()
; #define PG8_SCHED __builtin_amdgcn_sched_barrier(0)
; template <class Epi, class Sched, bool ALIGN_EPI = false, bool SP2 = false>
; __device__ __forceinline__ void gemm_phase(PG8_LAS unsigned char* lds, const Gemm g, const Sched& S, const Epi& E, int wave_s) {
;     ...
;         for (int t = 0; t < nt; t += 2) {
;             const bool last = (t == nt - 2);
;             const char* a1 = cA + (size_t)(t + 1) * kstep;
;             const char* a2 = last ? nA : cA + (size_t)(t + 2) * kstep; const char* b2 = last ? nB : cB + (size_t)(t + 2) * kstep;
;     ...
;             PG8_LDB(B0, 1, 0); PG8_LDB(B1, 1, 1); PG8_SCHED; PG8_LDA(At, 1, 0); PG8_STAGE(PG8_SA(0, 1), a2 + hstepA, voffA);
;             PG8_WAIT_V(8); PG8_WAIT_L(0); PG8_BAR; PG8_MMA(0, 0, At, B0); PG8_MMA(0, 1, At, B1); PG8_BAR; PG8_SCHED;
;             PG8_LDA(At, 1, 1); PG8_STAGE(PG8_SB(1, 0), b3, voffB); PG8_STAGE(PG8_SB(1, 1), b3 + hstepB, voffB); PG8_STAGE(PG8_SA(1, 0), a3, voffA);
;             PG8_WAIT_V(8); PG8_WAIT_L(0); PG8_BAR; PG8_MMA(1, 0, At, B0); PG8_MMA(1, 1, At, B1); PG8_BAR; PG8_SCHED;
	s_add_i32 s84, 0, 0x18000
	s_add_i32 s85, 0, 0x1c000
	v_add_u32_e32 v110, s84, v211
	v_add_u32_e32 v150, s85, v211
	ds_read_b128 v[78:81], v110
	ds_read_b128 v[86:89], v110 offset:1024
	ds_read_b128 v[102:105], v110 offset:2048
	ds_read_b128 v[110:113], v110 offset:3072
	ds_read_b128 v[122:125], v150
	ds_read_b128 v[134:137], v150 offset:1024
	ds_read_b128 v[146:149], v150 offset:2048
	ds_read_b128 v[150:153], v150 offset:3072
	s_add_u32 s8, s30, 0x160000
	s_addc_u32 s9, s31, 0
	s_mov_b32 m0, s37
	v_lshl_add_u64 v[218:219], s[8:9], 0, v[196:197]
	ds_read_b128 v[162:165], v212 offset:32768
	ds_read_b128 v[166:169], v212 offset:33792
	ds_read_b128 v[170:173], v212 offset:34816
	ds_read_b128 v[174:177], v212 offset:35840
	ds_read_b128 v[178:181], v212 offset:36864
	ds_read_b128 v[182:185], v212 offset:37888
	ds_read_b128 v[186:189], v212 offset:38912
	ds_read_b128 v[202:205], v212 offset:39936
	global_load_lds_dwordx4 v[218:219], off
	v_lshl_add_u64 v[218:219], s[8:9], 0, v[192:193]
	s_mov_b32 m0, s40
	s_nop 0
	global_load_lds_dwordx4 v[218:219], off
	s_waitcnt vmcnt(8)
	s_waitcnt lgkmcnt(0)
	s_barrier
	v_mfma_f32_16x16x32_bf16 v[158:161], v[78:81], v[162:165], v[158:161]
	v_mfma_f32_16x16x32_bf16 v[154:157], v[102:105], v[162:165], v[154:157]
	v_mfma_f32_16x16x32_bf16 v[130:133], v[78:81], v[170:173], v[130:133]
	v_mfma_f32_16x16x32_bf16 v[126:129], v[102:105], v[170:173], v[126:129]
	v_mfma_f32_16x16x32_bf16 v[106:109], v[78:81], v[178:181], v[106:109]
	v_mfma_f32_16x16x32_bf16 v[98:101], v[102:105], v[178:181], v[98:101]
	v_mfma_f32_16x16x32_bf16 v[82:85], v[78:81], v[186:189], v[82:85]
	v_mfma_f32_16x16x32_bf16 v[74:77], v[102:105], v[186:189], v[74:77]
	v_mfma_f32_16x16x32_bf16 v[158:161], v[86:89], v[166:169], v[158:161]
	v_mfma_f32_16x16x32_bf16 v[154:157], v[110:113], v[166:169], v[154:157]
	v_mfma_f32_16x16x32_bf16 v[130:133], v[86:89], v[174:177], v[130:133]
	v_mfma_f32_16x16x32_bf16 v[126:129], v[110:113], v[174:177], v[126:129]
	v_mfma_f32_16x16x32_bf16 v[106:109], v[86:89], v[182:185], v[106:109]
	v_mfma_f32_16x16x32_bf16 v[98:101], v[110:113], v[182:185], v[98:101]
	v_mfma_f32_16x16x32_bf16 v[82:85], v[86:89], v[202:205], v[82:85]
	v_mfma_f32_16x16x32_bf16 v[74:77], v[110:113], v[202:205], v[74:77]
	v_mfma_f32_16x16x32_bf16 v[142:145], v[122:125], v[162:165], v[142:145]
	v_mfma_f32_16x16x32_bf16 v[138:141], v[146:149], v[162:165], v[138:141]
	v_mfma_f32_16x16x32_bf16 v[118:121], v[122:125], v[170:173], v[118:121]
	v_mfma_f32_16x16x32_bf16 v[114:117], v[146:149], v[170:173], v[114:117]
	v_mfma_f32_16x16x32_bf16 v[94:97], v[122:125], v[178:181], v[94:97]
	v_mfma_f32_16x16x32_bf16 v[90:93], v[146:149], v[178:181], v[90:93]
	v_mfma_f32_16x16x32_bf16 v[70:73], v[122:125], v[186:189], v[70:73]
	v_mfma_f32_16x16x32_bf16 v[66:69], v[146:149], v[186:189], v[66:69]
	v_mfma_f32_16x16x32_bf16 v[142:145], v[134:137], v[166:169], v[142:145]
	v_mfma_f32_16x16x32_bf16 v[138:141], v[150:153], v[166:169], v[138:141]
	v_mfma_f32_16x16x32_bf16 v[118:121], v[134:137], v[174:177], v[118:121]
	v_mfma_f32_16x16x32_bf16 v[114:117], v[150:153], v[174:177], v[114:117]
	v_mfma_f32_16x16x32_bf16 v[94:97], v[134:137], v[182:185], v[94:97]
	v_mfma_f32_16x16x32_bf16 v[90:93], v[150:153], v[182:185], v[90:93]
	v_mfma_f32_16x16x32_bf16 v[70:73], v[134:137], v[202:205], v[70:73]
	v_mfma_f32_16x16x32_bf16 v[66:69], v[150:153], v[202:205], v[66:69]
	s_barrier
	s_add_i32 s8, s84, s22
	v_lshl_add_u64 v[206:207], v[206:207], 0, s[60:61]
	s_mov_b32 m0, s8
	ds_read_b128 v[162:165], v212 offset:49152
	ds_read_b128 v[166:169], v212 offset:50176
	ds_read_b128 v[170:173], v212 offset:51200
	ds_read_b128 v[174:177], v212 offset:52224
	ds_read_b128 v[178:181], v212 offset:53248
	ds_read_b128 v[182:185], v212 offset:54272
	ds_read_b128 v[186:189], v212 offset:55296
	ds_read_b128 v[202:205], v212 offset:56320
	global_load_lds_dwordx4 v[206:207], off
	s_add_i32 m0, s8, 0x2000
	s_add_u32 s6, s6, 0x160080
	v_lshl_add_u64 v[206:207], v[208:209], 0, s[60:61]
	s_addc_u32 s7, s7, 0
	s_add_i32 s8, s85, s22
	global_load_lds_dwordx4 v[206:207], off
	v_lshl_add_u64 v[206:207], s[6:7], 0, v[194:195]
	s_mov_b32 m0, s8
	s_nop 0
	global_load_lds_dwordx4 v[206:207], off
	v_lshl_add_u64 v[206:207], s[6:7], 0, v[190:191]
	s_add_i32 m0, s8, 0x2000
	s_nop 0
	global_load_lds_dwordx4 v[206:207], off
	v_lshl_add_u64 v[206:207], v[214:215], 0, s[60:61]
	s_mov_b32 m0, s44
	s_nop 0
	global_load_lds_dwordx4 v[206:207], off
	v_lshl_add_u64 v[206:207], v[216:217], 0, s[60:61]
	s_mov_b32 m0, s45
	s_nop 0
	global_load_lds_dwordx4 v[206:207], off
	s_waitcnt vmcnt(8)
	s_waitcnt lgkmcnt(0)
	s_barrier
	v_mfma_f32_16x16x32_bf16 v[62:65], v[78:81], v[162:165], v[62:65]
	v_mfma_f32_16x16x32_bf16 v[58:61], v[102:105], v[162:165], v[58:61]
	v_mfma_f32_16x16x32_bf16 v[46:49], v[78:81], v[170:173], v[46:49]
	v_mfma_f32_16x16x32_bf16 v[42:45], v[102:105], v[170:173], v[42:45]
	v_mfma_f32_16x16x32_bf16 v[30:33], v[78:81], v[178:181], v[30:33]
	v_mfma_f32_16x16x32_bf16 v[26:29], v[102:105], v[178:181], v[26:29]
	v_mfma_f32_16x16x32_bf16 v[14:17], v[78:81], v[186:189], v[14:17]
	v_mfma_f32_16x16x32_bf16 v[10:13], v[102:105], v[186:189], v[10:13]
	v_mfma_f32_16x16x32_bf16 v[62:65], v[86:89], v[166:169], v[62:65]
	v_mfma_f32_16x16x32_bf16 v[58:61], v[110:113], v[166:169], v[58:61]
	v_mfma_f32_16x16x32_bf16 v[46:49], v[86:89], v[174:177], v[46:49]
	v_mfma_f32_16x16x32_bf16 v[42:45], v[110:113], v[174:177], v[42:45]
	v_mfma_f32_16x16x32_bf16 v[30:33], v[86:89], v[182:185], v[30:33]
	v_mfma_f32_16x16x32_bf16 v[26:29], v[110:113], v[182:185], v[26:29]
	v_mfma_f32_16x16x32_bf16 v[14:17], v[86:89], v[202:205], v[14:17]
	v_mfma_f32_16x16x32_bf16 v[10:13], v[110:113], v[202:205], v[10:13]
	v_mfma_f32_16x16x32_bf16 v[54:57], v[122:125], v[162:165], v[54:57]
	v_mfma_f32_16x16x32_bf16 v[50:53], v[146:149], v[162:165], v[50:53]
	v_mfma_f32_16x16x32_bf16 v[38:41], v[122:125], v[170:173], v[38:41]
	v_mfma_f32_16x16x32_bf16 v[34:37], v[146:149], v[170:173], v[34:37]
	v_mfma_f32_16x16x32_bf16 v[22:25], v[122:125], v[178:181], v[22:25]
	v_mfma_f32_16x16x32_bf16 v[18:21], v[146:149], v[178:181], v[18:21]
	v_mfma_f32_16x16x32_bf16 v[6:9], v[122:125], v[186:189], v[6:9]
	v_mfma_f32_16x16x32_bf16 v[2:5], v[146:149], v[186:189], v[2:5]
	v_mfma_f32_16x16x32_bf16 v[54:57], v[134:137], v[166:169], v[54:57]
	v_mfma_f32_16x16x32_bf16 v[50:53], v[150:153], v[166:169], v[50:53]
	v_mfma_f32_16x16x32_bf16 v[38:41], v[134:137], v[174:177], v[38:41]
	v_mfma_f32_16x16x32_bf16 v[34:37], v[150:153], v[174:177], v[34:37]
	v_mfma_f32_16x16x32_bf16 v[22:25], v[134:137], v[182:185], v[22:25]
	v_mfma_f32_16x16x32_bf16 v[18:21], v[150:153], v[182:185], v[18:21]
	v_mfma_f32_16x16x32_bf16 v[6:9], v[134:137], v[202:205], v[6:9]
	v_mfma_f32_16x16x32_bf16 v[2:5], v[150:153], v[202:205], v[2:5]
	s_barrier
	s_add_i32 s81, s81, 2
	s_add_u32 s2, s2, 0x100
	s_addc_u32 s3, s3, 0
	s_cmpk_gt_u32 s81, 0x55
	s_mov_b64 s[8:9], s[4:5]
	s_cbranch_scc0 .LBB0_786
	s_and_b64 vcc, exec, s[88:89]
	s_cbranch_vccz .LBB0_789
	s_barrier
